# w_in GEMM: tile search hoisted before the K-loop and next tile's first two k-steps prefetched in the K-loop tail (32x32x16 kept)
# baseline (speedup 1.0000x reference)
; #define GEMM_ISSUE(kt_, st_) do { char* sb_ = lw + (st_) * STAGE_B; const char* ak_ = Ab + (size_t)(kt_) * 128; const char* bk_ = Bb + (size_t)(kt_) * 128; \
;     _Pragma("unroll") for (int i_ = 0; i_ < 4; ++i_) glds16(ak_ + avo[i_], sb_ + i_ * 8192); \
;     _Pragma("unroll") for (int i_ = 0; i_ < 2; ++i_) glds16(bk_ + bvo[i_], sb_ + 32768 + i_ * 8192); } while (0)
;     ...
;   if (PART != 2) {
;     GEMM_ISSUE(0, 0);
;     if (nk > 1) GEMM_ISSUE(1, 1);
;   }
; template <class Epi>
; DI void gemm_phase(const bf16_t* A, int lda, const bf16_t* Bt, int ldb, int K, int MT, int NTl, int SN, const Epi& epi, char* lds, bool rev = false) {
;     ...
;   for (; L < lmax; L += gridDim.x) if (tile_map(L, MT, NTl, SN, mt, nt)) { have = true; if (rev) mt = MT - 1 - mt; break; }
;   f32x16 dummy[2][2];
;   if (have) gemm_core<1>(A + (size_t)mt * 256 * lda, lda, Bt + (size_t)nt * 128 * ldb, ldb, K, dummy, lds);
.LBB0_215:
	s_andn2_b64 vcc, exec, s[10:11]
	s_cbranch_vccnz .LBB0_670
	v_mov_b32_e32 v0, v129
	s_add_u32 s70, s4, 0x2100000
	s_addc_u32 s71, s22, 0
	v_lshlrev_b32_e32 v1, 4, v0
	s_ashr_i32 s9, s8, 31
	v_xor_b32_e32 v2, v1, v0
	v_lshlrev_b32_e32 v0, 8, v0
	s_lshl_b64 s[10:11], s[8:9], 19
	v_and_b32_e32 v0, 0xfffff800, v0
	s_movk_i32 s9, 0x70
	v_add_u32_e32 v14, 0, v1
	s_add_u32 s10, s88, s10
	v_and_or_b32 v130, v2, s9, v0
	v_readfirstlane_b32 s9, v14
	v_add_u32_e32 v3, 0x2000, v14
	s_addc_u32 s11, s89, s11
	v_add_u32_e32 v2, 0x40000, v130
	s_mov_b32 m0, s9
	v_readfirstlane_b32 s9, v3
	v_mov_b32_e32 v3, v131
	v_lshl_add_u64 v[10:11], s[10:11], 0, v[2:3]
	v_add_u32_e32 v3, 0x4000, v14
	s_ashr_i32 s15, s14, 31
	v_add_u32_e32 v0, 0x20000, v130
	global_load_lds_dwordx4 v130, s[10:11]
	s_mov_b32 m0, s9
	v_readfirstlane_b32 s9, v3
	s_lshl_b64 s[26:27], s[14:15], 18
	v_add_u32_e32 v4, 0x60000, v130
	global_load_lds_dwordx4 v0, s[10:11]
	s_mov_b32 m0, s9
	v_mov_b32_e32 v5, v131
	s_add_u32 s26, s70, s26
	global_load_lds_dwordx4 v2, s[10:11]
	v_lshl_add_u64 v[2:3], s[10:11], 0, v[4:5]
	v_add_u32_e32 v5, 0x6000, v14
	s_addc_u32 s27, s71, s27
	v_mov_b32_e32 v1, v131
	v_readfirstlane_b32 s9, v5
	v_add_u32_e32 v12, 0x8000, v14
	v_lshl_add_u64 v[8:9], s[10:11], 0, v[0:1]
	s_mov_b32 m0, s9
	v_readfirstlane_b32 s9, v12
	v_lshl_add_u64 v[12:13], s[26:27], 0, v[0:1]
	v_add_u32_e32 v1, 0xa000, v14
	global_load_lds_dwordx4 v4, s[10:11]
	s_mov_b32 m0, s9
	v_readfirstlane_b32 s9, v1
	v_lshl_add_u64 v[6:7], s[10:11], 0, v[130:131]
	global_load_lds_dwordx4 v130, s[26:27]
	s_mov_b32 m0, s9
	v_add_u32_e32 v15, 0xc000, v14
	global_load_lds_dwordx4 v0, s[26:27]
	v_lshl_add_u64 v[0:1], v[6:7], 0, s[92:93]
	v_readfirstlane_b32 s9, v15
	v_add_u32_e32 v6, 0xe000, v14
	s_mov_b32 m0, s9
	v_readfirstlane_b32 s9, v6
	v_add_u32_e32 v6, 0x10000, v14
	global_load_lds_dwordx4 v[0:1], off
	v_lshl_add_u64 v[0:1], v[8:9], 0, s[92:93]
	s_mov_b32 m0, s9
	v_readfirstlane_b32 s9, v6
	global_load_lds_dwordx4 v[0:1], off
	v_lshl_add_u64 v[0:1], v[10:11], 0, s[92:93]
	s_mov_b32 m0, s9
	v_lshl_add_u64 v[4:5], s[26:27], 0, v[130:131]
	global_load_lds_dwordx4 v[0:1], off
	v_lshl_add_u64 v[0:1], v[2:3], 0, s[92:93]
	v_add_u32_e32 v2, 0x12000, v14
	s_mov_b32 s68, s14
	v_readfirstlane_b32 s9, v2
	v_add_u32_e32 v2, 0x14000, v14
	s_mov_b32 m0, s9
	v_readfirstlane_b32 s9, v2
	v_add_u32_e32 v2, 0x16000, v14
	global_load_lds_dwordx4 v[0:1], off
	v_lshl_add_u64 v[0:1], v[4:5], 0, s[92:93]
	s_mov_b32 m0, s9
	v_readfirstlane_b32 s9, v2
	global_load_lds_dwordx4 v[0:1], off
	v_lshl_add_u64 v[0:1], v[12:13], 0, s[92:93]
	s_mov_b32 m0, s9
	s_mov_b32 s10, s8
	global_load_lds_dwordx4 v[0:1], off
	s_waitcnt vmcnt(0)
	s_mov_b32 s100, 0
	s_mov_b32 s101, 1
	s_branch .LBB0_220

; #define TIDX get_tid_()
;   const int tid = TIDX, lane = tid & 63, wid = tid >> 6, wr = wid >> 1, wc = wid & 1, r = lane & 31, h = lane >> 5;
;   const int ch = (tid & 7) ^ ((tid >> 4) & 7);
;   unsigned avo[4], bvo[2];
; #pragma unroll
;   for (int i = 0; i < 4; ++i) avo[i] = (unsigned)(((tid >> 3) + 64 * i) * lda * 2 + ch * 16);
; #pragma unroll
;   for (int i = 0; i < 2; ++i) bvo[i] = (unsigned)(((tid >> 3) + 64 * i) * ldb * 2 + ch * 16);
;   const char* Ab = (const char*)A; const char* Bb = (const char*)Bt;
;   char* lw = lds + tid * 16;
;   const int nk = K >> 6;
;   const unsigned swz = (unsigned)((r >> 1) & 7);
;   const unsigned arow_u = (unsigned)((wr * 64 + r) * 128), brow_u = (unsigned)((wc * 64 + r) * 128);
;   const unsigned co0 = ((0u + h) ^ swz) << 4, co1 = ((2u + h) ^ swz) << 4, co2 = ((4u + h) ^ swz) << 4, co3 = ((6u + h) ^ swz) << 4;
; DI void zero_acc(f32x16 (&acc)[2][2]) {
; #pragma unroll
;   for (int a = 0; a < 2; ++a)
; #pragma unroll
;     for (int b = 0; b < 2; ++b)
; #pragma unroll
;       for (int i = 0; i < 16; ++i) acc[a][b][i] = 0.f;
; }
.LBB0_220:
	v_mov_b32_e32 v1, v129
	s_ashr_i32 s9, s8, 31
	v_lshlrev_b32_e32 v5, 4, v1
	v_lshrrev_b32_e32 v3, 5, v1
	v_xor_b32_e32 v0, v5, v1
	v_lshlrev_b32_e32 v2, 8, v1
	v_and_b32_e32 v6, 31, v1
	v_bfe_u32 v7, v1, 5, 1
	v_add_u32_e32 v116, 0, v5
	v_lshrrev_b32_e32 v5, 1, v1
	v_bfe_u32 v8, v1, 1, 3
	v_lshlrev_b32_e32 v1, 7, v1
	v_and_b32_e32 v118, 0x2f80, v1
	v_bitop3_b32 v1, v3, v8, 1 bitop3:0x6c
	s_lshl_b64 s[26:27], s[8:9], 19
	v_lshlrev_b32_e32 v119, 4, v1
	v_bitop3_b32 v1, v7, v8, 2 bitop3:0x36
	s_add_u32 s26, s88, s26
	v_and_b32_e32 v2, 0xfffff800, v2
	s_movk_i32 s9, 0x70
	v_lshlrev_b32_e32 v120, 4, v1
	v_bitop3_b32 v1, v7, v8, 4 bitop3:0x36
	s_addc_u32 s27, s89, s27
	v_and_or_b32 v130, v0, s9, v2
	s_mov_b32 s9, 0x1ffffc0
	v_lshlrev_b32_e32 v121, 4, v1
	v_bitop3_b32 v1, v7, v8, 6 bitop3:0x36
	v_add_u32_e32 v8, 0x18000, v116
	v_add_u32_e32 v0, 0x20000, v130
	v_and_or_b32 v5, v5, s9, v6
	v_lshlrev_b32_e32 v122, 4, v1
	v_mov_b32_e32 v1, v131
	v_lshl_add_u64 v[64:65], s[26:27], 0, v[130:131]
	v_readfirstlane_b32 s9, v8
	v_add_u32_e32 v8, 0x1a000, v116
	v_lshl_add_u64 v[6:7], v[64:65], 0, s[78:79]
	v_lshl_add_u64 v[66:67], s[26:27], 0, v[0:1]
	v_readfirstlane_b32 s11, v8
	s_ashr_i32 s15, s14, 31
	v_lshl_add_u64 v[6:7], v[66:67], 0, s[78:79]
	s_lshl_b64 s[30:31], s[14:15], 18
	v_add_u32_e32 v2, 0x40000, v130
	v_add_u32_e32 v4, 0x60000, v130
	v_lshlrev_b32_e32 v117, 7, v5
	v_mov_b32_e32 v3, v131
	v_mov_b32_e32 v5, v131
	v_add_u32_e32 v6, 0x1c000, v116
	s_add_u32 s30, s70, s30
	v_lshl_add_u64 v[68:69], s[26:27], 0, v[2:3]
	v_readfirstlane_b32 s15, v6
	v_lshl_add_u64 v[70:71], s[26:27], 0, v[4:5]
	v_add_u32_e32 v4, 0x1e000, v116
	s_addc_u32 s31, s71, s31
	v_lshl_add_u64 v[2:3], v[68:69], 0, s[78:79]
	v_readfirstlane_b32 s26, v4
	v_add_u32_e32 v4, 0x20000, v116
	v_lshl_add_u64 v[2:3], v[70:71], 0, s[78:79]
	v_lshl_add_u64 v[72:73], s[30:31], 0, v[130:131]
	v_readfirstlane_b32 s27, v4
	v_lshl_add_u64 v[2:3], v[72:73], 0, s[78:79]
	v_lshl_add_u64 v[74:75], s[30:31], 0, v[0:1]
	v_add_u32_e32 v2, 0x22000, v116
	s_cmp_lg_u32 0, -1
	v_readfirstlane_b32 s30, v2
	v_lshl_add_u64 v[0:1], v[74:75], 0, s[78:79]
	s_cselect_b32 s31, 0, 0
	v_add_u32_e32 v0, s31, v117
	s_add_i32 s31, s31, 0x8000
	s_mov_b32 s53, s52
	v_add_u32_e32 v1, s31, v118
	s_mov_b32 s54, s52
	s_mov_b32 s55, s52
	s_mov_b32 s56, s52
	s_mov_b32 s57, s52
	s_mov_b32 s58, s52
	s_mov_b32 s59, s52
	s_mov_b32 s60, s52
	s_mov_b32 s61, s52
	s_mov_b32 s62, s52
	s_mov_b32 s63, s52
	s_mov_b32 s64, s52
	s_mov_b32 s65, s52
	s_mov_b32 s66, s52
	s_mov_b32 s67, s52
	v_mov_b64_e32 v[48:49], s[52:53]
	v_add_u32_e32 v76, v0, v119
	v_add_u32_e32 v77, v0, v120
	v_add_u32_e32 v78, v0, v121
	v_add_u32_e32 v79, v0, v122
	v_add_u32_e32 v80, v119, v1
	v_add_u32_e32 v81, v120, v1
	v_add_u32_e32 v82, v121, v1
	v_add_u32_e32 v83, v122, v1
	v_mov_b64_e32 v[50:51], s[54:55]
	v_mov_b64_e32 v[52:53], s[56:57]
	v_mov_b64_e32 v[54:55], s[58:59]
	v_mov_b64_e32 v[56:57], s[60:61]
	v_mov_b64_e32 v[58:59], s[62:63]
	v_mov_b64_e32 v[60:61], s[64:65]
	v_mov_b64_e32 v[62:63], s[66:67]
	v_mov_b64_e32 v[32:33], v[48:49]
	v_mov_b64_e32 v[16:17], v[48:49]
	v_mov_b64_e32 v[0:1], v[48:49]
	v_mov_b64_e32 v[34:35], v[50:51]
	v_mov_b64_e32 v[36:37], v[52:53]
	v_mov_b64_e32 v[38:39], v[54:55]
	v_mov_b64_e32 v[40:41], v[56:57]
	v_mov_b64_e32 v[42:43], v[58:59]
	v_mov_b64_e32 v[44:45], v[60:61]
	v_mov_b64_e32 v[46:47], v[62:63]
	v_mov_b64_e32 v[18:19], v[50:51]
	v_mov_b64_e32 v[20:21], v[52:53]
	v_mov_b64_e32 v[22:23], v[54:55]
	v_mov_b64_e32 v[24:25], v[56:57]
	v_mov_b64_e32 v[26:27], v[58:59]
	v_mov_b64_e32 v[28:29], v[60:61]
	v_mov_b64_e32 v[30:31], v[62:63]
	v_mov_b64_e32 v[2:3], v[50:51]
	v_mov_b64_e32 v[4:5], v[52:53]
	v_mov_b64_e32 v[6:7], v[54:55]
	v_mov_b64_e32 v[8:9], v[56:57]
	v_mov_b64_e32 v[10:11], v[58:59]
	v_mov_b64_e32 v[12:13], v[60:61]
	v_mov_b64_e32 v[14:15], v[62:63]
	s_add_i32 s23, s33, s23
	s_cmpk_gt_i32 s23, 0xc7f
	s_cbranch_scc0 .LBB0_222

; #define TIDX get_tid_()
;   const int tid = TIDX, lane = tid & 63, wid = tid >> 6, wr = wid >> 1, wc = wid & 1, r = lane & 31, h = lane >> 5;
;   const int ch = (tid & 7) ^ ((tid >> 4) & 7);
;   unsigned avo[4], bvo[2];
; #pragma unroll
;   for (int i = 0; i < 4; ++i) avo[i] = (unsigned)(((tid >> 3) + 64 * i) * lda * 2 + ch * 16);
; #pragma unroll
;   for (int i = 0; i < 2; ++i) bvo[i] = (unsigned)(((tid >> 3) + 64 * i) * ldb * 2 + ch * 16);
;   const char* Ab = (const char*)A; const char* Bb = (const char*)Bt;
;   char* lw = lds + tid * 16;
;   const int nk = K >> 6;
;   const unsigned swz = (unsigned)((r >> 1) & 7);
;   const unsigned arow_u = (unsigned)((wr * 64 + r) * 128), brow_u = (unsigned)((wc * 64 + r) * 128);
;   const unsigned co0 = ((0u + h) ^ swz) << 4, co1 = ((2u + h) ^ swz) << 4, co2 = ((4u + h) ^ swz) << 4, co3 = ((6u + h) ^ swz) << 4;
; template <class Epi>
; DI void gemm_phase(const bf16_t* A, int lda, const bf16_t* Bt, int ldb, int K, int MT, int NTl, int SN, const Epi& epi, char* lds, bool rev = false) {
;     ...
;     for (L += gridDim.x; L < lmax; L += gridDim.x) if (tile_map(L, MT, NTl, SN, mt, nt)) { have = true; if (rev) mt = MT - 1 - mt; break; }
;     if (have) gemm_core<1>(A + (size_t)mt * 256 * lda, lda, Bt + (size_t)nt * 128 * ldb, ldb, K, dummy, lds);
.LBB0_226:
.Lx3_go:
	s_sub_i32 s58, s10, s8
	s_ashr_i32 s59, s58, 31
	s_lshl_b64 s[58:59], s[58:59], 19
	s_and_b64 s[58:59], s[58:59], s[54:55]
	s_sub_i32 s60, s68, s14
	s_ashr_i32 s61, s60, 31
	s_lshl_b64 s[60:61], s[60:61], 18
	s_and_b64 s[60:61], s[60:61], s[54:55]
	v_and_b32_e32 v84, 31, v129
	v_bfe_u32 v85, v129, 5, 1
	v_lshrrev_b32_e32 v86, 6, v129
	v_bfe_u32 v88, v129, 1, 3
	v_lshrrev_b32_e32 v87, 1, v86
	v_and_b32_e32 v86, 1, v86
	v_xor_b32_e32 v85, v85, v88
	v_lshl_add_u32 v87, v87, 6, v84
	v_lshl_add_u32 v86, v86, 6, v84
	v_lshlrev_b32_e32 v85, 4, v85
	v_lshlrev_b32_e32 v87, 7, v87
	v_lshlrev_b32_e32 v86, 7, v86
	v_add_u32_e32 v86, 0x8000, v86
	v_add_u32_e32 v76, v87, v85
	v_add_u32_e32 v80, v86, v85
	v_xor_b32_e32 v89, 0x20, v85
	v_add_u32_e32 v77, v87, v89
	v_add_u32_e32 v81, v86, v89
	v_xor_b32_e32 v89, 0x40, v85
	v_add_u32_e32 v78, v87, v89
	v_add_u32_e32 v82, v86, v89
	v_xor_b32_e32 v89, 0x60, v85
	v_add_u32_e32 v79, v87, v89
	v_add_u32_e32 v83, v86, v89
	v_add_u32_e32 v116, 0x18000, v76
	v_add_u32_e32 v120, 0x18000, v80
	v_add_u32_e32 v117, 0x18000, v77
	v_add_u32_e32 v121, 0x18000, v81
	v_add_u32_e32 v118, 0x18000, v78
	v_add_u32_e32 v122, 0x18000, v82
	v_add_u32_e32 v119, 0x18000, v79
	v_add_u32_e32 v123, 0x18000, v83
	v_lshlrev_b32_e32 v84, 4, v129
	s_nop 0
	v_readfirstlane_b32 s31, v84
	s_mov_b32 s25, 0
	s_cmp_eq_u32 s101, 1
	s_cbranch_scc1 .Lx3_first
	s_waitcnt vmcnt(63)
	s_branch .Lx3_w0

;     ...
;   for (int kt = 0; kt < nk; ++kt) {
;     if (kt + 1 < nk) asm volatile("s_waitcnt vmcnt(6)" ::: "memory");
;     else asm volatile("s_waitcnt vmcnt(0)" ::: "memory");
;     __builtin_amdgcn_s_barrier();
;     asm volatile("" ::: "memory");
;     if (kt + 2 < nk) { const int st2 = (st >= 1) ? st - 1 : 2; GEMM_ISSUE(kt + 2, st2); }
;     const char* la = lds + st * STAGE_B;
;     const char* lb = la + 32768;
;     const unsigned sa_u = (unsigned)(size_t)la + arow_u, sb_u = (unsigned)(size_t)lb + brow_u;
;     const unsigned a0 = sa_u + co0, a1 = sa_u + co1, a2 = sa_u + co2, a3 = sa_u + co3;
;     const unsigned b0 = sb_u + co0, b1 = sb_u + co1, b2 = sb_u + co2, b3 = sb_u + co3;
;     {
;       bf16x8 p0, p1, q0, q1, u0, u1, w0, w1;
;       asm volatile(
;         "ds_read_b128 %4, %12\n\tds_read_b128 %5, %12 offset:4096\n\tds_read_b128 %6, %16\n\tds_read_b128 %7, %16 offset:4096\n\t"
;         "ds_read_b128 %8, %13\n\tds_read_b128 %9, %13 offset:4096\n\tds_read_b128 %10, %17\n\tds_read_b128 %11, %17 offset:4096\n\t"
;         "s_waitcnt lgkmcnt(4)\n\t"
;         "v_mfma_f32_32x32x16_bf16 %0, %4, %6, %0\n\tv_mfma_f32_32x32x16_bf16 %1, %4, %7, %1\n\tv_mfma_f32_32x32x16_bf16 %2, %5, %6, %2\n\tv_mfma_f32_32x32x16_bf16 %3, %5, %7, %3\n\t"
;         "ds_read_b128 %4, %14\n\tds_read_b128 %5, %14 offset:4096\n\tds_read_b128 %6, %18\n\tds_read_b128 %7, %18 offset:4096\n\t"
;         "s_waitcnt lgkmcnt(4)\n\t"
;         "v_mfma_f32_32x32x16_bf16 %0, %8, %10, %0\n\tv_mfma_f32_32x32x16_bf16 %1, %8, %11, %1\n\tv_mfma_f32_32x32x16_bf16 %2, %9, %10, %2\n\tv_mfma_f32_32x32x16_bf16 %3, %9, %11, %3\n\t"
;         "ds_read_b128 %8, %15\n\tds_read_b128 %9, %15 offset:4096\n\tds_read_b128 %10, %19\n\tds_read_b128 %11, %19 offset:4096\n\t"
;         "s_waitcnt lgkmcnt(4)\n\t"
;         "v_mfma_f32_32x32x16_bf16 %0, %4, %6, %0\n\tv_mfma_f32_32x32x16_bf16 %1, %4, %7, %1\n\tv_mfma_f32_32x32x16_bf16 %2, %5, %6, %2\n\tv_mfma_f32_32x32x16_bf16 %3, %5, %7, %3\n\t"
;         "s_waitcnt lgkmcnt(0)\n\t"
;         "v_mfma_f32_32x32x16_bf16 %0, %8, %10, %0\n\tv_mfma_f32_32x32x16_bf16 %1, %8, %11, %1\n\tv_mfma_f32_32x32x16_bf16 %2, %9, %10, %2\n\tv_mfma_f32_32x32x16_bf16 %3, %9, %11, %3"
;         : "+v"(acc[0][0]), "+v"(acc[0][1]), "+v"(acc[1][0]), "+v"(acc[1][1]),
;           "=&v"(p0), "=&v"(p1), "=&v"(q0), "=&v"(q1), "=&v"(u0), "=&v"(u1), "=&v"(w0), "=&v"(w1)
.Lx3_w0:
	s_barrier
	s_cmp_eq_u32 s100, 1
	s_cbranch_scc1 .Lx3_v1
	s_cmp_eq_u32 s100, 2
	s_cbranch_scc1 .Lx3_v2
	ds_read_b128 v[84:87], v76
	ds_read_b128 v[88:91], v76 offset:4096
	ds_read_b128 v[92:95], v80
	ds_read_b128 v[96:99], v80 offset:4096
	s_mov_b32 s24, 0x100
	s_mov_b32 s25, 0
	s_add_u32 m0, s31, 0x18000
	v_lshl_add_u64 v[124:125], v[64:65], 0, s[24:25]
	global_load_lds_dwordx4 v[124:125], off
	s_add_u32 m0, s31, 0x1a000
	v_lshl_add_u64 v[126:127], v[66:67], 0, s[24:25]
	global_load_lds_dwordx4 v[126:127], off
	ds_read_b128 v[100:103], v77
	ds_read_b128 v[104:107], v77 offset:4096
	ds_read_b128 v[108:111], v81
	ds_read_b128 v[112:115], v81 offset:4096
	s_waitcnt lgkmcnt(4)
	v_mfma_f32_32x32x16_bf16 v[48:63], v[84:87], v[92:95], v[48:63]
	s_add_u32 m0, s31, 0x1c000
	v_lshl_add_u64 v[124:125], v[68:69], 0, s[24:25]
	global_load_lds_dwordx4 v[124:125], off
	v_mfma_f32_32x32x16_bf16 v[32:47], v[84:87], v[96:99], v[32:47]
	v_mfma_f32_32x32x16_bf16 v[16:31], v[88:91], v[92:95], v[16:31]
	s_add_u32 m0, s31, 0x1e000
	v_lshl_add_u64 v[126:127], v[70:71], 0, s[24:25]
	global_load_lds_dwordx4 v[126:127], off
	v_mfma_f32_32x32x16_bf16 v[0:15], v[88:91], v[96:99], v[0:15]
	ds_read_b128 v[84:87], v78
	ds_read_b128 v[88:91], v78 offset:4096
	ds_read_b128 v[92:95], v82
	ds_read_b128 v[96:99], v82 offset:4096
	s_waitcnt lgkmcnt(4)
	v_mfma_f32_32x32x16_bf16 v[48:63], v[100:103], v[108:111], v[48:63]
	s_add_u32 m0, s31, 0x20000
	v_lshl_add_u64 v[124:125], v[72:73], 0, s[24:25]
	global_load_lds_dwordx4 v[124:125], off
	v_mfma_f32_32x32x16_bf16 v[32:47], v[100:103], v[112:115], v[32:47]
	v_mfma_f32_32x32x16_bf16 v[16:31], v[104:107], v[108:111], v[16:31]
	s_add_u32 m0, s31, 0x22000
	v_lshl_add_u64 v[126:127], v[74:75], 0, s[24:25]
	global_load_lds_dwordx4 v[126:127], off
	v_mfma_f32_32x32x16_bf16 v[0:15], v[104:107], v[112:115], v[0:15]
	ds_read_b128 v[100:103], v79
	ds_read_b128 v[104:107], v79 offset:4096
	ds_read_b128 v[108:111], v83
	ds_read_b128 v[112:115], v83 offset:4096
	s_waitcnt lgkmcnt(4)
	v_mfma_f32_32x32x16_bf16 v[48:63], v[84:87], v[92:95], v[48:63]
	v_mfma_f32_32x32x16_bf16 v[32:47], v[84:87], v[96:99], v[32:47]
	v_mfma_f32_32x32x16_bf16 v[16:31], v[88:91], v[92:95], v[16:31]
	v_mfma_f32_32x32x16_bf16 v[0:15], v[88:91], v[96:99], v[0:15]
	s_waitcnt vmcnt(6) lgkmcnt(0)
	s_barrier
	ds_read_b128 v[84:87], v76 offset:49152
	ds_read_b128 v[88:91], v76 offset:53248
	ds_read_b128 v[92:95], v80 offset:49152
	ds_read_b128 v[96:99], v80 offset:53248
	v_mfma_f32_32x32x16_bf16 v[48:63], v[100:103], v[108:111], v[48:63]
	s_mov_b32 s24, 0x180
	s_mov_b32 s25, 0
	s_mov_b32 m0, s31
	v_lshl_add_u64 v[124:125], v[64:65], 0, s[24:25]
	global_load_lds_dwordx4 v[124:125], off
	v_mfma_f32_32x32x16_bf16 v[32:47], v[100:103], v[112:115], v[32:47]
	v_mfma_f32_32x32x16_bf16 v[16:31], v[104:107], v[108:111], v[16:31]
	s_add_u32 m0, s31, 0x2000
	v_lshl_add_u64 v[126:127], v[66:67], 0, s[24:25]
	global_load_lds_dwordx4 v[126:127], off
	v_mfma_f32_32x32x16_bf16 v[0:15], v[104:107], v[112:115], v[0:15]
	ds_read_b128 v[100:103], v77 offset:49152
	ds_read_b128 v[104:107], v77 offset:53248
	ds_read_b128 v[108:111], v81 offset:49152
	ds_read_b128 v[112:115], v81 offset:53248
	s_waitcnt lgkmcnt(4)
	v_mfma_f32_32x32x16_bf16 v[48:63], v[84:87], v[92:95], v[48:63]
	s_add_u32 m0, s31, 0x4000
	v_lshl_add_u64 v[124:125], v[68:69], 0, s[24:25]
	global_load_lds_dwordx4 v[124:125], off
	v_mfma_f32_32x32x16_bf16 v[32:47], v[84:87], v[96:99], v[32:47]
	v_mfma_f32_32x32x16_bf16 v[16:31], v[88:91], v[92:95], v[16:31]
	s_add_u32 m0, s31, 0x6000
	v_lshl_add_u64 v[126:127], v[70:71], 0, s[24:25]
	global_load_lds_dwordx4 v[126:127], off
	v_mfma_f32_32x32x16_bf16 v[0:15], v[88:91], v[96:99], v[0:15]
	ds_read_b128 v[84:87], v78 offset:49152
	ds_read_b128 v[88:91], v78 offset:53248
	ds_read_b128 v[92:95], v82 offset:49152
	ds_read_b128 v[96:99], v82 offset:53248
	s_waitcnt lgkmcnt(4)
	v_mfma_f32_32x32x16_bf16 v[48:63], v[100:103], v[108:111], v[48:63]
	s_add_u32 m0, s31, 0x8000
	v_lshl_add_u64 v[124:125], v[72:73], 0, s[24:25]
	global_load_lds_dwordx4 v[124:125], off
	v_mfma_f32_32x32x16_bf16 v[32:47], v[100:103], v[112:115], v[32:47]
	v_mfma_f32_32x32x16_bf16 v[16:31], v[104:107], v[108:111], v[16:31]
	s_add_u32 m0, s31, 0xa000
	v_lshl_add_u64 v[126:127], v[74:75], 0, s[24:25]
	global_load_lds_dwordx4 v[126:127], off
	v_mfma_f32_32x32x16_bf16 v[0:15], v[104:107], v[112:115], v[0:15]
	ds_read_b128 v[100:103], v79 offset:49152
	ds_read_b128 v[104:107], v79 offset:53248
	ds_read_b128 v[108:111], v83 offset:49152
	ds_read_b128 v[112:115], v83 offset:53248
	s_waitcnt lgkmcnt(4)
	v_mfma_f32_32x32x16_bf16 v[48:63], v[84:87], v[92:95], v[48:63]
	v_mfma_f32_32x32x16_bf16 v[32:47], v[84:87], v[96:99], v[32:47]
	v_mfma_f32_32x32x16_bf16 v[16:31], v[88:91], v[92:95], v[16:31]
	v_mfma_f32_32x32x16_bf16 v[0:15], v[88:91], v[96:99], v[0:15]
	s_waitcnt vmcnt(6) lgkmcnt(0)
	s_barrier
;     ...
;   for (int kt = 0; kt < nk; ++kt) {
;     if (kt + 1 < nk) asm volatile("s_waitcnt vmcnt(6)" ::: "memory");
;     else asm volatile("s_waitcnt vmcnt(0)" ::: "memory");
;     __builtin_amdgcn_s_barrier();
;     asm volatile("" ::: "memory");
;     if (kt + 2 < nk) { const int st2 = (st >= 1) ? st - 1 : 2; GEMM_ISSUE(kt + 2, st2); }
;     const char* la = lds + st * STAGE_B;
;     const char* lb = la + 32768;
;     const unsigned sa_u = (unsigned)(size_t)la + arow_u, sb_u = (unsigned)(size_t)lb + brow_u;
;     const unsigned a0 = sa_u + co0, a1 = sa_u + co1, a2 = sa_u + co2, a3 = sa_u + co3;
;     const unsigned b0 = sb_u + co0, b1 = sb_u + co1, b2 = sb_u + co2, b3 = sb_u + co3;
;     {
;       bf16x8 p0, p1, q0, q1, u0, u1, w0, w1;
;       asm volatile(
;         "ds_read_b128 %4, %12\n\tds_read_b128 %5, %12 offset:4096\n\tds_read_b128 %6, %16\n\tds_read_b128 %7, %16 offset:4096\n\t"
;         "ds_read_b128 %8, %13\n\tds_read_b128 %9, %13 offset:4096\n\tds_read_b128 %10, %17\n\tds_read_b128 %11, %17 offset:4096\n\t"
;         "s_waitcnt lgkmcnt(4)\n\t"
;         "v_mfma_f32_32x32x16_bf16 %0, %4, %6, %0\n\tv_mfma_f32_32x32x16_bf16 %1, %4, %7, %1\n\tv_mfma_f32_32x32x16_bf16 %2, %5, %6, %2\n\tv_mfma_f32_32x32x16_bf16 %3, %5, %7, %3\n\t"
;         "ds_read_b128 %4, %14\n\tds_read_b128 %5, %14 offset:4096\n\tds_read_b128 %6, %18\n\tds_read_b128 %7, %18 offset:4096\n\t"
;         "s_waitcnt lgkmcnt(4)\n\t"
;         "v_mfma_f32_32x32x16_bf16 %0, %8, %10, %0\n\tv_mfma_f32_32x32x16_bf16 %1, %8, %11, %1\n\tv_mfma_f32_32x32x16_bf16 %2, %9, %10, %2\n\tv_mfma_f32_32x32x16_bf16 %3, %9, %11, %3\n\t"
;         "ds_read_b128 %8, %15\n\tds_read_b128 %9, %15 offset:4096\n\tds_read_b128 %10, %19\n\tds_read_b128 %11, %19 offset:4096\n\t"
;         "s_waitcnt lgkmcnt(4)\n\t"
;         "v_mfma_f32_32x32x16_bf16 %0, %4, %6, %0\n\tv_mfma_f32_32x32x16_bf16 %1, %4, %7, %1\n\tv_mfma_f32_32x32x16_bf16 %2, %5, %6, %2\n\tv_mfma_f32_32x32x16_bf16 %3, %5, %7, %3\n\t"
;         "s_waitcnt lgkmcnt(0)\n\t"
;         "v_mfma_f32_32x32x16_bf16 %0, %8, %10, %0\n\tv_mfma_f32_32x32x16_bf16 %1, %8, %11, %1\n\tv_mfma_f32_32x32x16_bf16 %2, %9, %10, %2\n\tv_mfma_f32_32x32x16_bf16 %3, %9, %11, %3"
;         : "+v"(acc[0][0]), "+v"(acc[0][1]), "+v"(acc[1][0]), "+v"(acc[1][1]),
;           "=&v"(p0), "=&v"(p1), "=&v"(q0), "=&v"(q1), "=&v"(u0), "=&v"(u1), "=&v"(w0), "=&v"(w1)
	ds_read_b128 v[84:87], v116
	ds_read_b128 v[88:91], v116 offset:4096
	ds_read_b128 v[92:95], v120
	ds_read_b128 v[96:99], v120 offset:4096
	v_mfma_f32_32x32x16_bf16 v[48:63], v[100:103], v[108:111], v[48:63]
	s_mov_b32 s24, 0x200
	s_mov_b32 s25, 0
	s_add_u32 m0, s31, 0xc000
	v_lshl_add_u64 v[124:125], v[64:65], 0, s[24:25]
	global_load_lds_dwordx4 v[124:125], off
	v_mfma_f32_32x32x16_bf16 v[32:47], v[100:103], v[112:115], v[32:47]
	v_mfma_f32_32x32x16_bf16 v[16:31], v[104:107], v[108:111], v[16:31]
	s_add_u32 m0, s31, 0xe000
	v_lshl_add_u64 v[126:127], v[66:67], 0, s[24:25]
	global_load_lds_dwordx4 v[126:127], off
	v_mfma_f32_32x32x16_bf16 v[0:15], v[104:107], v[112:115], v[0:15]
	ds_read_b128 v[100:103], v117
	ds_read_b128 v[104:107], v117 offset:4096
	ds_read_b128 v[108:111], v121
	ds_read_b128 v[112:115], v121 offset:4096
	s_waitcnt lgkmcnt(4)
	v_mfma_f32_32x32x16_bf16 v[48:63], v[84:87], v[92:95], v[48:63]
	s_add_u32 m0, s31, 0x10000
	v_lshl_add_u64 v[124:125], v[68:69], 0, s[24:25]
	global_load_lds_dwordx4 v[124:125], off
	v_mfma_f32_32x32x16_bf16 v[32:47], v[84:87], v[96:99], v[32:47]
	v_mfma_f32_32x32x16_bf16 v[16:31], v[88:91], v[92:95], v[16:31]
	s_add_u32 m0, s31, 0x12000
	v_lshl_add_u64 v[126:127], v[70:71], 0, s[24:25]
	global_load_lds_dwordx4 v[126:127], off
	v_mfma_f32_32x32x16_bf16 v[0:15], v[88:91], v[96:99], v[0:15]
	ds_read_b128 v[84:87], v118
	ds_read_b128 v[88:91], v118 offset:4096
	ds_read_b128 v[92:95], v122
	ds_read_b128 v[96:99], v122 offset:4096
	s_waitcnt lgkmcnt(4)
	v_mfma_f32_32x32x16_bf16 v[48:63], v[100:103], v[108:111], v[48:63]
	s_add_u32 m0, s31, 0x14000
	v_lshl_add_u64 v[124:125], v[72:73], 0, s[24:25]
	global_load_lds_dwordx4 v[124:125], off
	v_mfma_f32_32x32x16_bf16 v[32:47], v[100:103], v[112:115], v[32:47]
	v_mfma_f32_32x32x16_bf16 v[16:31], v[104:107], v[108:111], v[16:31]
	s_add_u32 m0, s31, 0x16000
	v_lshl_add_u64 v[126:127], v[74:75], 0, s[24:25]
	global_load_lds_dwordx4 v[126:127], off
	v_mfma_f32_32x32x16_bf16 v[0:15], v[104:107], v[112:115], v[0:15]
	ds_read_b128 v[100:103], v119
	ds_read_b128 v[104:107], v119 offset:4096
	ds_read_b128 v[108:111], v123
	ds_read_b128 v[112:115], v123 offset:4096
	s_waitcnt lgkmcnt(4)
	v_mfma_f32_32x32x16_bf16 v[48:63], v[84:87], v[92:95], v[48:63]
	v_mfma_f32_32x32x16_bf16 v[32:47], v[84:87], v[96:99], v[32:47]
	v_mfma_f32_32x32x16_bf16 v[16:31], v[88:91], v[92:95], v[16:31]
	v_mfma_f32_32x32x16_bf16 v[0:15], v[88:91], v[96:99], v[0:15]
	s_waitcnt vmcnt(6) lgkmcnt(0)
	s_barrier
	ds_read_b128 v[84:87], v76
	ds_read_b128 v[88:91], v76 offset:4096
	ds_read_b128 v[92:95], v80
	ds_read_b128 v[96:99], v80 offset:4096
	v_mfma_f32_32x32x16_bf16 v[48:63], v[100:103], v[108:111], v[48:63]
	s_mov_b32 s24, 0x280
	s_mov_b32 s25, 0
	s_add_u32 m0, s31, 0x18000
	v_lshl_add_u64 v[124:125], v[64:65], 0, s[24:25]
	global_load_lds_dwordx4 v[124:125], off
	v_mfma_f32_32x32x16_bf16 v[32:47], v[100:103], v[112:115], v[32:47]
	v_mfma_f32_32x32x16_bf16 v[16:31], v[104:107], v[108:111], v[16:31]
	s_add_u32 m0, s31, 0x1a000
	v_lshl_add_u64 v[126:127], v[66:67], 0, s[24:25]
	global_load_lds_dwordx4 v[126:127], off
	v_mfma_f32_32x32x16_bf16 v[0:15], v[104:107], v[112:115], v[0:15]
	ds_read_b128 v[100:103], v77
	ds_read_b128 v[104:107], v77 offset:4096
	ds_read_b128 v[108:111], v81
	ds_read_b128 v[112:115], v81 offset:4096
	s_waitcnt lgkmcnt(4)
	v_mfma_f32_32x32x16_bf16 v[48:63], v[84:87], v[92:95], v[48:63]
	s_add_u32 m0, s31, 0x1c000
	v_lshl_add_u64 v[124:125], v[68:69], 0, s[24:25]
	global_load_lds_dwordx4 v[124:125], off
	v_mfma_f32_32x32x16_bf16 v[32:47], v[84:87], v[96:99], v[32:47]
	v_mfma_f32_32x32x16_bf16 v[16:31], v[88:91], v[92:95], v[16:31]
	s_add_u32 m0, s31, 0x1e000
	v_lshl_add_u64 v[126:127], v[70:71], 0, s[24:25]
	global_load_lds_dwordx4 v[126:127], off
	v_mfma_f32_32x32x16_bf16 v[0:15], v[88:91], v[96:99], v[0:15]
	ds_read_b128 v[84:87], v78
	ds_read_b128 v[88:91], v78 offset:4096
	ds_read_b128 v[92:95], v82
	ds_read_b128 v[96:99], v82 offset:4096
	s_waitcnt lgkmcnt(4)
	v_mfma_f32_32x32x16_bf16 v[48:63], v[100:103], v[108:111], v[48:63]
	s_add_u32 m0, s31, 0x20000
	v_lshl_add_u64 v[124:125], v[72:73], 0, s[24:25]
	global_load_lds_dwordx4 v[124:125], off
	v_mfma_f32_32x32x16_bf16 v[32:47], v[100:103], v[112:115], v[32:47]
	v_mfma_f32_32x32x16_bf16 v[16:31], v[104:107], v[108:111], v[16:31]
	s_add_u32 m0, s31, 0x22000
	v_lshl_add_u64 v[126:127], v[74:75], 0, s[24:25]
	global_load_lds_dwordx4 v[126:127], off
	v_mfma_f32_32x32x16_bf16 v[0:15], v[104:107], v[112:115], v[0:15]
	ds_read_b128 v[100:103], v79
	ds_read_b128 v[104:107], v79 offset:4096
	ds_read_b128 v[108:111], v83
	ds_read_b128 v[112:115], v83 offset:4096
	s_waitcnt lgkmcnt(4)
	v_mfma_f32_32x32x16_bf16 v[48:63], v[84:87], v[92:95], v[48:63]
	v_mfma_f32_32x32x16_bf16 v[32:47], v[84:87], v[96:99], v[32:47]
	v_mfma_f32_32x32x16_bf16 v[16:31], v[88:91], v[92:95], v[16:31]
	v_mfma_f32_32x32x16_bf16 v[0:15], v[88:91], v[96:99], v[0:15]
	s_waitcnt vmcnt(6) lgkmcnt(0)
	s_barrier
;     ...
;   for (int kt = 0; kt < nk; ++kt) {
;     if (kt + 1 < nk) asm volatile("s_waitcnt vmcnt(6)" ::: "memory");
;     else asm volatile("s_waitcnt vmcnt(0)" ::: "memory");
;     __builtin_amdgcn_s_barrier();
;     asm volatile("" ::: "memory");
;     if (kt + 2 < nk) { const int st2 = (st >= 1) ? st - 1 : 2; GEMM_ISSUE(kt + 2, st2); }
;     const char* la = lds + st * STAGE_B;
;     const char* lb = la + 32768;
;     const unsigned sa_u = (unsigned)(size_t)la + arow_u, sb_u = (unsigned)(size_t)lb + brow_u;
;     const unsigned a0 = sa_u + co0, a1 = sa_u + co1, a2 = sa_u + co2, a3 = sa_u + co3;
;     const unsigned b0 = sb_u + co0, b1 = sb_u + co1, b2 = sb_u + co2, b3 = sb_u + co3;
;     {
;       bf16x8 p0, p1, q0, q1, u0, u1, w0, w1;
;       asm volatile(
;         "ds_read_b128 %4, %12\n\tds_read_b128 %5, %12 offset:4096\n\tds_read_b128 %6, %16\n\tds_read_b128 %7, %16 offset:4096\n\t"
;         "ds_read_b128 %8, %13\n\tds_read_b128 %9, %13 offset:4096\n\tds_read_b128 %10, %17\n\tds_read_b128 %11, %17 offset:4096\n\t"
;         "s_waitcnt lgkmcnt(4)\n\t"
;         "v_mfma_f32_32x32x16_bf16 %0, %4, %6, %0\n\tv_mfma_f32_32x32x16_bf16 %1, %4, %7, %1\n\tv_mfma_f32_32x32x16_bf16 %2, %5, %6, %2\n\tv_mfma_f32_32x32x16_bf16 %3, %5, %7, %3\n\t"
;         "ds_read_b128 %4, %14\n\tds_read_b128 %5, %14 offset:4096\n\tds_read_b128 %6, %18\n\tds_read_b128 %7, %18 offset:4096\n\t"
;         "s_waitcnt lgkmcnt(4)\n\t"
;         "v_mfma_f32_32x32x16_bf16 %0, %8, %10, %0\n\tv_mfma_f32_32x32x16_bf16 %1, %8, %11, %1\n\tv_mfma_f32_32x32x16_bf16 %2, %9, %10, %2\n\tv_mfma_f32_32x32x16_bf16 %3, %9, %11, %3\n\t"
;         "ds_read_b128 %8, %15\n\tds_read_b128 %9, %15 offset:4096\n\tds_read_b128 %10, %19\n\tds_read_b128 %11, %19 offset:4096\n\t"
;         "s_waitcnt lgkmcnt(4)\n\t"
;         "v_mfma_f32_32x32x16_bf16 %0, %4, %6, %0\n\tv_mfma_f32_32x32x16_bf16 %1, %4, %7, %1\n\tv_mfma_f32_32x32x16_bf16 %2, %5, %6, %2\n\tv_mfma_f32_32x32x16_bf16 %3, %5, %7, %3\n\t"
;         "s_waitcnt lgkmcnt(0)\n\t"
;         "v_mfma_f32_32x32x16_bf16 %0, %8, %10, %0\n\tv_mfma_f32_32x32x16_bf16 %1, %8, %11, %1\n\tv_mfma_f32_32x32x16_bf16 %2, %9, %10, %2\n\tv_mfma_f32_32x32x16_bf16 %3, %9, %11, %3"
;         : "+v"(acc[0][0]), "+v"(acc[0][1]), "+v"(acc[1][0]), "+v"(acc[1][1]),
;           "=&v"(p0), "=&v"(p1), "=&v"(q0), "=&v"(q1), "=&v"(u0), "=&v"(u1), "=&v"(w0), "=&v"(w1)
	ds_read_b128 v[84:87], v76 offset:49152
	ds_read_b128 v[88:91], v76 offset:53248
	ds_read_b128 v[92:95], v80 offset:49152
	ds_read_b128 v[96:99], v80 offset:53248
	v_mfma_f32_32x32x16_bf16 v[48:63], v[100:103], v[108:111], v[48:63]
	s_mov_b32 s24, 0x300
	s_mov_b32 s25, 0
	s_mov_b32 m0, s31
	v_lshl_add_u64 v[124:125], v[64:65], 0, s[24:25]
	global_load_lds_dwordx4 v[124:125], off
	v_mfma_f32_32x32x16_bf16 v[32:47], v[100:103], v[112:115], v[32:47]
	v_mfma_f32_32x32x16_bf16 v[16:31], v[104:107], v[108:111], v[16:31]
	s_add_u32 m0, s31, 0x2000
	v_lshl_add_u64 v[126:127], v[66:67], 0, s[24:25]
	global_load_lds_dwordx4 v[126:127], off
	v_mfma_f32_32x32x16_bf16 v[0:15], v[104:107], v[112:115], v[0:15]
	ds_read_b128 v[100:103], v77 offset:49152
	ds_read_b128 v[104:107], v77 offset:53248
	ds_read_b128 v[108:111], v81 offset:49152
	ds_read_b128 v[112:115], v81 offset:53248
	s_waitcnt lgkmcnt(4)
	v_mfma_f32_32x32x16_bf16 v[48:63], v[84:87], v[92:95], v[48:63]
	s_add_u32 m0, s31, 0x4000
	v_lshl_add_u64 v[124:125], v[68:69], 0, s[24:25]
	global_load_lds_dwordx4 v[124:125], off
	v_mfma_f32_32x32x16_bf16 v[32:47], v[84:87], v[96:99], v[32:47]
	v_mfma_f32_32x32x16_bf16 v[16:31], v[88:91], v[92:95], v[16:31]
	s_add_u32 m0, s31, 0x6000
	v_lshl_add_u64 v[126:127], v[70:71], 0, s[24:25]
	global_load_lds_dwordx4 v[126:127], off
	v_mfma_f32_32x32x16_bf16 v[0:15], v[88:91], v[96:99], v[0:15]
	ds_read_b128 v[84:87], v78 offset:49152
	ds_read_b128 v[88:91], v78 offset:53248
	ds_read_b128 v[92:95], v82 offset:49152
	ds_read_b128 v[96:99], v82 offset:53248
	s_waitcnt lgkmcnt(4)
	v_mfma_f32_32x32x16_bf16 v[48:63], v[100:103], v[108:111], v[48:63]
	s_add_u32 m0, s31, 0x8000
	v_lshl_add_u64 v[124:125], v[72:73], 0, s[24:25]
	global_load_lds_dwordx4 v[124:125], off
	v_mfma_f32_32x32x16_bf16 v[32:47], v[100:103], v[112:115], v[32:47]
	v_mfma_f32_32x32x16_bf16 v[16:31], v[104:107], v[108:111], v[16:31]
	s_add_u32 m0, s31, 0xa000
	v_lshl_add_u64 v[126:127], v[74:75], 0, s[24:25]
	global_load_lds_dwordx4 v[126:127], off
	v_mfma_f32_32x32x16_bf16 v[0:15], v[104:107], v[112:115], v[0:15]
	ds_read_b128 v[100:103], v79 offset:49152
	ds_read_b128 v[104:107], v79 offset:53248
	ds_read_b128 v[108:111], v83 offset:49152
	ds_read_b128 v[112:115], v83 offset:53248
	s_waitcnt lgkmcnt(4)
	v_mfma_f32_32x32x16_bf16 v[48:63], v[84:87], v[92:95], v[48:63]
	v_mfma_f32_32x32x16_bf16 v[32:47], v[84:87], v[96:99], v[32:47]
	v_mfma_f32_32x32x16_bf16 v[16:31], v[88:91], v[92:95], v[16:31]
	v_mfma_f32_32x32x16_bf16 v[0:15], v[88:91], v[96:99], v[0:15]
	s_waitcnt vmcnt(6) lgkmcnt(0)
	s_barrier
	ds_read_b128 v[84:87], v116
	ds_read_b128 v[88:91], v116 offset:4096
	ds_read_b128 v[92:95], v120
	ds_read_b128 v[96:99], v120 offset:4096
	v_mfma_f32_32x32x16_bf16 v[48:63], v[100:103], v[108:111], v[48:63]
	s_mov_b32 s24, 0x380
	s_mov_b32 s25, 0
	s_add_u32 m0, s31, 0xc000
	v_lshl_add_u64 v[124:125], v[64:65], 0, s[24:25]
	global_load_lds_dwordx4 v[124:125], off
	v_mfma_f32_32x32x16_bf16 v[32:47], v[100:103], v[112:115], v[32:47]
	v_mfma_f32_32x32x16_bf16 v[16:31], v[104:107], v[108:111], v[16:31]
	s_add_u32 m0, s31, 0xe000
	v_lshl_add_u64 v[126:127], v[66:67], 0, s[24:25]
	global_load_lds_dwordx4 v[126:127], off
	v_mfma_f32_32x32x16_bf16 v[0:15], v[104:107], v[112:115], v[0:15]
	ds_read_b128 v[100:103], v117
	ds_read_b128 v[104:107], v117 offset:4096
	ds_read_b128 v[108:111], v121
	ds_read_b128 v[112:115], v121 offset:4096
	s_waitcnt lgkmcnt(4)
	v_mfma_f32_32x32x16_bf16 v[48:63], v[84:87], v[92:95], v[48:63]
	s_add_u32 m0, s31, 0x10000
	v_lshl_add_u64 v[124:125], v[68:69], 0, s[24:25]
	global_load_lds_dwordx4 v[124:125], off
	v_mfma_f32_32x32x16_bf16 v[32:47], v[84:87], v[96:99], v[32:47]
	v_mfma_f32_32x32x16_bf16 v[16:31], v[88:91], v[92:95], v[16:31]
	s_add_u32 m0, s31, 0x12000
	v_lshl_add_u64 v[126:127], v[70:71], 0, s[24:25]
	global_load_lds_dwordx4 v[126:127], off
	v_mfma_f32_32x32x16_bf16 v[0:15], v[88:91], v[96:99], v[0:15]
	ds_read_b128 v[84:87], v118
	ds_read_b128 v[88:91], v118 offset:4096
	ds_read_b128 v[92:95], v122
	ds_read_b128 v[96:99], v122 offset:4096
	s_waitcnt lgkmcnt(4)
	v_mfma_f32_32x32x16_bf16 v[48:63], v[100:103], v[108:111], v[48:63]
	s_add_u32 m0, s31, 0x14000
	v_lshl_add_u64 v[124:125], v[72:73], 0, s[24:25]
	global_load_lds_dwordx4 v[124:125], off
	v_mfma_f32_32x32x16_bf16 v[32:47], v[100:103], v[112:115], v[32:47]
	v_mfma_f32_32x32x16_bf16 v[16:31], v[104:107], v[108:111], v[16:31]
	s_add_u32 m0, s31, 0x16000
	v_lshl_add_u64 v[126:127], v[74:75], 0, s[24:25]
	global_load_lds_dwordx4 v[126:127], off
	v_mfma_f32_32x32x16_bf16 v[0:15], v[104:107], v[112:115], v[0:15]
	ds_read_b128 v[100:103], v119
	ds_read_b128 v[104:107], v119 offset:4096
	ds_read_b128 v[108:111], v123
	ds_read_b128 v[112:115], v123 offset:4096
	s_waitcnt lgkmcnt(4)
	v_mfma_f32_32x32x16_bf16 v[48:63], v[84:87], v[92:95], v[48:63]
	v_mfma_f32_32x32x16_bf16 v[32:47], v[84:87], v[96:99], v[32:47]
	v_mfma_f32_32x32x16_bf16 v[16:31], v[88:91], v[92:95], v[16:31]
	v_mfma_f32_32x32x16_bf16 v[0:15], v[88:91], v[96:99], v[0:15]
	s_waitcnt vmcnt(6) lgkmcnt(0)
	s_barrier
;     ...
;   for (int kt = 0; kt < nk; ++kt) {
;     if (kt + 1 < nk) asm volatile("s_waitcnt vmcnt(6)" ::: "memory");
;     else asm volatile("s_waitcnt vmcnt(0)" ::: "memory");
;     __builtin_amdgcn_s_barrier();
;     asm volatile("" ::: "memory");
;     if (kt + 2 < nk) { const int st2 = (st >= 1) ? st - 1 : 2; GEMM_ISSUE(kt + 2, st2); }
;     const char* la = lds + st * STAGE_B;
;     const char* lb = la + 32768;
;     const unsigned sa_u = (unsigned)(size_t)la + arow_u, sb_u = (unsigned)(size_t)lb + brow_u;
;     const unsigned a0 = sa_u + co0, a1 = sa_u + co1, a2 = sa_u + co2, a3 = sa_u + co3;
;     const unsigned b0 = sb_u + co0, b1 = sb_u + co1, b2 = sb_u + co2, b3 = sb_u + co3;
;     {
;       bf16x8 p0, p1, q0, q1, u0, u1, w0, w1;
;       asm volatile(
;         "ds_read_b128 %4, %12\n\tds_read_b128 %5, %12 offset:4096\n\tds_read_b128 %6, %16\n\tds_read_b128 %7, %16 offset:4096\n\t"
;         "ds_read_b128 %8, %13\n\tds_read_b128 %9, %13 offset:4096\n\tds_read_b128 %10, %17\n\tds_read_b128 %11, %17 offset:4096\n\t"
;         "s_waitcnt lgkmcnt(4)\n\t"
;         "v_mfma_f32_32x32x16_bf16 %0, %4, %6, %0\n\tv_mfma_f32_32x32x16_bf16 %1, %4, %7, %1\n\tv_mfma_f32_32x32x16_bf16 %2, %5, %6, %2\n\tv_mfma_f32_32x32x16_bf16 %3, %5, %7, %3\n\t"
;         "ds_read_b128 %4, %14\n\tds_read_b128 %5, %14 offset:4096\n\tds_read_b128 %6, %18\n\tds_read_b128 %7, %18 offset:4096\n\t"
;         "s_waitcnt lgkmcnt(4)\n\t"
;         "v_mfma_f32_32x32x16_bf16 %0, %8, %10, %0\n\tv_mfma_f32_32x32x16_bf16 %1, %8, %11, %1\n\tv_mfma_f32_32x32x16_bf16 %2, %9, %10, %2\n\tv_mfma_f32_32x32x16_bf16 %3, %9, %11, %3\n\t"
;         "ds_read_b128 %8, %15\n\tds_read_b128 %9, %15 offset:4096\n\tds_read_b128 %10, %19\n\tds_read_b128 %11, %19 offset:4096\n\t"
;         "s_waitcnt lgkmcnt(4)\n\t"
;         "v_mfma_f32_32x32x16_bf16 %0, %4, %6, %0\n\tv_mfma_f32_32x32x16_bf16 %1, %4, %7, %1\n\tv_mfma_f32_32x32x16_bf16 %2, %5, %6, %2\n\tv_mfma_f32_32x32x16_bf16 %3, %5, %7, %3\n\t"
;         "s_waitcnt lgkmcnt(0)\n\t"
;         "v_mfma_f32_32x32x16_bf16 %0, %8, %10, %0\n\tv_mfma_f32_32x32x16_bf16 %1, %8, %11, %1\n\tv_mfma_f32_32x32x16_bf16 %2, %9, %10, %2\n\tv_mfma_f32_32x32x16_bf16 %3, %9, %11, %3"
;         : "+v"(acc[0][0]), "+v"(acc[0][1]), "+v"(acc[1][0]), "+v"(acc[1][1]),
;           "=&v"(p0), "=&v"(p1), "=&v"(q0), "=&v"(q1), "=&v"(u0), "=&v"(u1), "=&v"(w0), "=&v"(w1)
	ds_read_b128 v[84:87], v76
	ds_read_b128 v[88:91], v76 offset:4096
	ds_read_b128 v[92:95], v80
	ds_read_b128 v[96:99], v80 offset:4096
	v_mfma_f32_32x32x16_bf16 v[48:63], v[100:103], v[108:111], v[48:63]
	s_mov_b32 s24, 0x400
	s_mov_b32 s25, 0
	s_add_u32 m0, s31, 0x18000
	v_lshl_add_u64 v[124:125], v[64:65], 0, s[24:25]
	global_load_lds_dwordx4 v[124:125], off
	v_mfma_f32_32x32x16_bf16 v[32:47], v[100:103], v[112:115], v[32:47]
	v_mfma_f32_32x32x16_bf16 v[16:31], v[104:107], v[108:111], v[16:31]
	s_add_u32 m0, s31, 0x1a000
	v_lshl_add_u64 v[126:127], v[66:67], 0, s[24:25]
	global_load_lds_dwordx4 v[126:127], off
	v_mfma_f32_32x32x16_bf16 v[0:15], v[104:107], v[112:115], v[0:15]
	ds_read_b128 v[100:103], v77
	ds_read_b128 v[104:107], v77 offset:4096
	ds_read_b128 v[108:111], v81
	ds_read_b128 v[112:115], v81 offset:4096
	s_waitcnt lgkmcnt(4)
	v_mfma_f32_32x32x16_bf16 v[48:63], v[84:87], v[92:95], v[48:63]
	s_add_u32 m0, s31, 0x1c000
	v_lshl_add_u64 v[124:125], v[68:69], 0, s[24:25]
	global_load_lds_dwordx4 v[124:125], off
	v_mfma_f32_32x32x16_bf16 v[32:47], v[84:87], v[96:99], v[32:47]
	v_mfma_f32_32x32x16_bf16 v[16:31], v[88:91], v[92:95], v[16:31]
	s_add_u32 m0, s31, 0x1e000
	v_lshl_add_u64 v[126:127], v[70:71], 0, s[24:25]
	global_load_lds_dwordx4 v[126:127], off
	v_mfma_f32_32x32x16_bf16 v[0:15], v[88:91], v[96:99], v[0:15]
	ds_read_b128 v[84:87], v78
	ds_read_b128 v[88:91], v78 offset:4096
	ds_read_b128 v[92:95], v82
	ds_read_b128 v[96:99], v82 offset:4096
	s_waitcnt lgkmcnt(4)
	v_mfma_f32_32x32x16_bf16 v[48:63], v[100:103], v[108:111], v[48:63]
	s_add_u32 m0, s31, 0x20000
	v_lshl_add_u64 v[124:125], v[72:73], 0, s[24:25]
	global_load_lds_dwordx4 v[124:125], off
	v_mfma_f32_32x32x16_bf16 v[32:47], v[100:103], v[112:115], v[32:47]
	v_mfma_f32_32x32x16_bf16 v[16:31], v[104:107], v[108:111], v[16:31]
	s_add_u32 m0, s31, 0x22000
	v_lshl_add_u64 v[126:127], v[74:75], 0, s[24:25]
	global_load_lds_dwordx4 v[126:127], off
	v_mfma_f32_32x32x16_bf16 v[0:15], v[104:107], v[112:115], v[0:15]
	ds_read_b128 v[100:103], v79
	ds_read_b128 v[104:107], v79 offset:4096
	ds_read_b128 v[108:111], v83
	ds_read_b128 v[112:115], v83 offset:4096
	s_waitcnt lgkmcnt(4)
	v_mfma_f32_32x32x16_bf16 v[48:63], v[84:87], v[92:95], v[48:63]
	v_mfma_f32_32x32x16_bf16 v[32:47], v[84:87], v[96:99], v[32:47]
	v_mfma_f32_32x32x16_bf16 v[16:31], v[88:91], v[92:95], v[16:31]
	v_mfma_f32_32x32x16_bf16 v[0:15], v[88:91], v[96:99], v[0:15]
	s_waitcnt vmcnt(6) lgkmcnt(0)
	s_barrier
	ds_read_b128 v[84:87], v76 offset:49152
	ds_read_b128 v[88:91], v76 offset:53248
	ds_read_b128 v[92:95], v80 offset:49152
	ds_read_b128 v[96:99], v80 offset:53248
	v_mfma_f32_32x32x16_bf16 v[48:63], v[100:103], v[108:111], v[48:63]
	s_mov_b32 s24, 0x480
	s_mov_b32 s25, 0
	s_mov_b32 m0, s31
	v_lshl_add_u64 v[124:125], v[64:65], 0, s[24:25]
	global_load_lds_dwordx4 v[124:125], off
	v_mfma_f32_32x32x16_bf16 v[32:47], v[100:103], v[112:115], v[32:47]
	v_mfma_f32_32x32x16_bf16 v[16:31], v[104:107], v[108:111], v[16:31]
	s_add_u32 m0, s31, 0x2000
	v_lshl_add_u64 v[126:127], v[66:67], 0, s[24:25]
	global_load_lds_dwordx4 v[126:127], off
	v_mfma_f32_32x32x16_bf16 v[0:15], v[104:107], v[112:115], v[0:15]
	ds_read_b128 v[100:103], v77 offset:49152
	ds_read_b128 v[104:107], v77 offset:53248
	ds_read_b128 v[108:111], v81 offset:49152
	ds_read_b128 v[112:115], v81 offset:53248
	s_waitcnt lgkmcnt(4)
	v_mfma_f32_32x32x16_bf16 v[48:63], v[84:87], v[92:95], v[48:63]
	s_add_u32 m0, s31, 0x4000
	v_lshl_add_u64 v[124:125], v[68:69], 0, s[24:25]
	global_load_lds_dwordx4 v[124:125], off
	v_mfma_f32_32x32x16_bf16 v[32:47], v[84:87], v[96:99], v[32:47]
	v_mfma_f32_32x32x16_bf16 v[16:31], v[88:91], v[92:95], v[16:31]
	s_add_u32 m0, s31, 0x6000
	v_lshl_add_u64 v[126:127], v[70:71], 0, s[24:25]
	global_load_lds_dwordx4 v[126:127], off
	v_mfma_f32_32x32x16_bf16 v[0:15], v[88:91], v[96:99], v[0:15]
	ds_read_b128 v[84:87], v78 offset:49152
	ds_read_b128 v[88:91], v78 offset:53248
	ds_read_b128 v[92:95], v82 offset:49152
	ds_read_b128 v[96:99], v82 offset:53248
	s_waitcnt lgkmcnt(4)
	v_mfma_f32_32x32x16_bf16 v[48:63], v[100:103], v[108:111], v[48:63]
	s_add_u32 m0, s31, 0x8000
	v_lshl_add_u64 v[124:125], v[72:73], 0, s[24:25]
	global_load_lds_dwordx4 v[124:125], off
	v_mfma_f32_32x32x16_bf16 v[32:47], v[100:103], v[112:115], v[32:47]
	v_mfma_f32_32x32x16_bf16 v[16:31], v[104:107], v[108:111], v[16:31]
	s_add_u32 m0, s31, 0xa000
	v_lshl_add_u64 v[126:127], v[74:75], 0, s[24:25]
	global_load_lds_dwordx4 v[126:127], off
	v_mfma_f32_32x32x16_bf16 v[0:15], v[104:107], v[112:115], v[0:15]
	ds_read_b128 v[100:103], v79 offset:49152
	ds_read_b128 v[104:107], v79 offset:53248
	ds_read_b128 v[108:111], v83 offset:49152
	ds_read_b128 v[112:115], v83 offset:53248
	s_waitcnt lgkmcnt(4)
	v_mfma_f32_32x32x16_bf16 v[48:63], v[84:87], v[92:95], v[48:63]
	v_mfma_f32_32x32x16_bf16 v[32:47], v[84:87], v[96:99], v[32:47]
	v_mfma_f32_32x32x16_bf16 v[16:31], v[88:91], v[92:95], v[16:31]
	v_mfma_f32_32x32x16_bf16 v[0:15], v[88:91], v[96:99], v[0:15]
	s_waitcnt vmcnt(6) lgkmcnt(0)
	s_barrier
;     ...
;   for (int kt = 0; kt < nk; ++kt) {
;     if (kt + 1 < nk) asm volatile("s_waitcnt vmcnt(6)" ::: "memory");
;     else asm volatile("s_waitcnt vmcnt(0)" ::: "memory");
;     __builtin_amdgcn_s_barrier();
;     asm volatile("" ::: "memory");
;     if (kt + 2 < nk) { const int st2 = (st >= 1) ? st - 1 : 2; GEMM_ISSUE(kt + 2, st2); }
;     const char* la = lds + st * STAGE_B;
;     const char* lb = la + 32768;
;     const unsigned sa_u = (unsigned)(size_t)la + arow_u, sb_u = (unsigned)(size_t)lb + brow_u;
;     const unsigned a0 = sa_u + co0, a1 = sa_u + co1, a2 = sa_u + co2, a3 = sa_u + co3;
;     const unsigned b0 = sb_u + co0, b1 = sb_u + co1, b2 = sb_u + co2, b3 = sb_u + co3;
;     {
;       bf16x8 p0, p1, q0, q1, u0, u1, w0, w1;
;       asm volatile(
;         "ds_read_b128 %4, %12\n\tds_read_b128 %5, %12 offset:4096\n\tds_read_b128 %6, %16\n\tds_read_b128 %7, %16 offset:4096\n\t"
;         "ds_read_b128 %8, %13\n\tds_read_b128 %9, %13 offset:4096\n\tds_read_b128 %10, %17\n\tds_read_b128 %11, %17 offset:4096\n\t"
;         "s_waitcnt lgkmcnt(4)\n\t"
;         "v_mfma_f32_32x32x16_bf16 %0, %4, %6, %0\n\tv_mfma_f32_32x32x16_bf16 %1, %4, %7, %1\n\tv_mfma_f32_32x32x16_bf16 %2, %5, %6, %2\n\tv_mfma_f32_32x32x16_bf16 %3, %5, %7, %3\n\t"
;         "ds_read_b128 %4, %14\n\tds_read_b128 %5, %14 offset:4096\n\tds_read_b128 %6, %18\n\tds_read_b128 %7, %18 offset:4096\n\t"
;         "s_waitcnt lgkmcnt(4)\n\t"
;         "v_mfma_f32_32x32x16_bf16 %0, %8, %10, %0\n\tv_mfma_f32_32x32x16_bf16 %1, %8, %11, %1\n\tv_mfma_f32_32x32x16_bf16 %2, %9, %10, %2\n\tv_mfma_f32_32x32x16_bf16 %3, %9, %11, %3\n\t"
;         "ds_read_b128 %8, %15\n\tds_read_b128 %9, %15 offset:4096\n\tds_read_b128 %10, %19\n\tds_read_b128 %11, %19 offset:4096\n\t"
;         "s_waitcnt lgkmcnt(4)\n\t"
;         "v_mfma_f32_32x32x16_bf16 %0, %4, %6, %0\n\tv_mfma_f32_32x32x16_bf16 %1, %4, %7, %1\n\tv_mfma_f32_32x32x16_bf16 %2, %5, %6, %2\n\tv_mfma_f32_32x32x16_bf16 %3, %5, %7, %3\n\t"
;         "s_waitcnt lgkmcnt(0)\n\t"
;         "v_mfma_f32_32x32x16_bf16 %0, %8, %10, %0\n\tv_mfma_f32_32x32x16_bf16 %1, %8, %11, %1\n\tv_mfma_f32_32x32x16_bf16 %2, %9, %10, %2\n\tv_mfma_f32_32x32x16_bf16 %3, %9, %11, %3"
;         : "+v"(acc[0][0]), "+v"(acc[0][1]), "+v"(acc[1][0]), "+v"(acc[1][1]),
;           "=&v"(p0), "=&v"(p1), "=&v"(q0), "=&v"(q1), "=&v"(u0), "=&v"(u1), "=&v"(w0), "=&v"(w1)
	ds_read_b128 v[84:87], v116
	ds_read_b128 v[88:91], v116 offset:4096
	ds_read_b128 v[92:95], v120
	ds_read_b128 v[96:99], v120 offset:4096
	v_mfma_f32_32x32x16_bf16 v[48:63], v[100:103], v[108:111], v[48:63]
	s_mov_b32 s24, 0x500
	s_mov_b32 s25, 0
	s_add_u32 m0, s31, 0xc000
	v_lshl_add_u64 v[124:125], v[64:65], 0, s[24:25]
	global_load_lds_dwordx4 v[124:125], off
	v_mfma_f32_32x32x16_bf16 v[32:47], v[100:103], v[112:115], v[32:47]
	v_mfma_f32_32x32x16_bf16 v[16:31], v[104:107], v[108:111], v[16:31]
	s_add_u32 m0, s31, 0xe000
	v_lshl_add_u64 v[126:127], v[66:67], 0, s[24:25]
	global_load_lds_dwordx4 v[126:127], off
	v_mfma_f32_32x32x16_bf16 v[0:15], v[104:107], v[112:115], v[0:15]
	ds_read_b128 v[100:103], v117
	ds_read_b128 v[104:107], v117 offset:4096
	ds_read_b128 v[108:111], v121
	ds_read_b128 v[112:115], v121 offset:4096
	s_waitcnt lgkmcnt(4)
	v_mfma_f32_32x32x16_bf16 v[48:63], v[84:87], v[92:95], v[48:63]
	s_add_u32 m0, s31, 0x10000
	v_lshl_add_u64 v[124:125], v[68:69], 0, s[24:25]
	global_load_lds_dwordx4 v[124:125], off
	v_mfma_f32_32x32x16_bf16 v[32:47], v[84:87], v[96:99], v[32:47]
	v_mfma_f32_32x32x16_bf16 v[16:31], v[88:91], v[92:95], v[16:31]
	s_add_u32 m0, s31, 0x12000
	v_lshl_add_u64 v[126:127], v[70:71], 0, s[24:25]
	global_load_lds_dwordx4 v[126:127], off
	v_mfma_f32_32x32x16_bf16 v[0:15], v[88:91], v[96:99], v[0:15]
	ds_read_b128 v[84:87], v118
	ds_read_b128 v[88:91], v118 offset:4096
	ds_read_b128 v[92:95], v122
	ds_read_b128 v[96:99], v122 offset:4096
	s_waitcnt lgkmcnt(4)
	v_mfma_f32_32x32x16_bf16 v[48:63], v[100:103], v[108:111], v[48:63]
	s_add_u32 m0, s31, 0x14000
	v_lshl_add_u64 v[124:125], v[72:73], 0, s[24:25]
	global_load_lds_dwordx4 v[124:125], off
	v_mfma_f32_32x32x16_bf16 v[32:47], v[100:103], v[112:115], v[32:47]
	v_mfma_f32_32x32x16_bf16 v[16:31], v[104:107], v[108:111], v[16:31]
	s_add_u32 m0, s31, 0x16000
	v_lshl_add_u64 v[126:127], v[74:75], 0, s[24:25]
	global_load_lds_dwordx4 v[126:127], off
	v_mfma_f32_32x32x16_bf16 v[0:15], v[104:107], v[112:115], v[0:15]
	ds_read_b128 v[100:103], v119
	ds_read_b128 v[104:107], v119 offset:4096
	ds_read_b128 v[108:111], v123
	ds_read_b128 v[112:115], v123 offset:4096
	s_waitcnt lgkmcnt(4)
	v_mfma_f32_32x32x16_bf16 v[48:63], v[84:87], v[92:95], v[48:63]
	v_mfma_f32_32x32x16_bf16 v[32:47], v[84:87], v[96:99], v[32:47]
	v_mfma_f32_32x32x16_bf16 v[16:31], v[88:91], v[92:95], v[16:31]
	v_mfma_f32_32x32x16_bf16 v[0:15], v[88:91], v[96:99], v[0:15]
	s_waitcnt vmcnt(6) lgkmcnt(0)
	s_barrier
	ds_read_b128 v[84:87], v76
	ds_read_b128 v[88:91], v76 offset:4096
	ds_read_b128 v[92:95], v80
	ds_read_b128 v[96:99], v80 offset:4096
	v_mfma_f32_32x32x16_bf16 v[48:63], v[100:103], v[108:111], v[48:63]
	s_mov_b32 s24, 0x580
	s_mov_b32 s25, 0
	s_add_u32 m0, s31, 0x18000
	v_lshl_add_u64 v[124:125], v[64:65], 0, s[24:25]
	global_load_lds_dwordx4 v[124:125], off
	v_mfma_f32_32x32x16_bf16 v[32:47], v[100:103], v[112:115], v[32:47]
	v_mfma_f32_32x32x16_bf16 v[16:31], v[104:107], v[108:111], v[16:31]
	s_add_u32 m0, s31, 0x1a000
	v_lshl_add_u64 v[126:127], v[66:67], 0, s[24:25]
	global_load_lds_dwordx4 v[126:127], off
	v_mfma_f32_32x32x16_bf16 v[0:15], v[104:107], v[112:115], v[0:15]
	ds_read_b128 v[100:103], v77
	ds_read_b128 v[104:107], v77 offset:4096
	ds_read_b128 v[108:111], v81
	ds_read_b128 v[112:115], v81 offset:4096
	s_waitcnt lgkmcnt(4)
	v_mfma_f32_32x32x16_bf16 v[48:63], v[84:87], v[92:95], v[48:63]
	s_add_u32 m0, s31, 0x1c000
	v_lshl_add_u64 v[124:125], v[68:69], 0, s[24:25]
	global_load_lds_dwordx4 v[124:125], off
	v_mfma_f32_32x32x16_bf16 v[32:47], v[84:87], v[96:99], v[32:47]
	v_mfma_f32_32x32x16_bf16 v[16:31], v[88:91], v[92:95], v[16:31]
	s_add_u32 m0, s31, 0x1e000
	v_lshl_add_u64 v[126:127], v[70:71], 0, s[24:25]
	global_load_lds_dwordx4 v[126:127], off
	v_mfma_f32_32x32x16_bf16 v[0:15], v[88:91], v[96:99], v[0:15]
	ds_read_b128 v[84:87], v78
	ds_read_b128 v[88:91], v78 offset:4096
	ds_read_b128 v[92:95], v82
	ds_read_b128 v[96:99], v82 offset:4096
	s_waitcnt lgkmcnt(4)
	v_mfma_f32_32x32x16_bf16 v[48:63], v[100:103], v[108:111], v[48:63]
	s_add_u32 m0, s31, 0x20000
	v_lshl_add_u64 v[124:125], v[72:73], 0, s[24:25]
	global_load_lds_dwordx4 v[124:125], off
	v_mfma_f32_32x32x16_bf16 v[32:47], v[100:103], v[112:115], v[32:47]
	v_mfma_f32_32x32x16_bf16 v[16:31], v[104:107], v[108:111], v[16:31]
	s_add_u32 m0, s31, 0x22000
	v_lshl_add_u64 v[126:127], v[74:75], 0, s[24:25]
	global_load_lds_dwordx4 v[126:127], off
	v_mfma_f32_32x32x16_bf16 v[0:15], v[104:107], v[112:115], v[0:15]
	ds_read_b128 v[100:103], v79
	ds_read_b128 v[104:107], v79 offset:4096
	ds_read_b128 v[108:111], v83
	ds_read_b128 v[112:115], v83 offset:4096
	s_waitcnt lgkmcnt(4)
	v_mfma_f32_32x32x16_bf16 v[48:63], v[84:87], v[92:95], v[48:63]
	v_mfma_f32_32x32x16_bf16 v[32:47], v[84:87], v[96:99], v[32:47]
	v_mfma_f32_32x32x16_bf16 v[16:31], v[88:91], v[92:95], v[16:31]
	v_mfma_f32_32x32x16_bf16 v[0:15], v[88:91], v[96:99], v[0:15]
	s_waitcnt vmcnt(6) lgkmcnt(0)
	s_barrier
;     ...
;   for (int kt = 0; kt < nk; ++kt) {
;     if (kt + 1 < nk) asm volatile("s_waitcnt vmcnt(6)" ::: "memory");
;     else asm volatile("s_waitcnt vmcnt(0)" ::: "memory");
;     __builtin_amdgcn_s_barrier();
;     asm volatile("" ::: "memory");
;     if (kt + 2 < nk) { const int st2 = (st >= 1) ? st - 1 : 2; GEMM_ISSUE(kt + 2, st2); }
;     const char* la = lds + st * STAGE_B;
;     const char* lb = la + 32768;
;     const unsigned sa_u = (unsigned)(size_t)la + arow_u, sb_u = (unsigned)(size_t)lb + brow_u;
;     const unsigned a0 = sa_u + co0, a1 = sa_u + co1, a2 = sa_u + co2, a3 = sa_u + co3;
;     const unsigned b0 = sb_u + co0, b1 = sb_u + co1, b2 = sb_u + co2, b3 = sb_u + co3;
;     {
;       bf16x8 p0, p1, q0, q1, u0, u1, w0, w1;
;       asm volatile(
;         "ds_read_b128 %4, %12\n\tds_read_b128 %5, %12 offset:4096\n\tds_read_b128 %6, %16\n\tds_read_b128 %7, %16 offset:4096\n\t"
;         "ds_read_b128 %8, %13\n\tds_read_b128 %9, %13 offset:4096\n\tds_read_b128 %10, %17\n\tds_read_b128 %11, %17 offset:4096\n\t"
;         "s_waitcnt lgkmcnt(4)\n\t"
;         "v_mfma_f32_32x32x16_bf16 %0, %4, %6, %0\n\tv_mfma_f32_32x32x16_bf16 %1, %4, %7, %1\n\tv_mfma_f32_32x32x16_bf16 %2, %5, %6, %2\n\tv_mfma_f32_32x32x16_bf16 %3, %5, %7, %3\n\t"
;         "ds_read_b128 %4, %14\n\tds_read_b128 %5, %14 offset:4096\n\tds_read_b128 %6, %18\n\tds_read_b128 %7, %18 offset:4096\n\t"
;         "s_waitcnt lgkmcnt(4)\n\t"
;         "v_mfma_f32_32x32x16_bf16 %0, %8, %10, %0\n\tv_mfma_f32_32x32x16_bf16 %1, %8, %11, %1\n\tv_mfma_f32_32x32x16_bf16 %2, %9, %10, %2\n\tv_mfma_f32_32x32x16_bf16 %3, %9, %11, %3\n\t"
;         "ds_read_b128 %8, %15\n\tds_read_b128 %9, %15 offset:4096\n\tds_read_b128 %10, %19\n\tds_read_b128 %11, %19 offset:4096\n\t"
;         "s_waitcnt lgkmcnt(4)\n\t"
;         "v_mfma_f32_32x32x16_bf16 %0, %4, %6, %0\n\tv_mfma_f32_32x32x16_bf16 %1, %4, %7, %1\n\tv_mfma_f32_32x32x16_bf16 %2, %5, %6, %2\n\tv_mfma_f32_32x32x16_bf16 %3, %5, %7, %3\n\t"
;         "s_waitcnt lgkmcnt(0)\n\t"
;         "v_mfma_f32_32x32x16_bf16 %0, %8, %10, %0\n\tv_mfma_f32_32x32x16_bf16 %1, %8, %11, %1\n\tv_mfma_f32_32x32x16_bf16 %2, %9, %10, %2\n\tv_mfma_f32_32x32x16_bf16 %3, %9, %11, %3"
;         : "+v"(acc[0][0]), "+v"(acc[0][1]), "+v"(acc[1][0]), "+v"(acc[1][1]),
;           "=&v"(p0), "=&v"(p1), "=&v"(q0), "=&v"(q1), "=&v"(u0), "=&v"(u1), "=&v"(w0), "=&v"(w1)
	ds_read_b128 v[84:87], v76 offset:49152
	ds_read_b128 v[88:91], v76 offset:53248
	ds_read_b128 v[92:95], v80 offset:49152
	ds_read_b128 v[96:99], v80 offset:53248
	v_mfma_f32_32x32x16_bf16 v[48:63], v[100:103], v[108:111], v[48:63]
	s_mov_b32 s24, 0x600
	s_mov_b32 s25, 0
	s_mov_b32 m0, s31
	v_lshl_add_u64 v[124:125], v[64:65], 0, s[24:25]
	global_load_lds_dwordx4 v[124:125], off
	v_mfma_f32_32x32x16_bf16 v[32:47], v[100:103], v[112:115], v[32:47]
	v_mfma_f32_32x32x16_bf16 v[16:31], v[104:107], v[108:111], v[16:31]
	s_add_u32 m0, s31, 0x2000
	v_lshl_add_u64 v[126:127], v[66:67], 0, s[24:25]
	global_load_lds_dwordx4 v[126:127], off
	v_mfma_f32_32x32x16_bf16 v[0:15], v[104:107], v[112:115], v[0:15]
	ds_read_b128 v[100:103], v77 offset:49152
	ds_read_b128 v[104:107], v77 offset:53248
	ds_read_b128 v[108:111], v81 offset:49152
	ds_read_b128 v[112:115], v81 offset:53248
	s_waitcnt lgkmcnt(4)
	v_mfma_f32_32x32x16_bf16 v[48:63], v[84:87], v[92:95], v[48:63]
	s_add_u32 m0, s31, 0x4000
	v_lshl_add_u64 v[124:125], v[68:69], 0, s[24:25]
	global_load_lds_dwordx4 v[124:125], off
	v_mfma_f32_32x32x16_bf16 v[32:47], v[84:87], v[96:99], v[32:47]
	v_mfma_f32_32x32x16_bf16 v[16:31], v[88:91], v[92:95], v[16:31]
	s_add_u32 m0, s31, 0x6000
	v_lshl_add_u64 v[126:127], v[70:71], 0, s[24:25]
	global_load_lds_dwordx4 v[126:127], off
	v_mfma_f32_32x32x16_bf16 v[0:15], v[88:91], v[96:99], v[0:15]
	ds_read_b128 v[84:87], v78 offset:49152
	ds_read_b128 v[88:91], v78 offset:53248
	ds_read_b128 v[92:95], v82 offset:49152
	ds_read_b128 v[96:99], v82 offset:53248
	s_waitcnt lgkmcnt(4)
	v_mfma_f32_32x32x16_bf16 v[48:63], v[100:103], v[108:111], v[48:63]
	s_add_u32 m0, s31, 0x8000
	v_lshl_add_u64 v[124:125], v[72:73], 0, s[24:25]
	global_load_lds_dwordx4 v[124:125], off
	v_mfma_f32_32x32x16_bf16 v[32:47], v[100:103], v[112:115], v[32:47]
	v_mfma_f32_32x32x16_bf16 v[16:31], v[104:107], v[108:111], v[16:31]
	s_add_u32 m0, s31, 0xa000
	v_lshl_add_u64 v[126:127], v[74:75], 0, s[24:25]
	global_load_lds_dwordx4 v[126:127], off
	v_mfma_f32_32x32x16_bf16 v[0:15], v[104:107], v[112:115], v[0:15]
	ds_read_b128 v[100:103], v79 offset:49152
	ds_read_b128 v[104:107], v79 offset:53248
	ds_read_b128 v[108:111], v83 offset:49152
	ds_read_b128 v[112:115], v83 offset:53248
	s_waitcnt lgkmcnt(4)
	v_mfma_f32_32x32x16_bf16 v[48:63], v[84:87], v[92:95], v[48:63]
	v_mfma_f32_32x32x16_bf16 v[32:47], v[84:87], v[96:99], v[32:47]
	v_mfma_f32_32x32x16_bf16 v[16:31], v[88:91], v[92:95], v[16:31]
	v_mfma_f32_32x32x16_bf16 v[0:15], v[88:91], v[96:99], v[0:15]
	s_waitcnt vmcnt(6) lgkmcnt(0)
	s_barrier
	ds_read_b128 v[84:87], v116
	ds_read_b128 v[88:91], v116 offset:4096
	ds_read_b128 v[92:95], v120
	ds_read_b128 v[96:99], v120 offset:4096
	v_mfma_f32_32x32x16_bf16 v[48:63], v[100:103], v[108:111], v[48:63]
	s_mov_b32 s24, 0x680
	s_mov_b32 s25, 0
	s_add_u32 m0, s31, 0xc000
	v_lshl_add_u64 v[124:125], v[64:65], 0, s[24:25]
	global_load_lds_dwordx4 v[124:125], off
	v_mfma_f32_32x32x16_bf16 v[32:47], v[100:103], v[112:115], v[32:47]
	v_mfma_f32_32x32x16_bf16 v[16:31], v[104:107], v[108:111], v[16:31]
	s_add_u32 m0, s31, 0xe000
	v_lshl_add_u64 v[126:127], v[66:67], 0, s[24:25]
	global_load_lds_dwordx4 v[126:127], off
	v_mfma_f32_32x32x16_bf16 v[0:15], v[104:107], v[112:115], v[0:15]
	ds_read_b128 v[100:103], v117
	ds_read_b128 v[104:107], v117 offset:4096
	ds_read_b128 v[108:111], v121
	ds_read_b128 v[112:115], v121 offset:4096
	s_waitcnt lgkmcnt(4)
	v_mfma_f32_32x32x16_bf16 v[48:63], v[84:87], v[92:95], v[48:63]
	s_add_u32 m0, s31, 0x10000
	v_lshl_add_u64 v[124:125], v[68:69], 0, s[24:25]
	global_load_lds_dwordx4 v[124:125], off
	v_mfma_f32_32x32x16_bf16 v[32:47], v[84:87], v[96:99], v[32:47]
	v_mfma_f32_32x32x16_bf16 v[16:31], v[88:91], v[92:95], v[16:31]
	s_add_u32 m0, s31, 0x12000
	v_lshl_add_u64 v[126:127], v[70:71], 0, s[24:25]
	global_load_lds_dwordx4 v[126:127], off
	v_mfma_f32_32x32x16_bf16 v[0:15], v[88:91], v[96:99], v[0:15]
	ds_read_b128 v[84:87], v118
	ds_read_b128 v[88:91], v118 offset:4096
	ds_read_b128 v[92:95], v122
	ds_read_b128 v[96:99], v122 offset:4096
	s_waitcnt lgkmcnt(4)
	v_mfma_f32_32x32x16_bf16 v[48:63], v[100:103], v[108:111], v[48:63]
	s_add_u32 m0, s31, 0x14000
	v_lshl_add_u64 v[124:125], v[72:73], 0, s[24:25]
	global_load_lds_dwordx4 v[124:125], off
	v_mfma_f32_32x32x16_bf16 v[32:47], v[100:103], v[112:115], v[32:47]
	v_mfma_f32_32x32x16_bf16 v[16:31], v[104:107], v[108:111], v[16:31]
	s_add_u32 m0, s31, 0x16000
	v_lshl_add_u64 v[126:127], v[74:75], 0, s[24:25]
	global_load_lds_dwordx4 v[126:127], off
	v_mfma_f32_32x32x16_bf16 v[0:15], v[104:107], v[112:115], v[0:15]
	ds_read_b128 v[100:103], v119
	ds_read_b128 v[104:107], v119 offset:4096
	ds_read_b128 v[108:111], v123
	ds_read_b128 v[112:115], v123 offset:4096
	s_waitcnt lgkmcnt(4)
	v_mfma_f32_32x32x16_bf16 v[48:63], v[84:87], v[92:95], v[48:63]
	v_mfma_f32_32x32x16_bf16 v[32:47], v[84:87], v[96:99], v[32:47]
	v_mfma_f32_32x32x16_bf16 v[16:31], v[88:91], v[92:95], v[16:31]
	v_mfma_f32_32x32x16_bf16 v[0:15], v[88:91], v[96:99], v[0:15]
	s_waitcnt vmcnt(6) lgkmcnt(0)
	s_barrier
;     ...
;   for (int kt = 0; kt < nk; ++kt) {
;     if (kt + 1 < nk) asm volatile("s_waitcnt vmcnt(6)" ::: "memory");
;     else asm volatile("s_waitcnt vmcnt(0)" ::: "memory");
;     __builtin_amdgcn_s_barrier();
;     asm volatile("" ::: "memory");
;     if (kt + 2 < nk) { const int st2 = (st >= 1) ? st - 1 : 2; GEMM_ISSUE(kt + 2, st2); }
;     const char* la = lds + st * STAGE_B;
;     const char* lb = la + 32768;
;     const unsigned sa_u = (unsigned)(size_t)la + arow_u, sb_u = (unsigned)(size_t)lb + brow_u;
;     const unsigned a0 = sa_u + co0, a1 = sa_u + co1, a2 = sa_u + co2, a3 = sa_u + co3;
;     const unsigned b0 = sb_u + co0, b1 = sb_u + co1, b2 = sb_u + co2, b3 = sb_u + co3;
;     {
;       bf16x8 p0, p1, q0, q1, u0, u1, w0, w1;
;       asm volatile(
;         "ds_read_b128 %4, %12\n\tds_read_b128 %5, %12 offset:4096\n\tds_read_b128 %6, %16\n\tds_read_b128 %7, %16 offset:4096\n\t"
;         "ds_read_b128 %8, %13\n\tds_read_b128 %9, %13 offset:4096\n\tds_read_b128 %10, %17\n\tds_read_b128 %11, %17 offset:4096\n\t"
;         "s_waitcnt lgkmcnt(4)\n\t"
;         "v_mfma_f32_32x32x16_bf16 %0, %4, %6, %0\n\tv_mfma_f32_32x32x16_bf16 %1, %4, %7, %1\n\tv_mfma_f32_32x32x16_bf16 %2, %5, %6, %2\n\tv_mfma_f32_32x32x16_bf16 %3, %5, %7, %3\n\t"
;         "ds_read_b128 %4, %14\n\tds_read_b128 %5, %14 offset:4096\n\tds_read_b128 %6, %18\n\tds_read_b128 %7, %18 offset:4096\n\t"
;         "s_waitcnt lgkmcnt(4)\n\t"
;         "v_mfma_f32_32x32x16_bf16 %0, %8, %10, %0\n\tv_mfma_f32_32x32x16_bf16 %1, %8, %11, %1\n\tv_mfma_f32_32x32x16_bf16 %2, %9, %10, %2\n\tv_mfma_f32_32x32x16_bf16 %3, %9, %11, %3\n\t"
;         "ds_read_b128 %8, %15\n\tds_read_b128 %9, %15 offset:4096\n\tds_read_b128 %10, %19\n\tds_read_b128 %11, %19 offset:4096\n\t"
;         "s_waitcnt lgkmcnt(4)\n\t"
;         "v_mfma_f32_32x32x16_bf16 %0, %4, %6, %0\n\tv_mfma_f32_32x32x16_bf16 %1, %4, %7, %1\n\tv_mfma_f32_32x32x16_bf16 %2, %5, %6, %2\n\tv_mfma_f32_32x32x16_bf16 %3, %5, %7, %3\n\t"
;         "s_waitcnt lgkmcnt(0)\n\t"
;         "v_mfma_f32_32x32x16_bf16 %0, %8, %10, %0\n\tv_mfma_f32_32x32x16_bf16 %1, %8, %11, %1\n\tv_mfma_f32_32x32x16_bf16 %2, %9, %10, %2\n\tv_mfma_f32_32x32x16_bf16 %3, %9, %11, %3"
;         : "+v"(acc[0][0]), "+v"(acc[0][1]), "+v"(acc[1][0]), "+v"(acc[1][1]),
;           "=&v"(p0), "=&v"(p1), "=&v"(q0), "=&v"(q1), "=&v"(u0), "=&v"(u1), "=&v"(w0), "=&v"(w1)
	ds_read_b128 v[84:87], v76
	ds_read_b128 v[88:91], v76 offset:4096
	ds_read_b128 v[92:95], v80
	ds_read_b128 v[96:99], v80 offset:4096
	v_mfma_f32_32x32x16_bf16 v[48:63], v[100:103], v[108:111], v[48:63]
	s_mov_b32 s24, 0x700
	s_mov_b32 s25, 0
	s_add_u32 m0, s31, 0x18000
	v_lshl_add_u64 v[124:125], v[64:65], 0, s[24:25]
	global_load_lds_dwordx4 v[124:125], off
	v_mfma_f32_32x32x16_bf16 v[32:47], v[100:103], v[112:115], v[32:47]
	v_mfma_f32_32x32x16_bf16 v[16:31], v[104:107], v[108:111], v[16:31]
	s_add_u32 m0, s31, 0x1a000
	v_lshl_add_u64 v[126:127], v[66:67], 0, s[24:25]
	global_load_lds_dwordx4 v[126:127], off
	v_mfma_f32_32x32x16_bf16 v[0:15], v[104:107], v[112:115], v[0:15]
	ds_read_b128 v[100:103], v77
	ds_read_b128 v[104:107], v77 offset:4096
	ds_read_b128 v[108:111], v81
	ds_read_b128 v[112:115], v81 offset:4096
	s_waitcnt lgkmcnt(4)
	v_mfma_f32_32x32x16_bf16 v[48:63], v[84:87], v[92:95], v[48:63]
	s_add_u32 m0, s31, 0x1c000
	v_lshl_add_u64 v[124:125], v[68:69], 0, s[24:25]
	global_load_lds_dwordx4 v[124:125], off
	v_mfma_f32_32x32x16_bf16 v[32:47], v[84:87], v[96:99], v[32:47]
	v_mfma_f32_32x32x16_bf16 v[16:31], v[88:91], v[92:95], v[16:31]
	s_add_u32 m0, s31, 0x1e000
	v_lshl_add_u64 v[126:127], v[70:71], 0, s[24:25]
	global_load_lds_dwordx4 v[126:127], off
	v_mfma_f32_32x32x16_bf16 v[0:15], v[88:91], v[96:99], v[0:15]
	ds_read_b128 v[84:87], v78
	ds_read_b128 v[88:91], v78 offset:4096
	ds_read_b128 v[92:95], v82
	ds_read_b128 v[96:99], v82 offset:4096
	s_waitcnt lgkmcnt(4)
	v_mfma_f32_32x32x16_bf16 v[48:63], v[100:103], v[108:111], v[48:63]
	s_add_u32 m0, s31, 0x20000
	v_lshl_add_u64 v[124:125], v[72:73], 0, s[24:25]
	global_load_lds_dwordx4 v[124:125], off
	v_mfma_f32_32x32x16_bf16 v[32:47], v[100:103], v[112:115], v[32:47]
	v_mfma_f32_32x32x16_bf16 v[16:31], v[104:107], v[108:111], v[16:31]
	s_add_u32 m0, s31, 0x22000
	v_lshl_add_u64 v[126:127], v[74:75], 0, s[24:25]
	global_load_lds_dwordx4 v[126:127], off
	v_mfma_f32_32x32x16_bf16 v[0:15], v[104:107], v[112:115], v[0:15]
	ds_read_b128 v[100:103], v79
	ds_read_b128 v[104:107], v79 offset:4096
	ds_read_b128 v[108:111], v83
	ds_read_b128 v[112:115], v83 offset:4096
	s_waitcnt lgkmcnt(4)
	v_mfma_f32_32x32x16_bf16 v[48:63], v[84:87], v[92:95], v[48:63]
	v_mfma_f32_32x32x16_bf16 v[32:47], v[84:87], v[96:99], v[32:47]
	v_mfma_f32_32x32x16_bf16 v[16:31], v[88:91], v[92:95], v[16:31]
	v_mfma_f32_32x32x16_bf16 v[0:15], v[88:91], v[96:99], v[0:15]
	s_waitcnt vmcnt(6) lgkmcnt(0)
	s_barrier
	ds_read_b128 v[84:87], v76 offset:49152
	ds_read_b128 v[88:91], v76 offset:53248
	ds_read_b128 v[92:95], v80 offset:49152
	ds_read_b128 v[96:99], v80 offset:53248
	v_mfma_f32_32x32x16_bf16 v[48:63], v[100:103], v[108:111], v[48:63]
	s_mov_b32 s24, 0x780
	s_mov_b32 s25, 0
	s_mov_b32 m0, s31
	v_lshl_add_u64 v[124:125], v[64:65], 0, s[24:25]
	global_load_lds_dwordx4 v[124:125], off
	v_mfma_f32_32x32x16_bf16 v[32:47], v[100:103], v[112:115], v[32:47]
	v_mfma_f32_32x32x16_bf16 v[16:31], v[104:107], v[108:111], v[16:31]
	s_add_u32 m0, s31, 0x2000
	v_lshl_add_u64 v[126:127], v[66:67], 0, s[24:25]
	global_load_lds_dwordx4 v[126:127], off
	v_mfma_f32_32x32x16_bf16 v[0:15], v[104:107], v[112:115], v[0:15]
	ds_read_b128 v[100:103], v77 offset:49152
	ds_read_b128 v[104:107], v77 offset:53248
	ds_read_b128 v[108:111], v81 offset:49152
	ds_read_b128 v[112:115], v81 offset:53248
	s_waitcnt lgkmcnt(4)
	v_mfma_f32_32x32x16_bf16 v[48:63], v[84:87], v[92:95], v[48:63]
	s_add_u32 m0, s31, 0x4000
	v_lshl_add_u64 v[124:125], v[68:69], 0, s[24:25]
	global_load_lds_dwordx4 v[124:125], off
	v_mfma_f32_32x32x16_bf16 v[32:47], v[84:87], v[96:99], v[32:47]
	v_mfma_f32_32x32x16_bf16 v[16:31], v[88:91], v[92:95], v[16:31]
	s_add_u32 m0, s31, 0x6000
	v_lshl_add_u64 v[126:127], v[70:71], 0, s[24:25]
	global_load_lds_dwordx4 v[126:127], off
	v_mfma_f32_32x32x16_bf16 v[0:15], v[88:91], v[96:99], v[0:15]
	ds_read_b128 v[84:87], v78 offset:49152
	ds_read_b128 v[88:91], v78 offset:53248
	ds_read_b128 v[92:95], v82 offset:49152
	ds_read_b128 v[96:99], v82 offset:53248
	s_waitcnt lgkmcnt(4)
	v_mfma_f32_32x32x16_bf16 v[48:63], v[100:103], v[108:111], v[48:63]
	s_add_u32 m0, s31, 0x8000
	v_lshl_add_u64 v[124:125], v[72:73], 0, s[24:25]
	global_load_lds_dwordx4 v[124:125], off
	v_mfma_f32_32x32x16_bf16 v[32:47], v[100:103], v[112:115], v[32:47]
	v_mfma_f32_32x32x16_bf16 v[16:31], v[104:107], v[108:111], v[16:31]
	s_add_u32 m0, s31, 0xa000
	v_lshl_add_u64 v[126:127], v[74:75], 0, s[24:25]
	global_load_lds_dwordx4 v[126:127], off
	v_mfma_f32_32x32x16_bf16 v[0:15], v[104:107], v[112:115], v[0:15]
	ds_read_b128 v[100:103], v79 offset:49152
	ds_read_b128 v[104:107], v79 offset:53248
	ds_read_b128 v[108:111], v83 offset:49152
	ds_read_b128 v[112:115], v83 offset:53248
	s_waitcnt lgkmcnt(4)
	v_mfma_f32_32x32x16_bf16 v[48:63], v[84:87], v[92:95], v[48:63]
	v_mfma_f32_32x32x16_bf16 v[32:47], v[84:87], v[96:99], v[32:47]
	v_mfma_f32_32x32x16_bf16 v[16:31], v[88:91], v[92:95], v[16:31]
	v_mfma_f32_32x32x16_bf16 v[0:15], v[88:91], v[96:99], v[0:15]
	s_waitcnt vmcnt(6) lgkmcnt(0)
	s_barrier
;     ...
;   for (int kt = 0; kt < nk; ++kt) {
;     if (kt + 1 < nk) asm volatile("s_waitcnt vmcnt(6)" ::: "memory");
;     else asm volatile("s_waitcnt vmcnt(0)" ::: "memory");
;     __builtin_amdgcn_s_barrier();
;     asm volatile("" ::: "memory");
;     if (kt + 2 < nk) { const int st2 = (st >= 1) ? st - 1 : 2; GEMM_ISSUE(kt + 2, st2); }
;     const char* la = lds + st * STAGE_B;
;     const char* lb = la + 32768;
;     const unsigned sa_u = (unsigned)(size_t)la + arow_u, sb_u = (unsigned)(size_t)lb + brow_u;
;     const unsigned a0 = sa_u + co0, a1 = sa_u + co1, a2 = sa_u + co2, a3 = sa_u + co3;
;     const unsigned b0 = sb_u + co0, b1 = sb_u + co1, b2 = sb_u + co2, b3 = sb_u + co3;
;     {
;       bf16x8 p0, p1, q0, q1, u0, u1, w0, w1;
;       asm volatile(
;         "ds_read_b128 %4, %12\n\tds_read_b128 %5, %12 offset:4096\n\tds_read_b128 %6, %16\n\tds_read_b128 %7, %16 offset:4096\n\t"
;         "ds_read_b128 %8, %13\n\tds_read_b128 %9, %13 offset:4096\n\tds_read_b128 %10, %17\n\tds_read_b128 %11, %17 offset:4096\n\t"
;         "s_waitcnt lgkmcnt(4)\n\t"
;         "v_mfma_f32_32x32x16_bf16 %0, %4, %6, %0\n\tv_mfma_f32_32x32x16_bf16 %1, %4, %7, %1\n\tv_mfma_f32_32x32x16_bf16 %2, %5, %6, %2\n\tv_mfma_f32_32x32x16_bf16 %3, %5, %7, %3\n\t"
;         "ds_read_b128 %4, %14\n\tds_read_b128 %5, %14 offset:4096\n\tds_read_b128 %6, %18\n\tds_read_b128 %7, %18 offset:4096\n\t"
;         "s_waitcnt lgkmcnt(4)\n\t"
;         "v_mfma_f32_32x32x16_bf16 %0, %8, %10, %0\n\tv_mfma_f32_32x32x16_bf16 %1, %8, %11, %1\n\tv_mfma_f32_32x32x16_bf16 %2, %9, %10, %2\n\tv_mfma_f32_32x32x16_bf16 %3, %9, %11, %3\n\t"
;         "ds_read_b128 %8, %15\n\tds_read_b128 %9, %15 offset:4096\n\tds_read_b128 %10, %19\n\tds_read_b128 %11, %19 offset:4096\n\t"
;         "s_waitcnt lgkmcnt(4)\n\t"
;         "v_mfma_f32_32x32x16_bf16 %0, %4, %6, %0\n\tv_mfma_f32_32x32x16_bf16 %1, %4, %7, %1\n\tv_mfma_f32_32x32x16_bf16 %2, %5, %6, %2\n\tv_mfma_f32_32x32x16_bf16 %3, %5, %7, %3\n\t"
;         "s_waitcnt lgkmcnt(0)\n\t"
;         "v_mfma_f32_32x32x16_bf16 %0, %8, %10, %0\n\tv_mfma_f32_32x32x16_bf16 %1, %8, %11, %1\n\tv_mfma_f32_32x32x16_bf16 %2, %9, %10, %2\n\tv_mfma_f32_32x32x16_bf16 %3, %9, %11, %3"
;         : "+v"(acc[0][0]), "+v"(acc[0][1]), "+v"(acc[1][0]), "+v"(acc[1][1]),
;           "=&v"(p0), "=&v"(p1), "=&v"(q0), "=&v"(q1), "=&v"(u0), "=&v"(u1), "=&v"(w0), "=&v"(w1)
	ds_read_b128 v[84:87], v116
	ds_read_b128 v[88:91], v116 offset:4096
	ds_read_b128 v[92:95], v120
	ds_read_b128 v[96:99], v120 offset:4096
	v_mfma_f32_32x32x16_bf16 v[48:63], v[100:103], v[108:111], v[48:63]
	s_add_u32 s24, s58, 0x0
	s_addc_u32 s25, s59, 0
	s_add_u32 m0, s31, 0xc000
	v_lshl_add_u64 v[124:125], v[64:65], 0, s[24:25]
	global_load_lds_dwordx4 v[124:125], off
	v_mfma_f32_32x32x16_bf16 v[32:47], v[100:103], v[112:115], v[32:47]
	v_mfma_f32_32x32x16_bf16 v[16:31], v[104:107], v[108:111], v[16:31]
	s_add_u32 m0, s31, 0xe000
	v_lshl_add_u64 v[126:127], v[66:67], 0, s[24:25]
	global_load_lds_dwordx4 v[126:127], off
	v_mfma_f32_32x32x16_bf16 v[0:15], v[104:107], v[112:115], v[0:15]
	ds_read_b128 v[100:103], v117
	ds_read_b128 v[104:107], v117 offset:4096
	ds_read_b128 v[108:111], v121
	ds_read_b128 v[112:115], v121 offset:4096
	s_waitcnt lgkmcnt(4)
	v_mfma_f32_32x32x16_bf16 v[48:63], v[84:87], v[92:95], v[48:63]
	s_add_u32 m0, s31, 0x10000
	v_lshl_add_u64 v[124:125], v[68:69], 0, s[24:25]
	global_load_lds_dwordx4 v[124:125], off
	v_mfma_f32_32x32x16_bf16 v[32:47], v[84:87], v[96:99], v[32:47]
	v_mfma_f32_32x32x16_bf16 v[16:31], v[88:91], v[92:95], v[16:31]
	s_add_u32 m0, s31, 0x12000
	v_lshl_add_u64 v[126:127], v[70:71], 0, s[24:25]
	global_load_lds_dwordx4 v[126:127], off
	v_mfma_f32_32x32x16_bf16 v[0:15], v[88:91], v[96:99], v[0:15]
	ds_read_b128 v[84:87], v118
	ds_read_b128 v[88:91], v118 offset:4096
	ds_read_b128 v[92:95], v122
	ds_read_b128 v[96:99], v122 offset:4096
	s_waitcnt lgkmcnt(4)
	v_mfma_f32_32x32x16_bf16 v[48:63], v[100:103], v[108:111], v[48:63]
	s_add_u32 s24, s60, 0x0
	s_addc_u32 s25, s61, 0
	s_add_u32 m0, s31, 0x14000
	v_lshl_add_u64 v[124:125], v[72:73], 0, s[24:25]
	global_load_lds_dwordx4 v[124:125], off
	v_mfma_f32_32x32x16_bf16 v[32:47], v[100:103], v[112:115], v[32:47]
	v_mfma_f32_32x32x16_bf16 v[16:31], v[104:107], v[108:111], v[16:31]
	s_add_u32 m0, s31, 0x16000
	v_lshl_add_u64 v[126:127], v[74:75], 0, s[24:25]
	global_load_lds_dwordx4 v[126:127], off
	v_mfma_f32_32x32x16_bf16 v[0:15], v[104:107], v[112:115], v[0:15]
	ds_read_b128 v[100:103], v119
	ds_read_b128 v[104:107], v119 offset:4096
	ds_read_b128 v[108:111], v123
	ds_read_b128 v[112:115], v123 offset:4096
	s_waitcnt lgkmcnt(4)
	v_mfma_f32_32x32x16_bf16 v[48:63], v[84:87], v[92:95], v[48:63]
	v_mfma_f32_32x32x16_bf16 v[32:47], v[84:87], v[96:99], v[32:47]
	v_mfma_f32_32x32x16_bf16 v[16:31], v[88:91], v[92:95], v[16:31]
	v_mfma_f32_32x32x16_bf16 v[0:15], v[88:91], v[96:99], v[0:15]
	s_waitcnt vmcnt(6) lgkmcnt(0)
	s_barrier
	ds_read_b128 v[84:87], v76
	ds_read_b128 v[88:91], v76 offset:4096
	ds_read_b128 v[92:95], v80
	ds_read_b128 v[96:99], v80 offset:4096
	v_mfma_f32_32x32x16_bf16 v[48:63], v[100:103], v[108:111], v[48:63]
	s_add_u32 s24, s58, 0x80
	s_addc_u32 s25, s59, 0
	s_add_u32 m0, s31, 0x18000
	v_lshl_add_u64 v[124:125], v[64:65], 0, s[24:25]
	global_load_lds_dwordx4 v[124:125], off
	v_mfma_f32_32x32x16_bf16 v[32:47], v[100:103], v[112:115], v[32:47]
	v_mfma_f32_32x32x16_bf16 v[16:31], v[104:107], v[108:111], v[16:31]
	s_add_u32 m0, s31, 0x1a000
	v_lshl_add_u64 v[126:127], v[66:67], 0, s[24:25]
	global_load_lds_dwordx4 v[126:127], off
	v_mfma_f32_32x32x16_bf16 v[0:15], v[104:107], v[112:115], v[0:15]
	ds_read_b128 v[100:103], v77
	ds_read_b128 v[104:107], v77 offset:4096
	ds_read_b128 v[108:111], v81
	ds_read_b128 v[112:115], v81 offset:4096
	s_waitcnt lgkmcnt(4)
	v_mfma_f32_32x32x16_bf16 v[48:63], v[84:87], v[92:95], v[48:63]
	s_add_u32 m0, s31, 0x1c000
	v_lshl_add_u64 v[124:125], v[68:69], 0, s[24:25]
	global_load_lds_dwordx4 v[124:125], off
	v_mfma_f32_32x32x16_bf16 v[32:47], v[84:87], v[96:99], v[32:47]
	v_mfma_f32_32x32x16_bf16 v[16:31], v[88:91], v[92:95], v[16:31]
	s_add_u32 m0, s31, 0x1e000
	v_lshl_add_u64 v[126:127], v[70:71], 0, s[24:25]
	global_load_lds_dwordx4 v[126:127], off
	v_mfma_f32_32x32x16_bf16 v[0:15], v[88:91], v[96:99], v[0:15]
	ds_read_b128 v[84:87], v78
	ds_read_b128 v[88:91], v78 offset:4096
	ds_read_b128 v[92:95], v82
	ds_read_b128 v[96:99], v82 offset:4096
	s_waitcnt lgkmcnt(4)
	v_mfma_f32_32x32x16_bf16 v[48:63], v[100:103], v[108:111], v[48:63]
	s_add_u32 s24, s60, 0x80
	s_addc_u32 s25, s61, 0
	s_add_u32 m0, s31, 0x20000
	v_lshl_add_u64 v[124:125], v[72:73], 0, s[24:25]
	global_load_lds_dwordx4 v[124:125], off
	v_mfma_f32_32x32x16_bf16 v[32:47], v[100:103], v[112:115], v[32:47]
	v_mfma_f32_32x32x16_bf16 v[16:31], v[104:107], v[108:111], v[16:31]
	s_add_u32 m0, s31, 0x22000
	v_lshl_add_u64 v[126:127], v[74:75], 0, s[24:25]
	global_load_lds_dwordx4 v[126:127], off
	v_mfma_f32_32x32x16_bf16 v[0:15], v[104:107], v[112:115], v[0:15]
	ds_read_b128 v[100:103], v79
	ds_read_b128 v[104:107], v79 offset:4096
	ds_read_b128 v[108:111], v83
	ds_read_b128 v[112:115], v83 offset:4096
	s_waitcnt lgkmcnt(4)
	v_mfma_f32_32x32x16_bf16 v[48:63], v[84:87], v[92:95], v[48:63]
	v_mfma_f32_32x32x16_bf16 v[32:47], v[84:87], v[96:99], v[32:47]
	v_mfma_f32_32x32x16_bf16 v[16:31], v[88:91], v[92:95], v[16:31]
	v_mfma_f32_32x32x16_bf16 v[0:15], v[88:91], v[96:99], v[0:15]
	s_waitcnt lgkmcnt(0)
	v_mfma_f32_32x32x16_bf16 v[48:63], v[100:103], v[108:111], v[48:63]
	v_mfma_f32_32x32x16_bf16 v[32:47], v[100:103], v[112:115], v[32:47]
	v_mfma_f32_32x32x16_bf16 v[16:31], v[104:107], v[108:111], v[16:31]
	v_mfma_f32_32x32x16_bf16 v[0:15], v[104:107], v[112:115], v[0:15]
	s_branch .Lx3_done
;     ...
;   for (int kt = 0; kt < nk; ++kt) {
;     if (kt + 1 < nk) asm volatile("s_waitcnt vmcnt(6)" ::: "memory");
;     else asm volatile("s_waitcnt vmcnt(0)" ::: "memory");
;     __builtin_amdgcn_s_barrier();
;     asm volatile("" ::: "memory");
;     if (kt + 2 < nk) { const int st2 = (st >= 1) ? st - 1 : 2; GEMM_ISSUE(kt + 2, st2); }
;     const char* la = lds + st * STAGE_B;
;     const char* lb = la + 32768;
;     const unsigned sa_u = (unsigned)(size_t)la + arow_u, sb_u = (unsigned)(size_t)lb + brow_u;
;     const unsigned a0 = sa_u + co0, a1 = sa_u + co1, a2 = sa_u + co2, a3 = sa_u + co3;
;     const unsigned b0 = sb_u + co0, b1 = sb_u + co1, b2 = sb_u + co2, b3 = sb_u + co3;
;     {
;       bf16x8 p0, p1, q0, q1, u0, u1, w0, w1;
;       asm volatile(
;         "ds_read_b128 %4, %12\n\tds_read_b128 %5, %12 offset:4096\n\tds_read_b128 %6, %16\n\tds_read_b128 %7, %16 offset:4096\n\t"
;         "ds_read_b128 %8, %13\n\tds_read_b128 %9, %13 offset:4096\n\tds_read_b128 %10, %17\n\tds_read_b128 %11, %17 offset:4096\n\t"
;         "s_waitcnt lgkmcnt(4)\n\t"
;         "v_mfma_f32_32x32x16_bf16 %0, %4, %6, %0\n\tv_mfma_f32_32x32x16_bf16 %1, %4, %7, %1\n\tv_mfma_f32_32x32x16_bf16 %2, %5, %6, %2\n\tv_mfma_f32_32x32x16_bf16 %3, %5, %7, %3\n\t"
;         "ds_read_b128 %4, %14\n\tds_read_b128 %5, %14 offset:4096\n\tds_read_b128 %6, %18\n\tds_read_b128 %7, %18 offset:4096\n\t"
;         "s_waitcnt lgkmcnt(4)\n\t"
;         "v_mfma_f32_32x32x16_bf16 %0, %8, %10, %0\n\tv_mfma_f32_32x32x16_bf16 %1, %8, %11, %1\n\tv_mfma_f32_32x32x16_bf16 %2, %9, %10, %2\n\tv_mfma_f32_32x32x16_bf16 %3, %9, %11, %3\n\t"
;         "ds_read_b128 %8, %15\n\tds_read_b128 %9, %15 offset:4096\n\tds_read_b128 %10, %19\n\tds_read_b128 %11, %19 offset:4096\n\t"
;         "s_waitcnt lgkmcnt(4)\n\t"
;         "v_mfma_f32_32x32x16_bf16 %0, %4, %6, %0\n\tv_mfma_f32_32x32x16_bf16 %1, %4, %7, %1\n\tv_mfma_f32_32x32x16_bf16 %2, %5, %6, %2\n\tv_mfma_f32_32x32x16_bf16 %3, %5, %7, %3\n\t"
;         "s_waitcnt lgkmcnt(0)\n\t"
;         "v_mfma_f32_32x32x16_bf16 %0, %8, %10, %0\n\tv_mfma_f32_32x32x16_bf16 %1, %8, %11, %1\n\tv_mfma_f32_32x32x16_bf16 %2, %9, %10, %2\n\tv_mfma_f32_32x32x16_bf16 %3, %9, %11, %3"
;         : "+v"(acc[0][0]), "+v"(acc[0][1]), "+v"(acc[1][0]), "+v"(acc[1][1]),
;           "=&v"(p0), "=&v"(p1), "=&v"(q0), "=&v"(q1), "=&v"(u0), "=&v"(u1), "=&v"(w0), "=&v"(w1)
.Lx3_v1:
	ds_read_b128 v[84:87], v76 offset:49152
	ds_read_b128 v[88:91], v76 offset:53248
	ds_read_b128 v[92:95], v80 offset:49152
	ds_read_b128 v[96:99], v80 offset:53248
	s_mov_b32 s24, 0x100
	s_mov_b32 s25, 0
	s_mov_b32 m0, s31
	v_lshl_add_u64 v[124:125], v[64:65], 0, s[24:25]
	global_load_lds_dwordx4 v[124:125], off
	s_add_u32 m0, s31, 0x2000
	v_lshl_add_u64 v[126:127], v[66:67], 0, s[24:25]
	global_load_lds_dwordx4 v[126:127], off
	ds_read_b128 v[100:103], v77 offset:49152
	ds_read_b128 v[104:107], v77 offset:53248
	ds_read_b128 v[108:111], v81 offset:49152
	ds_read_b128 v[112:115], v81 offset:53248
	s_waitcnt lgkmcnt(4)
	v_mfma_f32_32x32x16_bf16 v[48:63], v[84:87], v[92:95], v[48:63]
	s_add_u32 m0, s31, 0x4000
	v_lshl_add_u64 v[124:125], v[68:69], 0, s[24:25]
	global_load_lds_dwordx4 v[124:125], off
	v_mfma_f32_32x32x16_bf16 v[32:47], v[84:87], v[96:99], v[32:47]
	v_mfma_f32_32x32x16_bf16 v[16:31], v[88:91], v[92:95], v[16:31]
	s_add_u32 m0, s31, 0x6000
	v_lshl_add_u64 v[126:127], v[70:71], 0, s[24:25]
	global_load_lds_dwordx4 v[126:127], off
	v_mfma_f32_32x32x16_bf16 v[0:15], v[88:91], v[96:99], v[0:15]
	ds_read_b128 v[84:87], v78 offset:49152
	ds_read_b128 v[88:91], v78 offset:53248
	ds_read_b128 v[92:95], v82 offset:49152
	ds_read_b128 v[96:99], v82 offset:53248
	s_waitcnt lgkmcnt(4)
	v_mfma_f32_32x32x16_bf16 v[48:63], v[100:103], v[108:111], v[48:63]
	s_add_u32 m0, s31, 0x8000
	v_lshl_add_u64 v[124:125], v[72:73], 0, s[24:25]
	global_load_lds_dwordx4 v[124:125], off
	v_mfma_f32_32x32x16_bf16 v[32:47], v[100:103], v[112:115], v[32:47]
	v_mfma_f32_32x32x16_bf16 v[16:31], v[104:107], v[108:111], v[16:31]
	s_add_u32 m0, s31, 0xa000
	v_lshl_add_u64 v[126:127], v[74:75], 0, s[24:25]
	global_load_lds_dwordx4 v[126:127], off
	v_mfma_f32_32x32x16_bf16 v[0:15], v[104:107], v[112:115], v[0:15]
	ds_read_b128 v[100:103], v79 offset:49152
	ds_read_b128 v[104:107], v79 offset:53248
	ds_read_b128 v[108:111], v83 offset:49152
	ds_read_b128 v[112:115], v83 offset:53248
	s_waitcnt lgkmcnt(4)
	v_mfma_f32_32x32x16_bf16 v[48:63], v[84:87], v[92:95], v[48:63]
	v_mfma_f32_32x32x16_bf16 v[32:47], v[84:87], v[96:99], v[32:47]
	v_mfma_f32_32x32x16_bf16 v[16:31], v[88:91], v[92:95], v[16:31]
	v_mfma_f32_32x32x16_bf16 v[0:15], v[88:91], v[96:99], v[0:15]
	s_waitcnt vmcnt(6) lgkmcnt(0)
	s_barrier
	ds_read_b128 v[84:87], v116
	ds_read_b128 v[88:91], v116 offset:4096
	ds_read_b128 v[92:95], v120
	ds_read_b128 v[96:99], v120 offset:4096
	v_mfma_f32_32x32x16_bf16 v[48:63], v[100:103], v[108:111], v[48:63]
	s_mov_b32 s24, 0x180
	s_mov_b32 s25, 0
	s_add_u32 m0, s31, 0xc000
	v_lshl_add_u64 v[124:125], v[64:65], 0, s[24:25]
	global_load_lds_dwordx4 v[124:125], off
	v_mfma_f32_32x32x16_bf16 v[32:47], v[100:103], v[112:115], v[32:47]
	v_mfma_f32_32x32x16_bf16 v[16:31], v[104:107], v[108:111], v[16:31]
	s_add_u32 m0, s31, 0xe000
	v_lshl_add_u64 v[126:127], v[66:67], 0, s[24:25]
	global_load_lds_dwordx4 v[126:127], off
	v_mfma_f32_32x32x16_bf16 v[0:15], v[104:107], v[112:115], v[0:15]
	ds_read_b128 v[100:103], v117
	ds_read_b128 v[104:107], v117 offset:4096
	ds_read_b128 v[108:111], v121
	ds_read_b128 v[112:115], v121 offset:4096
	s_waitcnt lgkmcnt(4)
	v_mfma_f32_32x32x16_bf16 v[48:63], v[84:87], v[92:95], v[48:63]
	s_add_u32 m0, s31, 0x10000
	v_lshl_add_u64 v[124:125], v[68:69], 0, s[24:25]
	global_load_lds_dwordx4 v[124:125], off
	v_mfma_f32_32x32x16_bf16 v[32:47], v[84:87], v[96:99], v[32:47]
	v_mfma_f32_32x32x16_bf16 v[16:31], v[88:91], v[92:95], v[16:31]
	s_add_u32 m0, s31, 0x12000
	v_lshl_add_u64 v[126:127], v[70:71], 0, s[24:25]
	global_load_lds_dwordx4 v[126:127], off
	v_mfma_f32_32x32x16_bf16 v[0:15], v[88:91], v[96:99], v[0:15]
	ds_read_b128 v[84:87], v118
	ds_read_b128 v[88:91], v118 offset:4096
	ds_read_b128 v[92:95], v122
	ds_read_b128 v[96:99], v122 offset:4096
	s_waitcnt lgkmcnt(4)
	v_mfma_f32_32x32x16_bf16 v[48:63], v[100:103], v[108:111], v[48:63]
	s_add_u32 m0, s31, 0x14000
	v_lshl_add_u64 v[124:125], v[72:73], 0, s[24:25]
	global_load_lds_dwordx4 v[124:125], off
	v_mfma_f32_32x32x16_bf16 v[32:47], v[100:103], v[112:115], v[32:47]
	v_mfma_f32_32x32x16_bf16 v[16:31], v[104:107], v[108:111], v[16:31]
	s_add_u32 m0, s31, 0x16000
	v_lshl_add_u64 v[126:127], v[74:75], 0, s[24:25]
	global_load_lds_dwordx4 v[126:127], off
	v_mfma_f32_32x32x16_bf16 v[0:15], v[104:107], v[112:115], v[0:15]
	ds_read_b128 v[100:103], v119
	ds_read_b128 v[104:107], v119 offset:4096
	ds_read_b128 v[108:111], v123
	ds_read_b128 v[112:115], v123 offset:4096
	s_waitcnt lgkmcnt(4)
	v_mfma_f32_32x32x16_bf16 v[48:63], v[84:87], v[92:95], v[48:63]
	v_mfma_f32_32x32x16_bf16 v[32:47], v[84:87], v[96:99], v[32:47]
	v_mfma_f32_32x32x16_bf16 v[16:31], v[88:91], v[92:95], v[16:31]
	v_mfma_f32_32x32x16_bf16 v[0:15], v[88:91], v[96:99], v[0:15]
	s_waitcnt vmcnt(6) lgkmcnt(0)
	s_barrier
;     ...
;   for (int kt = 0; kt < nk; ++kt) {
;     if (kt + 1 < nk) asm volatile("s_waitcnt vmcnt(6)" ::: "memory");
;     else asm volatile("s_waitcnt vmcnt(0)" ::: "memory");
;     __builtin_amdgcn_s_barrier();
;     asm volatile("" ::: "memory");
;     if (kt + 2 < nk) { const int st2 = (st >= 1) ? st - 1 : 2; GEMM_ISSUE(kt + 2, st2); }
;     const char* la = lds + st * STAGE_B;
;     const char* lb = la + 32768;
;     const unsigned sa_u = (unsigned)(size_t)la + arow_u, sb_u = (unsigned)(size_t)lb + brow_u;
;     const unsigned a0 = sa_u + co0, a1 = sa_u + co1, a2 = sa_u + co2, a3 = sa_u + co3;
;     const unsigned b0 = sb_u + co0, b1 = sb_u + co1, b2 = sb_u + co2, b3 = sb_u + co3;
;     {
;       bf16x8 p0, p1, q0, q1, u0, u1, w0, w1;
;       asm volatile(
;         "ds_read_b128 %4, %12\n\tds_read_b128 %5, %12 offset:4096\n\tds_read_b128 %6, %16\n\tds_read_b128 %7, %16 offset:4096\n\t"
;         "ds_read_b128 %8, %13\n\tds_read_b128 %9, %13 offset:4096\n\tds_read_b128 %10, %17\n\tds_read_b128 %11, %17 offset:4096\n\t"
;         "s_waitcnt lgkmcnt(4)\n\t"
;         "v_mfma_f32_32x32x16_bf16 %0, %4, %6, %0\n\tv_mfma_f32_32x32x16_bf16 %1, %4, %7, %1\n\tv_mfma_f32_32x32x16_bf16 %2, %5, %6, %2\n\tv_mfma_f32_32x32x16_bf16 %3, %5, %7, %3\n\t"
;         "ds_read_b128 %4, %14\n\tds_read_b128 %5, %14 offset:4096\n\tds_read_b128 %6, %18\n\tds_read_b128 %7, %18 offset:4096\n\t"
;         "s_waitcnt lgkmcnt(4)\n\t"
;         "v_mfma_f32_32x32x16_bf16 %0, %8, %10, %0\n\tv_mfma_f32_32x32x16_bf16 %1, %8, %11, %1\n\tv_mfma_f32_32x32x16_bf16 %2, %9, %10, %2\n\tv_mfma_f32_32x32x16_bf16 %3, %9, %11, %3\n\t"
;         "ds_read_b128 %8, %15\n\tds_read_b128 %9, %15 offset:4096\n\tds_read_b128 %10, %19\n\tds_read_b128 %11, %19 offset:4096\n\t"
;         "s_waitcnt lgkmcnt(4)\n\t"
;         "v_mfma_f32_32x32x16_bf16 %0, %4, %6, %0\n\tv_mfma_f32_32x32x16_bf16 %1, %4, %7, %1\n\tv_mfma_f32_32x32x16_bf16 %2, %5, %6, %2\n\tv_mfma_f32_32x32x16_bf16 %3, %5, %7, %3\n\t"
;         "s_waitcnt lgkmcnt(0)\n\t"
;         "v_mfma_f32_32x32x16_bf16 %0, %8, %10, %0\n\tv_mfma_f32_32x32x16_bf16 %1, %8, %11, %1\n\tv_mfma_f32_32x32x16_bf16 %2, %9, %10, %2\n\tv_mfma_f32_32x32x16_bf16 %3, %9, %11, %3"
;         : "+v"(acc[0][0]), "+v"(acc[0][1]), "+v"(acc[1][0]), "+v"(acc[1][1]),
;           "=&v"(p0), "=&v"(p1), "=&v"(q0), "=&v"(q1), "=&v"(u0), "=&v"(u1), "=&v"(w0), "=&v"(w1)
	ds_read_b128 v[84:87], v76
	ds_read_b128 v[88:91], v76 offset:4096
	ds_read_b128 v[92:95], v80
	ds_read_b128 v[96:99], v80 offset:4096
	v_mfma_f32_32x32x16_bf16 v[48:63], v[100:103], v[108:111], v[48:63]
	s_mov_b32 s24, 0x200
	s_mov_b32 s25, 0
	s_add_u32 m0, s31, 0x18000
	v_lshl_add_u64 v[124:125], v[64:65], 0, s[24:25]
	global_load_lds_dwordx4 v[124:125], off
	v_mfma_f32_32x32x16_bf16 v[32:47], v[100:103], v[112:115], v[32:47]
	v_mfma_f32_32x32x16_bf16 v[16:31], v[104:107], v[108:111], v[16:31]
	s_add_u32 m0, s31, 0x1a000
	v_lshl_add_u64 v[126:127], v[66:67], 0, s[24:25]
	global_load_lds_dwordx4 v[126:127], off
	v_mfma_f32_32x32x16_bf16 v[0:15], v[104:107], v[112:115], v[0:15]
	ds_read_b128 v[100:103], v77
	ds_read_b128 v[104:107], v77 offset:4096
	ds_read_b128 v[108:111], v81
	ds_read_b128 v[112:115], v81 offset:4096
	s_waitcnt lgkmcnt(4)
	v_mfma_f32_32x32x16_bf16 v[48:63], v[84:87], v[92:95], v[48:63]
	s_add_u32 m0, s31, 0x1c000
	v_lshl_add_u64 v[124:125], v[68:69], 0, s[24:25]
	global_load_lds_dwordx4 v[124:125], off
	v_mfma_f32_32x32x16_bf16 v[32:47], v[84:87], v[96:99], v[32:47]
	v_mfma_f32_32x32x16_bf16 v[16:31], v[88:91], v[92:95], v[16:31]
	s_add_u32 m0, s31, 0x1e000
	v_lshl_add_u64 v[126:127], v[70:71], 0, s[24:25]
	global_load_lds_dwordx4 v[126:127], off
	v_mfma_f32_32x32x16_bf16 v[0:15], v[88:91], v[96:99], v[0:15]
	ds_read_b128 v[84:87], v78
	ds_read_b128 v[88:91], v78 offset:4096
	ds_read_b128 v[92:95], v82
	ds_read_b128 v[96:99], v82 offset:4096
	s_waitcnt lgkmcnt(4)
	v_mfma_f32_32x32x16_bf16 v[48:63], v[100:103], v[108:111], v[48:63]
	s_add_u32 m0, s31, 0x20000
	v_lshl_add_u64 v[124:125], v[72:73], 0, s[24:25]
	global_load_lds_dwordx4 v[124:125], off
	v_mfma_f32_32x32x16_bf16 v[32:47], v[100:103], v[112:115], v[32:47]
	v_mfma_f32_32x32x16_bf16 v[16:31], v[104:107], v[108:111], v[16:31]
	s_add_u32 m0, s31, 0x22000
	v_lshl_add_u64 v[126:127], v[74:75], 0, s[24:25]
	global_load_lds_dwordx4 v[126:127], off
	v_mfma_f32_32x32x16_bf16 v[0:15], v[104:107], v[112:115], v[0:15]
	ds_read_b128 v[100:103], v79
	ds_read_b128 v[104:107], v79 offset:4096
	ds_read_b128 v[108:111], v83
	ds_read_b128 v[112:115], v83 offset:4096
	s_waitcnt lgkmcnt(4)
	v_mfma_f32_32x32x16_bf16 v[48:63], v[84:87], v[92:95], v[48:63]
	v_mfma_f32_32x32x16_bf16 v[32:47], v[84:87], v[96:99], v[32:47]
	v_mfma_f32_32x32x16_bf16 v[16:31], v[88:91], v[92:95], v[16:31]
	v_mfma_f32_32x32x16_bf16 v[0:15], v[88:91], v[96:99], v[0:15]
	s_waitcnt vmcnt(6) lgkmcnt(0)
	s_barrier
	ds_read_b128 v[84:87], v76 offset:49152
	ds_read_b128 v[88:91], v76 offset:53248
	ds_read_b128 v[92:95], v80 offset:49152
	ds_read_b128 v[96:99], v80 offset:53248
	v_mfma_f32_32x32x16_bf16 v[48:63], v[100:103], v[108:111], v[48:63]
	s_mov_b32 s24, 0x280
	s_mov_b32 s25, 0
	s_mov_b32 m0, s31
	v_lshl_add_u64 v[124:125], v[64:65], 0, s[24:25]
	global_load_lds_dwordx4 v[124:125], off
	v_mfma_f32_32x32x16_bf16 v[32:47], v[100:103], v[112:115], v[32:47]
	v_mfma_f32_32x32x16_bf16 v[16:31], v[104:107], v[108:111], v[16:31]
	s_add_u32 m0, s31, 0x2000
	v_lshl_add_u64 v[126:127], v[66:67], 0, s[24:25]
	global_load_lds_dwordx4 v[126:127], off
	v_mfma_f32_32x32x16_bf16 v[0:15], v[104:107], v[112:115], v[0:15]
	ds_read_b128 v[100:103], v77 offset:49152
	ds_read_b128 v[104:107], v77 offset:53248
	ds_read_b128 v[108:111], v81 offset:49152
	ds_read_b128 v[112:115], v81 offset:53248
	s_waitcnt lgkmcnt(4)
	v_mfma_f32_32x32x16_bf16 v[48:63], v[84:87], v[92:95], v[48:63]
	s_add_u32 m0, s31, 0x4000
	v_lshl_add_u64 v[124:125], v[68:69], 0, s[24:25]
	global_load_lds_dwordx4 v[124:125], off
	v_mfma_f32_32x32x16_bf16 v[32:47], v[84:87], v[96:99], v[32:47]
	v_mfma_f32_32x32x16_bf16 v[16:31], v[88:91], v[92:95], v[16:31]
	s_add_u32 m0, s31, 0x6000
	v_lshl_add_u64 v[126:127], v[70:71], 0, s[24:25]
	global_load_lds_dwordx4 v[126:127], off
	v_mfma_f32_32x32x16_bf16 v[0:15], v[88:91], v[96:99], v[0:15]
	ds_read_b128 v[84:87], v78 offset:49152
	ds_read_b128 v[88:91], v78 offset:53248
	ds_read_b128 v[92:95], v82 offset:49152
	ds_read_b128 v[96:99], v82 offset:53248
	s_waitcnt lgkmcnt(4)
	v_mfma_f32_32x32x16_bf16 v[48:63], v[100:103], v[108:111], v[48:63]
	s_add_u32 m0, s31, 0x8000
	v_lshl_add_u64 v[124:125], v[72:73], 0, s[24:25]
	global_load_lds_dwordx4 v[124:125], off
	v_mfma_f32_32x32x16_bf16 v[32:47], v[100:103], v[112:115], v[32:47]
	v_mfma_f32_32x32x16_bf16 v[16:31], v[104:107], v[108:111], v[16:31]
	s_add_u32 m0, s31, 0xa000
	v_lshl_add_u64 v[126:127], v[74:75], 0, s[24:25]
	global_load_lds_dwordx4 v[126:127], off
	v_mfma_f32_32x32x16_bf16 v[0:15], v[104:107], v[112:115], v[0:15]
	ds_read_b128 v[100:103], v79 offset:49152
	ds_read_b128 v[104:107], v79 offset:53248
	ds_read_b128 v[108:111], v83 offset:49152
	ds_read_b128 v[112:115], v83 offset:53248
	s_waitcnt lgkmcnt(4)
	v_mfma_f32_32x32x16_bf16 v[48:63], v[84:87], v[92:95], v[48:63]
	v_mfma_f32_32x32x16_bf16 v[32:47], v[84:87], v[96:99], v[32:47]
	v_mfma_f32_32x32x16_bf16 v[16:31], v[88:91], v[92:95], v[16:31]
	v_mfma_f32_32x32x16_bf16 v[0:15], v[88:91], v[96:99], v[0:15]
	s_waitcnt vmcnt(6) lgkmcnt(0)
	s_barrier
;     ...
;   for (int kt = 0; kt < nk; ++kt) {
;     if (kt + 1 < nk) asm volatile("s_waitcnt vmcnt(6)" ::: "memory");
;     else asm volatile("s_waitcnt vmcnt(0)" ::: "memory");
;     __builtin_amdgcn_s_barrier();
;     asm volatile("" ::: "memory");
;     if (kt + 2 < nk) { const int st2 = (st >= 1) ? st - 1 : 2; GEMM_ISSUE(kt + 2, st2); }
;     const char* la = lds + st * STAGE_B;
;     const char* lb = la + 32768;
;     const unsigned sa_u = (unsigned)(size_t)la + arow_u, sb_u = (unsigned)(size_t)lb + brow_u;
;     const unsigned a0 = sa_u + co0, a1 = sa_u + co1, a2 = sa_u + co2, a3 = sa_u + co3;
;     const unsigned b0 = sb_u + co0, b1 = sb_u + co1, b2 = sb_u + co2, b3 = sb_u + co3;
;     {
;       bf16x8 p0, p1, q0, q1, u0, u1, w0, w1;
;       asm volatile(
;         "ds_read_b128 %4, %12\n\tds_read_b128 %5, %12 offset:4096\n\tds_read_b128 %6, %16\n\tds_read_b128 %7, %16 offset:4096\n\t"
;         "ds_read_b128 %8, %13\n\tds_read_b128 %9, %13 offset:4096\n\tds_read_b128 %10, %17\n\tds_read_b128 %11, %17 offset:4096\n\t"
;         "s_waitcnt lgkmcnt(4)\n\t"
;         "v_mfma_f32_32x32x16_bf16 %0, %4, %6, %0\n\tv_mfma_f32_32x32x16_bf16 %1, %4, %7, %1\n\tv_mfma_f32_32x32x16_bf16 %2, %5, %6, %2\n\tv_mfma_f32_32x32x16_bf16 %3, %5, %7, %3\n\t"
;         "ds_read_b128 %4, %14\n\tds_read_b128 %5, %14 offset:4096\n\tds_read_b128 %6, %18\n\tds_read_b128 %7, %18 offset:4096\n\t"
;         "s_waitcnt lgkmcnt(4)\n\t"
;         "v_mfma_f32_32x32x16_bf16 %0, %8, %10, %0\n\tv_mfma_f32_32x32x16_bf16 %1, %8, %11, %1\n\tv_mfma_f32_32x32x16_bf16 %2, %9, %10, %2\n\tv_mfma_f32_32x32x16_bf16 %3, %9, %11, %3\n\t"
;         "ds_read_b128 %8, %15\n\tds_read_b128 %9, %15 offset:4096\n\tds_read_b128 %10, %19\n\tds_read_b128 %11, %19 offset:4096\n\t"
;         "s_waitcnt lgkmcnt(4)\n\t"
;         "v_mfma_f32_32x32x16_bf16 %0, %4, %6, %0\n\tv_mfma_f32_32x32x16_bf16 %1, %4, %7, %1\n\tv_mfma_f32_32x32x16_bf16 %2, %5, %6, %2\n\tv_mfma_f32_32x32x16_bf16 %3, %5, %7, %3\n\t"
;         "s_waitcnt lgkmcnt(0)\n\t"
;         "v_mfma_f32_32x32x16_bf16 %0, %8, %10, %0\n\tv_mfma_f32_32x32x16_bf16 %1, %8, %11, %1\n\tv_mfma_f32_32x32x16_bf16 %2, %9, %10, %2\n\tv_mfma_f32_32x32x16_bf16 %3, %9, %11, %3"
;         : "+v"(acc[0][0]), "+v"(acc[0][1]), "+v"(acc[1][0]), "+v"(acc[1][1]),
;           "=&v"(p0), "=&v"(p1), "=&v"(q0), "=&v"(q1), "=&v"(u0), "=&v"(u1), "=&v"(w0), "=&v"(w1)
	ds_read_b128 v[84:87], v116
	ds_read_b128 v[88:91], v116 offset:4096
	ds_read_b128 v[92:95], v120
	ds_read_b128 v[96:99], v120 offset:4096
	v_mfma_f32_32x32x16_bf16 v[48:63], v[100:103], v[108:111], v[48:63]
	s_mov_b32 s24, 0x300
	s_mov_b32 s25, 0
	s_add_u32 m0, s31, 0xc000
	v_lshl_add_u64 v[124:125], v[64:65], 0, s[24:25]
	global_load_lds_dwordx4 v[124:125], off
	v_mfma_f32_32x32x16_bf16 v[32:47], v[100:103], v[112:115], v[32:47]
	v_mfma_f32_32x32x16_bf16 v[16:31], v[104:107], v[108:111], v[16:31]
	s_add_u32 m0, s31, 0xe000
	v_lshl_add_u64 v[126:127], v[66:67], 0, s[24:25]
	global_load_lds_dwordx4 v[126:127], off
	v_mfma_f32_32x32x16_bf16 v[0:15], v[104:107], v[112:115], v[0:15]
	ds_read_b128 v[100:103], v117
	ds_read_b128 v[104:107], v117 offset:4096
	ds_read_b128 v[108:111], v121
	ds_read_b128 v[112:115], v121 offset:4096
	s_waitcnt lgkmcnt(4)
	v_mfma_f32_32x32x16_bf16 v[48:63], v[84:87], v[92:95], v[48:63]
	s_add_u32 m0, s31, 0x10000
	v_lshl_add_u64 v[124:125], v[68:69], 0, s[24:25]
	global_load_lds_dwordx4 v[124:125], off
	v_mfma_f32_32x32x16_bf16 v[32:47], v[84:87], v[96:99], v[32:47]
	v_mfma_f32_32x32x16_bf16 v[16:31], v[88:91], v[92:95], v[16:31]
	s_add_u32 m0, s31, 0x12000
	v_lshl_add_u64 v[126:127], v[70:71], 0, s[24:25]
	global_load_lds_dwordx4 v[126:127], off
	v_mfma_f32_32x32x16_bf16 v[0:15], v[88:91], v[96:99], v[0:15]
	ds_read_b128 v[84:87], v118
	ds_read_b128 v[88:91], v118 offset:4096
	ds_read_b128 v[92:95], v122
	ds_read_b128 v[96:99], v122 offset:4096
	s_waitcnt lgkmcnt(4)
	v_mfma_f32_32x32x16_bf16 v[48:63], v[100:103], v[108:111], v[48:63]
	s_add_u32 m0, s31, 0x14000
	v_lshl_add_u64 v[124:125], v[72:73], 0, s[24:25]
	global_load_lds_dwordx4 v[124:125], off
	v_mfma_f32_32x32x16_bf16 v[32:47], v[100:103], v[112:115], v[32:47]
	v_mfma_f32_32x32x16_bf16 v[16:31], v[104:107], v[108:111], v[16:31]
	s_add_u32 m0, s31, 0x16000
	v_lshl_add_u64 v[126:127], v[74:75], 0, s[24:25]
	global_load_lds_dwordx4 v[126:127], off
	v_mfma_f32_32x32x16_bf16 v[0:15], v[104:107], v[112:115], v[0:15]
	ds_read_b128 v[100:103], v119
	ds_read_b128 v[104:107], v119 offset:4096
	ds_read_b128 v[108:111], v123
	ds_read_b128 v[112:115], v123 offset:4096
	s_waitcnt lgkmcnt(4)
	v_mfma_f32_32x32x16_bf16 v[48:63], v[84:87], v[92:95], v[48:63]
	v_mfma_f32_32x32x16_bf16 v[32:47], v[84:87], v[96:99], v[32:47]
	v_mfma_f32_32x32x16_bf16 v[16:31], v[88:91], v[92:95], v[16:31]
	v_mfma_f32_32x32x16_bf16 v[0:15], v[88:91], v[96:99], v[0:15]
	s_waitcnt vmcnt(6) lgkmcnt(0)
	s_barrier
	ds_read_b128 v[84:87], v76
	ds_read_b128 v[88:91], v76 offset:4096
	ds_read_b128 v[92:95], v80
	ds_read_b128 v[96:99], v80 offset:4096
	v_mfma_f32_32x32x16_bf16 v[48:63], v[100:103], v[108:111], v[48:63]
	s_mov_b32 s24, 0x380
	s_mov_b32 s25, 0
	s_add_u32 m0, s31, 0x18000
	v_lshl_add_u64 v[124:125], v[64:65], 0, s[24:25]
	global_load_lds_dwordx4 v[124:125], off
	v_mfma_f32_32x32x16_bf16 v[32:47], v[100:103], v[112:115], v[32:47]
	v_mfma_f32_32x32x16_bf16 v[16:31], v[104:107], v[108:111], v[16:31]
	s_add_u32 m0, s31, 0x1a000
	v_lshl_add_u64 v[126:127], v[66:67], 0, s[24:25]
	global_load_lds_dwordx4 v[126:127], off
	v_mfma_f32_32x32x16_bf16 v[0:15], v[104:107], v[112:115], v[0:15]
	ds_read_b128 v[100:103], v77
	ds_read_b128 v[104:107], v77 offset:4096
	ds_read_b128 v[108:111], v81
	ds_read_b128 v[112:115], v81 offset:4096
	s_waitcnt lgkmcnt(4)
	v_mfma_f32_32x32x16_bf16 v[48:63], v[84:87], v[92:95], v[48:63]
	s_add_u32 m0, s31, 0x1c000
	v_lshl_add_u64 v[124:125], v[68:69], 0, s[24:25]
	global_load_lds_dwordx4 v[124:125], off
	v_mfma_f32_32x32x16_bf16 v[32:47], v[84:87], v[96:99], v[32:47]
	v_mfma_f32_32x32x16_bf16 v[16:31], v[88:91], v[92:95], v[16:31]
	s_add_u32 m0, s31, 0x1e000
	v_lshl_add_u64 v[126:127], v[70:71], 0, s[24:25]
	global_load_lds_dwordx4 v[126:127], off
	v_mfma_f32_32x32x16_bf16 v[0:15], v[88:91], v[96:99], v[0:15]
	ds_read_b128 v[84:87], v78
	ds_read_b128 v[88:91], v78 offset:4096
	ds_read_b128 v[92:95], v82
	ds_read_b128 v[96:99], v82 offset:4096
	s_waitcnt lgkmcnt(4)
	v_mfma_f32_32x32x16_bf16 v[48:63], v[100:103], v[108:111], v[48:63]
	s_add_u32 m0, s31, 0x20000
	v_lshl_add_u64 v[124:125], v[72:73], 0, s[24:25]
	global_load_lds_dwordx4 v[124:125], off
	v_mfma_f32_32x32x16_bf16 v[32:47], v[100:103], v[112:115], v[32:47]
	v_mfma_f32_32x32x16_bf16 v[16:31], v[104:107], v[108:111], v[16:31]
	s_add_u32 m0, s31, 0x22000
	v_lshl_add_u64 v[126:127], v[74:75], 0, s[24:25]
	global_load_lds_dwordx4 v[126:127], off
	v_mfma_f32_32x32x16_bf16 v[0:15], v[104:107], v[112:115], v[0:15]
	ds_read_b128 v[100:103], v79
	ds_read_b128 v[104:107], v79 offset:4096
	ds_read_b128 v[108:111], v83
	ds_read_b128 v[112:115], v83 offset:4096
	s_waitcnt lgkmcnt(4)
	v_mfma_f32_32x32x16_bf16 v[48:63], v[84:87], v[92:95], v[48:63]
	v_mfma_f32_32x32x16_bf16 v[32:47], v[84:87], v[96:99], v[32:47]
	v_mfma_f32_32x32x16_bf16 v[16:31], v[88:91], v[92:95], v[16:31]
	v_mfma_f32_32x32x16_bf16 v[0:15], v[88:91], v[96:99], v[0:15]
	s_waitcnt vmcnt(6) lgkmcnt(0)
	s_barrier
;     ...
;   for (int kt = 0; kt < nk; ++kt) {
;     if (kt + 1 < nk) asm volatile("s_waitcnt vmcnt(6)" ::: "memory");
;     else asm volatile("s_waitcnt vmcnt(0)" ::: "memory");
;     __builtin_amdgcn_s_barrier();
;     asm volatile("" ::: "memory");
;     if (kt + 2 < nk) { const int st2 = (st >= 1) ? st - 1 : 2; GEMM_ISSUE(kt + 2, st2); }
;     const char* la = lds + st * STAGE_B;
;     const char* lb = la + 32768;
;     const unsigned sa_u = (unsigned)(size_t)la + arow_u, sb_u = (unsigned)(size_t)lb + brow_u;
;     const unsigned a0 = sa_u + co0, a1 = sa_u + co1, a2 = sa_u + co2, a3 = sa_u + co3;
;     const unsigned b0 = sb_u + co0, b1 = sb_u + co1, b2 = sb_u + co2, b3 = sb_u + co3;
;     {
;       bf16x8 p0, p1, q0, q1, u0, u1, w0, w1;
;       asm volatile(
;         "ds_read_b128 %4, %12\n\tds_read_b128 %5, %12 offset:4096\n\tds_read_b128 %6, %16\n\tds_read_b128 %7, %16 offset:4096\n\t"
;         "ds_read_b128 %8, %13\n\tds_read_b128 %9, %13 offset:4096\n\tds_read_b128 %10, %17\n\tds_read_b128 %11, %17 offset:4096\n\t"
;         "s_waitcnt lgkmcnt(4)\n\t"
;         "v_mfma_f32_32x32x16_bf16 %0, %4, %6, %0\n\tv_mfma_f32_32x32x16_bf16 %1, %4, %7, %1\n\tv_mfma_f32_32x32x16_bf16 %2, %5, %6, %2\n\tv_mfma_f32_32x32x16_bf16 %3, %5, %7, %3\n\t"
;         "ds_read_b128 %4, %14\n\tds_read_b128 %5, %14 offset:4096\n\tds_read_b128 %6, %18\n\tds_read_b128 %7, %18 offset:4096\n\t"
;         "s_waitcnt lgkmcnt(4)\n\t"
;         "v_mfma_f32_32x32x16_bf16 %0, %8, %10, %0\n\tv_mfma_f32_32x32x16_bf16 %1, %8, %11, %1\n\tv_mfma_f32_32x32x16_bf16 %2, %9, %10, %2\n\tv_mfma_f32_32x32x16_bf16 %3, %9, %11, %3\n\t"
;         "ds_read_b128 %8, %15\n\tds_read_b128 %9, %15 offset:4096\n\tds_read_b128 %10, %19\n\tds_read_b128 %11, %19 offset:4096\n\t"
;         "s_waitcnt lgkmcnt(4)\n\t"
;         "v_mfma_f32_32x32x16_bf16 %0, %4, %6, %0\n\tv_mfma_f32_32x32x16_bf16 %1, %4, %7, %1\n\tv_mfma_f32_32x32x16_bf16 %2, %5, %6, %2\n\tv_mfma_f32_32x32x16_bf16 %3, %5, %7, %3\n\t"
;         "s_waitcnt lgkmcnt(0)\n\t"
;         "v_mfma_f32_32x32x16_bf16 %0, %8, %10, %0\n\tv_mfma_f32_32x32x16_bf16 %1, %8, %11, %1\n\tv_mfma_f32_32x32x16_bf16 %2, %9, %10, %2\n\tv_mfma_f32_32x32x16_bf16 %3, %9, %11, %3"
;         : "+v"(acc[0][0]), "+v"(acc[0][1]), "+v"(acc[1][0]), "+v"(acc[1][1]),
;           "=&v"(p0), "=&v"(p1), "=&v"(q0), "=&v"(q1), "=&v"(u0), "=&v"(u1), "=&v"(w0), "=&v"(w1)
	ds_read_b128 v[84:87], v76 offset:49152
	ds_read_b128 v[88:91], v76 offset:53248
	ds_read_b128 v[92:95], v80 offset:49152
	ds_read_b128 v[96:99], v80 offset:53248
	v_mfma_f32_32x32x16_bf16 v[48:63], v[100:103], v[108:111], v[48:63]
	s_mov_b32 s24, 0x400
	s_mov_b32 s25, 0
	s_mov_b32 m0, s31
	v_lshl_add_u64 v[124:125], v[64:65], 0, s[24:25]
	global_load_lds_dwordx4 v[124:125], off
	v_mfma_f32_32x32x16_bf16 v[32:47], v[100:103], v[112:115], v[32:47]
	v_mfma_f32_32x32x16_bf16 v[16:31], v[104:107], v[108:111], v[16:31]
	s_add_u32 m0, s31, 0x2000
	v_lshl_add_u64 v[126:127], v[66:67], 0, s[24:25]
	global_load_lds_dwordx4 v[126:127], off
	v_mfma_f32_32x32x16_bf16 v[0:15], v[104:107], v[112:115], v[0:15]
	ds_read_b128 v[100:103], v77 offset:49152
	ds_read_b128 v[104:107], v77 offset:53248
	ds_read_b128 v[108:111], v81 offset:49152
	ds_read_b128 v[112:115], v81 offset:53248
	s_waitcnt lgkmcnt(4)
	v_mfma_f32_32x32x16_bf16 v[48:63], v[84:87], v[92:95], v[48:63]
	s_add_u32 m0, s31, 0x4000
	v_lshl_add_u64 v[124:125], v[68:69], 0, s[24:25]
	global_load_lds_dwordx4 v[124:125], off
	v_mfma_f32_32x32x16_bf16 v[32:47], v[84:87], v[96:99], v[32:47]
	v_mfma_f32_32x32x16_bf16 v[16:31], v[88:91], v[92:95], v[16:31]
	s_add_u32 m0, s31, 0x6000
	v_lshl_add_u64 v[126:127], v[70:71], 0, s[24:25]
	global_load_lds_dwordx4 v[126:127], off
	v_mfma_f32_32x32x16_bf16 v[0:15], v[88:91], v[96:99], v[0:15]
	ds_read_b128 v[84:87], v78 offset:49152
	ds_read_b128 v[88:91], v78 offset:53248
	ds_read_b128 v[92:95], v82 offset:49152
	ds_read_b128 v[96:99], v82 offset:53248
	s_waitcnt lgkmcnt(4)
	v_mfma_f32_32x32x16_bf16 v[48:63], v[100:103], v[108:111], v[48:63]
	s_add_u32 m0, s31, 0x8000
	v_lshl_add_u64 v[124:125], v[72:73], 0, s[24:25]
	global_load_lds_dwordx4 v[124:125], off
	v_mfma_f32_32x32x16_bf16 v[32:47], v[100:103], v[112:115], v[32:47]
	v_mfma_f32_32x32x16_bf16 v[16:31], v[104:107], v[108:111], v[16:31]
	s_add_u32 m0, s31, 0xa000
	v_lshl_add_u64 v[126:127], v[74:75], 0, s[24:25]
	global_load_lds_dwordx4 v[126:127], off
	v_mfma_f32_32x32x16_bf16 v[0:15], v[104:107], v[112:115], v[0:15]
	ds_read_b128 v[100:103], v79 offset:49152
	ds_read_b128 v[104:107], v79 offset:53248
	ds_read_b128 v[108:111], v83 offset:49152
	ds_read_b128 v[112:115], v83 offset:53248
	s_waitcnt lgkmcnt(4)
	v_mfma_f32_32x32x16_bf16 v[48:63], v[84:87], v[92:95], v[48:63]
	v_mfma_f32_32x32x16_bf16 v[32:47], v[84:87], v[96:99], v[32:47]
	v_mfma_f32_32x32x16_bf16 v[16:31], v[88:91], v[92:95], v[16:31]
	v_mfma_f32_32x32x16_bf16 v[0:15], v[88:91], v[96:99], v[0:15]
	s_waitcnt vmcnt(6) lgkmcnt(0)
	s_barrier
	ds_read_b128 v[84:87], v116
	ds_read_b128 v[88:91], v116 offset:4096
	ds_read_b128 v[92:95], v120
	ds_read_b128 v[96:99], v120 offset:4096
	v_mfma_f32_32x32x16_bf16 v[48:63], v[100:103], v[108:111], v[48:63]
	s_mov_b32 s24, 0x480
	s_mov_b32 s25, 0
	s_add_u32 m0, s31, 0xc000
	v_lshl_add_u64 v[124:125], v[64:65], 0, s[24:25]
	global_load_lds_dwordx4 v[124:125], off
	v_mfma_f32_32x32x16_bf16 v[32:47], v[100:103], v[112:115], v[32:47]
	v_mfma_f32_32x32x16_bf16 v[16:31], v[104:107], v[108:111], v[16:31]
	s_add_u32 m0, s31, 0xe000
	v_lshl_add_u64 v[126:127], v[66:67], 0, s[24:25]
	global_load_lds_dwordx4 v[126:127], off
	v_mfma_f32_32x32x16_bf16 v[0:15], v[104:107], v[112:115], v[0:15]
	ds_read_b128 v[100:103], v117
	ds_read_b128 v[104:107], v117 offset:4096
	ds_read_b128 v[108:111], v121
	ds_read_b128 v[112:115], v121 offset:4096
	s_waitcnt lgkmcnt(4)
	v_mfma_f32_32x32x16_bf16 v[48:63], v[84:87], v[92:95], v[48:63]
	s_add_u32 m0, s31, 0x10000
	v_lshl_add_u64 v[124:125], v[68:69], 0, s[24:25]
	global_load_lds_dwordx4 v[124:125], off
	v_mfma_f32_32x32x16_bf16 v[32:47], v[84:87], v[96:99], v[32:47]
	v_mfma_f32_32x32x16_bf16 v[16:31], v[88:91], v[92:95], v[16:31]
	s_add_u32 m0, s31, 0x12000
	v_lshl_add_u64 v[126:127], v[70:71], 0, s[24:25]
	global_load_lds_dwordx4 v[126:127], off
	v_mfma_f32_32x32x16_bf16 v[0:15], v[88:91], v[96:99], v[0:15]
	ds_read_b128 v[84:87], v118
	ds_read_b128 v[88:91], v118 offset:4096
	ds_read_b128 v[92:95], v122
	ds_read_b128 v[96:99], v122 offset:4096
	s_waitcnt lgkmcnt(4)
	v_mfma_f32_32x32x16_bf16 v[48:63], v[100:103], v[108:111], v[48:63]
	s_add_u32 m0, s31, 0x14000
	v_lshl_add_u64 v[124:125], v[72:73], 0, s[24:25]
	global_load_lds_dwordx4 v[124:125], off
	v_mfma_f32_32x32x16_bf16 v[32:47], v[100:103], v[112:115], v[32:47]
	v_mfma_f32_32x32x16_bf16 v[16:31], v[104:107], v[108:111], v[16:31]
	s_add_u32 m0, s31, 0x16000
	v_lshl_add_u64 v[126:127], v[74:75], 0, s[24:25]
	global_load_lds_dwordx4 v[126:127], off
	v_mfma_f32_32x32x16_bf16 v[0:15], v[104:107], v[112:115], v[0:15]
	ds_read_b128 v[100:103], v119
	ds_read_b128 v[104:107], v119 offset:4096
	ds_read_b128 v[108:111], v123
	ds_read_b128 v[112:115], v123 offset:4096
	s_waitcnt lgkmcnt(4)
	v_mfma_f32_32x32x16_bf16 v[48:63], v[84:87], v[92:95], v[48:63]
	v_mfma_f32_32x32x16_bf16 v[32:47], v[84:87], v[96:99], v[32:47]
	v_mfma_f32_32x32x16_bf16 v[16:31], v[88:91], v[92:95], v[16:31]
	v_mfma_f32_32x32x16_bf16 v[0:15], v[88:91], v[96:99], v[0:15]
	s_waitcnt vmcnt(6) lgkmcnt(0)
	s_barrier
;     ...
;   for (int kt = 0; kt < nk; ++kt) {
;     if (kt + 1 < nk) asm volatile("s_waitcnt vmcnt(6)" ::: "memory");
;     else asm volatile("s_waitcnt vmcnt(0)" ::: "memory");
;     __builtin_amdgcn_s_barrier();
;     asm volatile("" ::: "memory");
;     if (kt + 2 < nk) { const int st2 = (st >= 1) ? st - 1 : 2; GEMM_ISSUE(kt + 2, st2); }
;     const char* la = lds + st * STAGE_B;
;     const char* lb = la + 32768;
;     const unsigned sa_u = (unsigned)(size_t)la + arow_u, sb_u = (unsigned)(size_t)lb + brow_u;
;     const unsigned a0 = sa_u + co0, a1 = sa_u + co1, a2 = sa_u + co2, a3 = sa_u + co3;
;     const unsigned b0 = sb_u + co0, b1 = sb_u + co1, b2 = sb_u + co2, b3 = sb_u + co3;
;     {
;       bf16x8 p0, p1, q0, q1, u0, u1, w0, w1;
;       asm volatile(
;         "ds_read_b128 %4, %12\n\tds_read_b128 %5, %12 offset:4096\n\tds_read_b128 %6, %16\n\tds_read_b128 %7, %16 offset:4096\n\t"
;         "ds_read_b128 %8, %13\n\tds_read_b128 %9, %13 offset:4096\n\tds_read_b128 %10, %17\n\tds_read_b128 %11, %17 offset:4096\n\t"
;         "s_waitcnt lgkmcnt(4)\n\t"
;         "v_mfma_f32_32x32x16_bf16 %0, %4, %6, %0\n\tv_mfma_f32_32x32x16_bf16 %1, %4, %7, %1\n\tv_mfma_f32_32x32x16_bf16 %2, %5, %6, %2\n\tv_mfma_f32_32x32x16_bf16 %3, %5, %7, %3\n\t"
;         "ds_read_b128 %4, %14\n\tds_read_b128 %5, %14 offset:4096\n\tds_read_b128 %6, %18\n\tds_read_b128 %7, %18 offset:4096\n\t"
;         "s_waitcnt lgkmcnt(4)\n\t"
;         "v_mfma_f32_32x32x16_bf16 %0, %8, %10, %0\n\tv_mfma_f32_32x32x16_bf16 %1, %8, %11, %1\n\tv_mfma_f32_32x32x16_bf16 %2, %9, %10, %2\n\tv_mfma_f32_32x32x16_bf16 %3, %9, %11, %3\n\t"
;         "ds_read_b128 %8, %15\n\tds_read_b128 %9, %15 offset:4096\n\tds_read_b128 %10, %19\n\tds_read_b128 %11, %19 offset:4096\n\t"
;         "s_waitcnt lgkmcnt(4)\n\t"
;         "v_mfma_f32_32x32x16_bf16 %0, %4, %6, %0\n\tv_mfma_f32_32x32x16_bf16 %1, %4, %7, %1\n\tv_mfma_f32_32x32x16_bf16 %2, %5, %6, %2\n\tv_mfma_f32_32x32x16_bf16 %3, %5, %7, %3\n\t"
;         "s_waitcnt lgkmcnt(0)\n\t"
;         "v_mfma_f32_32x32x16_bf16 %0, %8, %10, %0\n\tv_mfma_f32_32x32x16_bf16 %1, %8, %11, %1\n\tv_mfma_f32_32x32x16_bf16 %2, %9, %10, %2\n\tv_mfma_f32_32x32x16_bf16 %3, %9, %11, %3"
;         : "+v"(acc[0][0]), "+v"(acc[0][1]), "+v"(acc[1][0]), "+v"(acc[1][1]),
;           "=&v"(p0), "=&v"(p1), "=&v"(q0), "=&v"(q1), "=&v"(u0), "=&v"(u1), "=&v"(w0), "=&v"(w1)
	ds_read_b128 v[84:87], v76
	ds_read_b128 v[88:91], v76 offset:4096
	ds_read_b128 v[92:95], v80
	ds_read_b128 v[96:99], v80 offset:4096
	v_mfma_f32_32x32x16_bf16 v[48:63], v[100:103], v[108:111], v[48:63]
	s_mov_b32 s24, 0x500
	s_mov_b32 s25, 0
	s_add_u32 m0, s31, 0x18000
	v_lshl_add_u64 v[124:125], v[64:65], 0, s[24:25]
	global_load_lds_dwordx4 v[124:125], off
	v_mfma_f32_32x32x16_bf16 v[32:47], v[100:103], v[112:115], v[32:47]
	v_mfma_f32_32x32x16_bf16 v[16:31], v[104:107], v[108:111], v[16:31]
	s_add_u32 m0, s31, 0x1a000
	v_lshl_add_u64 v[126:127], v[66:67], 0, s[24:25]
	global_load_lds_dwordx4 v[126:127], off
	v_mfma_f32_32x32x16_bf16 v[0:15], v[104:107], v[112:115], v[0:15]
	ds_read_b128 v[100:103], v77
	ds_read_b128 v[104:107], v77 offset:4096
	ds_read_b128 v[108:111], v81
	ds_read_b128 v[112:115], v81 offset:4096
	s_waitcnt lgkmcnt(4)
	v_mfma_f32_32x32x16_bf16 v[48:63], v[84:87], v[92:95], v[48:63]
	s_add_u32 m0, s31, 0x1c000
	v_lshl_add_u64 v[124:125], v[68:69], 0, s[24:25]
	global_load_lds_dwordx4 v[124:125], off
	v_mfma_f32_32x32x16_bf16 v[32:47], v[84:87], v[96:99], v[32:47]
	v_mfma_f32_32x32x16_bf16 v[16:31], v[88:91], v[92:95], v[16:31]
	s_add_u32 m0, s31, 0x1e000
	v_lshl_add_u64 v[126:127], v[70:71], 0, s[24:25]
	global_load_lds_dwordx4 v[126:127], off
	v_mfma_f32_32x32x16_bf16 v[0:15], v[88:91], v[96:99], v[0:15]
	ds_read_b128 v[84:87], v78
	ds_read_b128 v[88:91], v78 offset:4096
	ds_read_b128 v[92:95], v82
	ds_read_b128 v[96:99], v82 offset:4096
	s_waitcnt lgkmcnt(4)
	v_mfma_f32_32x32x16_bf16 v[48:63], v[100:103], v[108:111], v[48:63]
	s_add_u32 m0, s31, 0x20000
	v_lshl_add_u64 v[124:125], v[72:73], 0, s[24:25]
	global_load_lds_dwordx4 v[124:125], off
	v_mfma_f32_32x32x16_bf16 v[32:47], v[100:103], v[112:115], v[32:47]
	v_mfma_f32_32x32x16_bf16 v[16:31], v[104:107], v[108:111], v[16:31]
	s_add_u32 m0, s31, 0x22000
	v_lshl_add_u64 v[126:127], v[74:75], 0, s[24:25]
	global_load_lds_dwordx4 v[126:127], off
	v_mfma_f32_32x32x16_bf16 v[0:15], v[104:107], v[112:115], v[0:15]
	ds_read_b128 v[100:103], v79
	ds_read_b128 v[104:107], v79 offset:4096
	ds_read_b128 v[108:111], v83
	ds_read_b128 v[112:115], v83 offset:4096
	s_waitcnt lgkmcnt(4)
	v_mfma_f32_32x32x16_bf16 v[48:63], v[84:87], v[92:95], v[48:63]
	v_mfma_f32_32x32x16_bf16 v[32:47], v[84:87], v[96:99], v[32:47]
	v_mfma_f32_32x32x16_bf16 v[16:31], v[88:91], v[92:95], v[16:31]
	v_mfma_f32_32x32x16_bf16 v[0:15], v[88:91], v[96:99], v[0:15]
	s_waitcnt vmcnt(6) lgkmcnt(0)
	s_barrier
	ds_read_b128 v[84:87], v76 offset:49152
	ds_read_b128 v[88:91], v76 offset:53248
	ds_read_b128 v[92:95], v80 offset:49152
	ds_read_b128 v[96:99], v80 offset:53248
	v_mfma_f32_32x32x16_bf16 v[48:63], v[100:103], v[108:111], v[48:63]
	s_mov_b32 s24, 0x580
	s_mov_b32 s25, 0
	s_mov_b32 m0, s31
	v_lshl_add_u64 v[124:125], v[64:65], 0, s[24:25]
	global_load_lds_dwordx4 v[124:125], off
	v_mfma_f32_32x32x16_bf16 v[32:47], v[100:103], v[112:115], v[32:47]
	v_mfma_f32_32x32x16_bf16 v[16:31], v[104:107], v[108:111], v[16:31]
	s_add_u32 m0, s31, 0x2000
	v_lshl_add_u64 v[126:127], v[66:67], 0, s[24:25]
	global_load_lds_dwordx4 v[126:127], off
	v_mfma_f32_32x32x16_bf16 v[0:15], v[104:107], v[112:115], v[0:15]
	ds_read_b128 v[100:103], v77 offset:49152
	ds_read_b128 v[104:107], v77 offset:53248
	ds_read_b128 v[108:111], v81 offset:49152
	ds_read_b128 v[112:115], v81 offset:53248
	s_waitcnt lgkmcnt(4)
	v_mfma_f32_32x32x16_bf16 v[48:63], v[84:87], v[92:95], v[48:63]
	s_add_u32 m0, s31, 0x4000
	v_lshl_add_u64 v[124:125], v[68:69], 0, s[24:25]
	global_load_lds_dwordx4 v[124:125], off
	v_mfma_f32_32x32x16_bf16 v[32:47], v[84:87], v[96:99], v[32:47]
	v_mfma_f32_32x32x16_bf16 v[16:31], v[88:91], v[92:95], v[16:31]
	s_add_u32 m0, s31, 0x6000
	v_lshl_add_u64 v[126:127], v[70:71], 0, s[24:25]
	global_load_lds_dwordx4 v[126:127], off
	v_mfma_f32_32x32x16_bf16 v[0:15], v[88:91], v[96:99], v[0:15]
	ds_read_b128 v[84:87], v78 offset:49152
	ds_read_b128 v[88:91], v78 offset:53248
	ds_read_b128 v[92:95], v82 offset:49152
	ds_read_b128 v[96:99], v82 offset:53248
	s_waitcnt lgkmcnt(4)
	v_mfma_f32_32x32x16_bf16 v[48:63], v[100:103], v[108:111], v[48:63]
	s_add_u32 m0, s31, 0x8000
	v_lshl_add_u64 v[124:125], v[72:73], 0, s[24:25]
	global_load_lds_dwordx4 v[124:125], off
	v_mfma_f32_32x32x16_bf16 v[32:47], v[100:103], v[112:115], v[32:47]
	v_mfma_f32_32x32x16_bf16 v[16:31], v[104:107], v[108:111], v[16:31]
	s_add_u32 m0, s31, 0xa000
	v_lshl_add_u64 v[126:127], v[74:75], 0, s[24:25]
	global_load_lds_dwordx4 v[126:127], off
	v_mfma_f32_32x32x16_bf16 v[0:15], v[104:107], v[112:115], v[0:15]
	ds_read_b128 v[100:103], v79 offset:49152
	ds_read_b128 v[104:107], v79 offset:53248
	ds_read_b128 v[108:111], v83 offset:49152
	ds_read_b128 v[112:115], v83 offset:53248
	s_waitcnt lgkmcnt(4)
	v_mfma_f32_32x32x16_bf16 v[48:63], v[84:87], v[92:95], v[48:63]
	v_mfma_f32_32x32x16_bf16 v[32:47], v[84:87], v[96:99], v[32:47]
	v_mfma_f32_32x32x16_bf16 v[16:31], v[88:91], v[92:95], v[16:31]
	v_mfma_f32_32x32x16_bf16 v[0:15], v[88:91], v[96:99], v[0:15]
	s_waitcnt vmcnt(6) lgkmcnt(0)
	s_barrier
;     ...
;   for (int kt = 0; kt < nk; ++kt) {
;     if (kt + 1 < nk) asm volatile("s_waitcnt vmcnt(6)" ::: "memory");
;     else asm volatile("s_waitcnt vmcnt(0)" ::: "memory");
;     __builtin_amdgcn_s_barrier();
;     asm volatile("" ::: "memory");
;     if (kt + 2 < nk) { const int st2 = (st >= 1) ? st - 1 : 2; GEMM_ISSUE(kt + 2, st2); }
;     const char* la = lds + st * STAGE_B;
;     const char* lb = la + 32768;
;     const unsigned sa_u = (unsigned)(size_t)la + arow_u, sb_u = (unsigned)(size_t)lb + brow_u;
;     const unsigned a0 = sa_u + co0, a1 = sa_u + co1, a2 = sa_u + co2, a3 = sa_u + co3;
;     const unsigned b0 = sb_u + co0, b1 = sb_u + co1, b2 = sb_u + co2, b3 = sb_u + co3;
;     {
;       bf16x8 p0, p1, q0, q1, u0, u1, w0, w1;
;       asm volatile(
;         "ds_read_b128 %4, %12\n\tds_read_b128 %5, %12 offset:4096\n\tds_read_b128 %6, %16\n\tds_read_b128 %7, %16 offset:4096\n\t"
;         "ds_read_b128 %8, %13\n\tds_read_b128 %9, %13 offset:4096\n\tds_read_b128 %10, %17\n\tds_read_b128 %11, %17 offset:4096\n\t"
;         "s_waitcnt lgkmcnt(4)\n\t"
;         "v_mfma_f32_32x32x16_bf16 %0, %4, %6, %0\n\tv_mfma_f32_32x32x16_bf16 %1, %4, %7, %1\n\tv_mfma_f32_32x32x16_bf16 %2, %5, %6, %2\n\tv_mfma_f32_32x32x16_bf16 %3, %5, %7, %3\n\t"
;         "ds_read_b128 %4, %14\n\tds_read_b128 %5, %14 offset:4096\n\tds_read_b128 %6, %18\n\tds_read_b128 %7, %18 offset:4096\n\t"
;         "s_waitcnt lgkmcnt(4)\n\t"
;         "v_mfma_f32_32x32x16_bf16 %0, %8, %10, %0\n\tv_mfma_f32_32x32x16_bf16 %1, %8, %11, %1\n\tv_mfma_f32_32x32x16_bf16 %2, %9, %10, %2\n\tv_mfma_f32_32x32x16_bf16 %3, %9, %11, %3\n\t"
;         "ds_read_b128 %8, %15\n\tds_read_b128 %9, %15 offset:4096\n\tds_read_b128 %10, %19\n\tds_read_b128 %11, %19 offset:4096\n\t"
;         "s_waitcnt lgkmcnt(4)\n\t"
;         "v_mfma_f32_32x32x16_bf16 %0, %4, %6, %0\n\tv_mfma_f32_32x32x16_bf16 %1, %4, %7, %1\n\tv_mfma_f32_32x32x16_bf16 %2, %5, %6, %2\n\tv_mfma_f32_32x32x16_bf16 %3, %5, %7, %3\n\t"
;         "s_waitcnt lgkmcnt(0)\n\t"
;         "v_mfma_f32_32x32x16_bf16 %0, %8, %10, %0\n\tv_mfma_f32_32x32x16_bf16 %1, %8, %11, %1\n\tv_mfma_f32_32x32x16_bf16 %2, %9, %10, %2\n\tv_mfma_f32_32x32x16_bf16 %3, %9, %11, %3"
;         : "+v"(acc[0][0]), "+v"(acc[0][1]), "+v"(acc[1][0]), "+v"(acc[1][1]),
;           "=&v"(p0), "=&v"(p1), "=&v"(q0), "=&v"(q1), "=&v"(u0), "=&v"(u1), "=&v"(w0), "=&v"(w1)
	ds_read_b128 v[84:87], v116
	ds_read_b128 v[88:91], v116 offset:4096
	ds_read_b128 v[92:95], v120
	ds_read_b128 v[96:99], v120 offset:4096
	v_mfma_f32_32x32x16_bf16 v[48:63], v[100:103], v[108:111], v[48:63]
	s_mov_b32 s24, 0x600
	s_mov_b32 s25, 0
	s_add_u32 m0, s31, 0xc000
	v_lshl_add_u64 v[124:125], v[64:65], 0, s[24:25]
	global_load_lds_dwordx4 v[124:125], off
	v_mfma_f32_32x32x16_bf16 v[32:47], v[100:103], v[112:115], v[32:47]
	v_mfma_f32_32x32x16_bf16 v[16:31], v[104:107], v[108:111], v[16:31]
	s_add_u32 m0, s31, 0xe000
	v_lshl_add_u64 v[126:127], v[66:67], 0, s[24:25]
	global_load_lds_dwordx4 v[126:127], off
	v_mfma_f32_32x32x16_bf16 v[0:15], v[104:107], v[112:115], v[0:15]
	ds_read_b128 v[100:103], v117
	ds_read_b128 v[104:107], v117 offset:4096
	ds_read_b128 v[108:111], v121
	ds_read_b128 v[112:115], v121 offset:4096
	s_waitcnt lgkmcnt(4)
	v_mfma_f32_32x32x16_bf16 v[48:63], v[84:87], v[92:95], v[48:63]
	s_add_u32 m0, s31, 0x10000
	v_lshl_add_u64 v[124:125], v[68:69], 0, s[24:25]
	global_load_lds_dwordx4 v[124:125], off
	v_mfma_f32_32x32x16_bf16 v[32:47], v[84:87], v[96:99], v[32:47]
	v_mfma_f32_32x32x16_bf16 v[16:31], v[88:91], v[92:95], v[16:31]
	s_add_u32 m0, s31, 0x12000
	v_lshl_add_u64 v[126:127], v[70:71], 0, s[24:25]
	global_load_lds_dwordx4 v[126:127], off
	v_mfma_f32_32x32x16_bf16 v[0:15], v[88:91], v[96:99], v[0:15]
	ds_read_b128 v[84:87], v118
	ds_read_b128 v[88:91], v118 offset:4096
	ds_read_b128 v[92:95], v122
	ds_read_b128 v[96:99], v122 offset:4096
	s_waitcnt lgkmcnt(4)
	v_mfma_f32_32x32x16_bf16 v[48:63], v[100:103], v[108:111], v[48:63]
	s_add_u32 m0, s31, 0x14000
	v_lshl_add_u64 v[124:125], v[72:73], 0, s[24:25]
	global_load_lds_dwordx4 v[124:125], off
	v_mfma_f32_32x32x16_bf16 v[32:47], v[100:103], v[112:115], v[32:47]
	v_mfma_f32_32x32x16_bf16 v[16:31], v[104:107], v[108:111], v[16:31]
	s_add_u32 m0, s31, 0x16000
	v_lshl_add_u64 v[126:127], v[74:75], 0, s[24:25]
	global_load_lds_dwordx4 v[126:127], off
	v_mfma_f32_32x32x16_bf16 v[0:15], v[104:107], v[112:115], v[0:15]
	ds_read_b128 v[100:103], v119
	ds_read_b128 v[104:107], v119 offset:4096
	ds_read_b128 v[108:111], v123
	ds_read_b128 v[112:115], v123 offset:4096
	s_waitcnt lgkmcnt(4)
	v_mfma_f32_32x32x16_bf16 v[48:63], v[84:87], v[92:95], v[48:63]
	v_mfma_f32_32x32x16_bf16 v[32:47], v[84:87], v[96:99], v[32:47]
	v_mfma_f32_32x32x16_bf16 v[16:31], v[88:91], v[92:95], v[16:31]
	v_mfma_f32_32x32x16_bf16 v[0:15], v[88:91], v[96:99], v[0:15]
	s_waitcnt vmcnt(6) lgkmcnt(0)
	s_barrier
	ds_read_b128 v[84:87], v76
	ds_read_b128 v[88:91], v76 offset:4096
	ds_read_b128 v[92:95], v80
	ds_read_b128 v[96:99], v80 offset:4096
	v_mfma_f32_32x32x16_bf16 v[48:63], v[100:103], v[108:111], v[48:63]
	s_mov_b32 s24, 0x680
	s_mov_b32 s25, 0
	s_add_u32 m0, s31, 0x18000
	v_lshl_add_u64 v[124:125], v[64:65], 0, s[24:25]
	global_load_lds_dwordx4 v[124:125], off
	v_mfma_f32_32x32x16_bf16 v[32:47], v[100:103], v[112:115], v[32:47]
	v_mfma_f32_32x32x16_bf16 v[16:31], v[104:107], v[108:111], v[16:31]
	s_add_u32 m0, s31, 0x1a000
	v_lshl_add_u64 v[126:127], v[66:67], 0, s[24:25]
	global_load_lds_dwordx4 v[126:127], off
	v_mfma_f32_32x32x16_bf16 v[0:15], v[104:107], v[112:115], v[0:15]
	ds_read_b128 v[100:103], v77
	ds_read_b128 v[104:107], v77 offset:4096
	ds_read_b128 v[108:111], v81
	ds_read_b128 v[112:115], v81 offset:4096
	s_waitcnt lgkmcnt(4)
	v_mfma_f32_32x32x16_bf16 v[48:63], v[84:87], v[92:95], v[48:63]
	s_add_u32 m0, s31, 0x1c000
	v_lshl_add_u64 v[124:125], v[68:69], 0, s[24:25]
	global_load_lds_dwordx4 v[124:125], off
	v_mfma_f32_32x32x16_bf16 v[32:47], v[84:87], v[96:99], v[32:47]
	v_mfma_f32_32x32x16_bf16 v[16:31], v[88:91], v[92:95], v[16:31]
	s_add_u32 m0, s31, 0x1e000
	v_lshl_add_u64 v[126:127], v[70:71], 0, s[24:25]
	global_load_lds_dwordx4 v[126:127], off
	v_mfma_f32_32x32x16_bf16 v[0:15], v[88:91], v[96:99], v[0:15]
	ds_read_b128 v[84:87], v78
	ds_read_b128 v[88:91], v78 offset:4096
	ds_read_b128 v[92:95], v82
	ds_read_b128 v[96:99], v82 offset:4096
	s_waitcnt lgkmcnt(4)
	v_mfma_f32_32x32x16_bf16 v[48:63], v[100:103], v[108:111], v[48:63]
	s_add_u32 m0, s31, 0x20000
	v_lshl_add_u64 v[124:125], v[72:73], 0, s[24:25]
	global_load_lds_dwordx4 v[124:125], off
	v_mfma_f32_32x32x16_bf16 v[32:47], v[100:103], v[112:115], v[32:47]
	v_mfma_f32_32x32x16_bf16 v[16:31], v[104:107], v[108:111], v[16:31]
	s_add_u32 m0, s31, 0x22000
	v_lshl_add_u64 v[126:127], v[74:75], 0, s[24:25]
	global_load_lds_dwordx4 v[126:127], off
	v_mfma_f32_32x32x16_bf16 v[0:15], v[104:107], v[112:115], v[0:15]
	ds_read_b128 v[100:103], v79
	ds_read_b128 v[104:107], v79 offset:4096
	ds_read_b128 v[108:111], v83
	ds_read_b128 v[112:115], v83 offset:4096
	s_waitcnt lgkmcnt(4)
	v_mfma_f32_32x32x16_bf16 v[48:63], v[84:87], v[92:95], v[48:63]
	v_mfma_f32_32x32x16_bf16 v[32:47], v[84:87], v[96:99], v[32:47]
	v_mfma_f32_32x32x16_bf16 v[16:31], v[88:91], v[92:95], v[16:31]
	v_mfma_f32_32x32x16_bf16 v[0:15], v[88:91], v[96:99], v[0:15]
	s_waitcnt vmcnt(6) lgkmcnt(0)
	s_barrier
;     ...
;   for (int kt = 0; kt < nk; ++kt) {
;     if (kt + 1 < nk) asm volatile("s_waitcnt vmcnt(6)" ::: "memory");
;     else asm volatile("s_waitcnt vmcnt(0)" ::: "memory");
;     __builtin_amdgcn_s_barrier();
;     asm volatile("" ::: "memory");
;     if (kt + 2 < nk) { const int st2 = (st >= 1) ? st - 1 : 2; GEMM_ISSUE(kt + 2, st2); }
;     const char* la = lds + st * STAGE_B;
;     const char* lb = la + 32768;
;     const unsigned sa_u = (unsigned)(size_t)la + arow_u, sb_u = (unsigned)(size_t)lb + brow_u;
;     const unsigned a0 = sa_u + co0, a1 = sa_u + co1, a2 = sa_u + co2, a3 = sa_u + co3;
;     const unsigned b0 = sb_u + co0, b1 = sb_u + co1, b2 = sb_u + co2, b3 = sb_u + co3;
;     {
;       bf16x8 p0, p1, q0, q1, u0, u1, w0, w1;
;       asm volatile(
;         "ds_read_b128 %4, %12\n\tds_read_b128 %5, %12 offset:4096\n\tds_read_b128 %6, %16\n\tds_read_b128 %7, %16 offset:4096\n\t"
;         "ds_read_b128 %8, %13\n\tds_read_b128 %9, %13 offset:4096\n\tds_read_b128 %10, %17\n\tds_read_b128 %11, %17 offset:4096\n\t"
;         "s_waitcnt lgkmcnt(4)\n\t"
;         "v_mfma_f32_32x32x16_bf16 %0, %4, %6, %0\n\tv_mfma_f32_32x32x16_bf16 %1, %4, %7, %1\n\tv_mfma_f32_32x32x16_bf16 %2, %5, %6, %2\n\tv_mfma_f32_32x32x16_bf16 %3, %5, %7, %3\n\t"
;         "ds_read_b128 %4, %14\n\tds_read_b128 %5, %14 offset:4096\n\tds_read_b128 %6, %18\n\tds_read_b128 %7, %18 offset:4096\n\t"
;         "s_waitcnt lgkmcnt(4)\n\t"
;         "v_mfma_f32_32x32x16_bf16 %0, %8, %10, %0\n\tv_mfma_f32_32x32x16_bf16 %1, %8, %11, %1\n\tv_mfma_f32_32x32x16_bf16 %2, %9, %10, %2\n\tv_mfma_f32_32x32x16_bf16 %3, %9, %11, %3\n\t"
;         "ds_read_b128 %8, %15\n\tds_read_b128 %9, %15 offset:4096\n\tds_read_b128 %10, %19\n\tds_read_b128 %11, %19 offset:4096\n\t"
;         "s_waitcnt lgkmcnt(4)\n\t"
;         "v_mfma_f32_32x32x16_bf16 %0, %4, %6, %0\n\tv_mfma_f32_32x32x16_bf16 %1, %4, %7, %1\n\tv_mfma_f32_32x32x16_bf16 %2, %5, %6, %2\n\tv_mfma_f32_32x32x16_bf16 %3, %5, %7, %3\n\t"
;         "s_waitcnt lgkmcnt(0)\n\t"
;         "v_mfma_f32_32x32x16_bf16 %0, %8, %10, %0\n\tv_mfma_f32_32x32x16_bf16 %1, %8, %11, %1\n\tv_mfma_f32_32x32x16_bf16 %2, %9, %10, %2\n\tv_mfma_f32_32x32x16_bf16 %3, %9, %11, %3"
;         : "+v"(acc[0][0]), "+v"(acc[0][1]), "+v"(acc[1][0]), "+v"(acc[1][1]),
;           "=&v"(p0), "=&v"(p1), "=&v"(q0), "=&v"(q1), "=&v"(u0), "=&v"(u1), "=&v"(w0), "=&v"(w1)
	ds_read_b128 v[84:87], v76 offset:49152
	ds_read_b128 v[88:91], v76 offset:53248
	ds_read_b128 v[92:95], v80 offset:49152
	ds_read_b128 v[96:99], v80 offset:53248
	v_mfma_f32_32x32x16_bf16 v[48:63], v[100:103], v[108:111], v[48:63]
	s_mov_b32 s24, 0x700
	s_mov_b32 s25, 0
	s_mov_b32 m0, s31
	v_lshl_add_u64 v[124:125], v[64:65], 0, s[24:25]
	global_load_lds_dwordx4 v[124:125], off
	v_mfma_f32_32x32x16_bf16 v[32:47], v[100:103], v[112:115], v[32:47]
	v_mfma_f32_32x32x16_bf16 v[16:31], v[104:107], v[108:111], v[16:31]
	s_add_u32 m0, s31, 0x2000
	v_lshl_add_u64 v[126:127], v[66:67], 0, s[24:25]
	global_load_lds_dwordx4 v[126:127], off
	v_mfma_f32_32x32x16_bf16 v[0:15], v[104:107], v[112:115], v[0:15]
	ds_read_b128 v[100:103], v77 offset:49152
	ds_read_b128 v[104:107], v77 offset:53248
	ds_read_b128 v[108:111], v81 offset:49152
	ds_read_b128 v[112:115], v81 offset:53248
	s_waitcnt lgkmcnt(4)
	v_mfma_f32_32x32x16_bf16 v[48:63], v[84:87], v[92:95], v[48:63]
	s_add_u32 m0, s31, 0x4000
	v_lshl_add_u64 v[124:125], v[68:69], 0, s[24:25]
	global_load_lds_dwordx4 v[124:125], off
	v_mfma_f32_32x32x16_bf16 v[32:47], v[84:87], v[96:99], v[32:47]
	v_mfma_f32_32x32x16_bf16 v[16:31], v[88:91], v[92:95], v[16:31]
	s_add_u32 m0, s31, 0x6000
	v_lshl_add_u64 v[126:127], v[70:71], 0, s[24:25]
	global_load_lds_dwordx4 v[126:127], off
	v_mfma_f32_32x32x16_bf16 v[0:15], v[88:91], v[96:99], v[0:15]
	ds_read_b128 v[84:87], v78 offset:49152
	ds_read_b128 v[88:91], v78 offset:53248
	ds_read_b128 v[92:95], v82 offset:49152
	ds_read_b128 v[96:99], v82 offset:53248
	s_waitcnt lgkmcnt(4)
	v_mfma_f32_32x32x16_bf16 v[48:63], v[100:103], v[108:111], v[48:63]
	s_add_u32 m0, s31, 0x8000
	v_lshl_add_u64 v[124:125], v[72:73], 0, s[24:25]
	global_load_lds_dwordx4 v[124:125], off
	v_mfma_f32_32x32x16_bf16 v[32:47], v[100:103], v[112:115], v[32:47]
	v_mfma_f32_32x32x16_bf16 v[16:31], v[104:107], v[108:111], v[16:31]
	s_add_u32 m0, s31, 0xa000
	v_lshl_add_u64 v[126:127], v[74:75], 0, s[24:25]
	global_load_lds_dwordx4 v[126:127], off
	v_mfma_f32_32x32x16_bf16 v[0:15], v[104:107], v[112:115], v[0:15]
	ds_read_b128 v[100:103], v79 offset:49152
	ds_read_b128 v[104:107], v79 offset:53248
	ds_read_b128 v[108:111], v83 offset:49152
	ds_read_b128 v[112:115], v83 offset:53248
	s_waitcnt lgkmcnt(4)
	v_mfma_f32_32x32x16_bf16 v[48:63], v[84:87], v[92:95], v[48:63]
	v_mfma_f32_32x32x16_bf16 v[32:47], v[84:87], v[96:99], v[32:47]
	v_mfma_f32_32x32x16_bf16 v[16:31], v[88:91], v[92:95], v[16:31]
	v_mfma_f32_32x32x16_bf16 v[0:15], v[88:91], v[96:99], v[0:15]
	s_waitcnt vmcnt(6) lgkmcnt(0)
	s_barrier
	ds_read_b128 v[84:87], v116
	ds_read_b128 v[88:91], v116 offset:4096
	ds_read_b128 v[92:95], v120
	ds_read_b128 v[96:99], v120 offset:4096
	v_mfma_f32_32x32x16_bf16 v[48:63], v[100:103], v[108:111], v[48:63]
	s_mov_b32 s24, 0x780
	s_mov_b32 s25, 0
	s_add_u32 m0, s31, 0xc000
	v_lshl_add_u64 v[124:125], v[64:65], 0, s[24:25]
	global_load_lds_dwordx4 v[124:125], off
	v_mfma_f32_32x32x16_bf16 v[32:47], v[100:103], v[112:115], v[32:47]
	v_mfma_f32_32x32x16_bf16 v[16:31], v[104:107], v[108:111], v[16:31]
	s_add_u32 m0, s31, 0xe000
	v_lshl_add_u64 v[126:127], v[66:67], 0, s[24:25]
	global_load_lds_dwordx4 v[126:127], off
	v_mfma_f32_32x32x16_bf16 v[0:15], v[104:107], v[112:115], v[0:15]
	ds_read_b128 v[100:103], v117
	ds_read_b128 v[104:107], v117 offset:4096
	ds_read_b128 v[108:111], v121
	ds_read_b128 v[112:115], v121 offset:4096
	s_waitcnt lgkmcnt(4)
	v_mfma_f32_32x32x16_bf16 v[48:63], v[84:87], v[92:95], v[48:63]
	s_add_u32 m0, s31, 0x10000
	v_lshl_add_u64 v[124:125], v[68:69], 0, s[24:25]
	global_load_lds_dwordx4 v[124:125], off
	v_mfma_f32_32x32x16_bf16 v[32:47], v[84:87], v[96:99], v[32:47]
	v_mfma_f32_32x32x16_bf16 v[16:31], v[88:91], v[92:95], v[16:31]
	s_add_u32 m0, s31, 0x12000
	v_lshl_add_u64 v[126:127], v[70:71], 0, s[24:25]
	global_load_lds_dwordx4 v[126:127], off
	v_mfma_f32_32x32x16_bf16 v[0:15], v[88:91], v[96:99], v[0:15]
	ds_read_b128 v[84:87], v118
	ds_read_b128 v[88:91], v118 offset:4096
	ds_read_b128 v[92:95], v122
	ds_read_b128 v[96:99], v122 offset:4096
	s_waitcnt lgkmcnt(4)
	v_mfma_f32_32x32x16_bf16 v[48:63], v[100:103], v[108:111], v[48:63]
	s_add_u32 m0, s31, 0x14000
	v_lshl_add_u64 v[124:125], v[72:73], 0, s[24:25]
	global_load_lds_dwordx4 v[124:125], off
	v_mfma_f32_32x32x16_bf16 v[32:47], v[100:103], v[112:115], v[32:47]
	v_mfma_f32_32x32x16_bf16 v[16:31], v[104:107], v[108:111], v[16:31]
	s_add_u32 m0, s31, 0x16000
	v_lshl_add_u64 v[126:127], v[74:75], 0, s[24:25]
	global_load_lds_dwordx4 v[126:127], off
	v_mfma_f32_32x32x16_bf16 v[0:15], v[104:107], v[112:115], v[0:15]
	ds_read_b128 v[100:103], v119
	ds_read_b128 v[104:107], v119 offset:4096
	ds_read_b128 v[108:111], v123
	ds_read_b128 v[112:115], v123 offset:4096
	s_waitcnt lgkmcnt(4)
	v_mfma_f32_32x32x16_bf16 v[48:63], v[84:87], v[92:95], v[48:63]
	v_mfma_f32_32x32x16_bf16 v[32:47], v[84:87], v[96:99], v[32:47]
	v_mfma_f32_32x32x16_bf16 v[16:31], v[88:91], v[92:95], v[16:31]
	v_mfma_f32_32x32x16_bf16 v[0:15], v[88:91], v[96:99], v[0:15]
	s_waitcnt vmcnt(6) lgkmcnt(0)
	s_barrier
;     ...
;   for (int kt = 0; kt < nk; ++kt) {
;     if (kt + 1 < nk) asm volatile("s_waitcnt vmcnt(6)" ::: "memory");
;     else asm volatile("s_waitcnt vmcnt(0)" ::: "memory");
;     __builtin_amdgcn_s_barrier();
;     asm volatile("" ::: "memory");
;     if (kt + 2 < nk) { const int st2 = (st >= 1) ? st - 1 : 2; GEMM_ISSUE(kt + 2, st2); }
;     const char* la = lds + st * STAGE_B;
;     const char* lb = la + 32768;
;     const unsigned sa_u = (unsigned)(size_t)la + arow_u, sb_u = (unsigned)(size_t)lb + brow_u;
;     const unsigned a0 = sa_u + co0, a1 = sa_u + co1, a2 = sa_u + co2, a3 = sa_u + co3;
;     const unsigned b0 = sb_u + co0, b1 = sb_u + co1, b2 = sb_u + co2, b3 = sb_u + co3;
;     {
;       bf16x8 p0, p1, q0, q1, u0, u1, w0, w1;
;       asm volatile(
;         "ds_read_b128 %4, %12\n\tds_read_b128 %5, %12 offset:4096\n\tds_read_b128 %6, %16\n\tds_read_b128 %7, %16 offset:4096\n\t"
;         "ds_read_b128 %8, %13\n\tds_read_b128 %9, %13 offset:4096\n\tds_read_b128 %10, %17\n\tds_read_b128 %11, %17 offset:4096\n\t"
;         "s_waitcnt lgkmcnt(4)\n\t"
;         "v_mfma_f32_32x32x16_bf16 %0, %4, %6, %0\n\tv_mfma_f32_32x32x16_bf16 %1, %4, %7, %1\n\tv_mfma_f32_32x32x16_bf16 %2, %5, %6, %2\n\tv_mfma_f32_32x32x16_bf16 %3, %5, %7, %3\n\t"
;         "ds_read_b128 %4, %14\n\tds_read_b128 %5, %14 offset:4096\n\tds_read_b128 %6, %18\n\tds_read_b128 %7, %18 offset:4096\n\t"
;         "s_waitcnt lgkmcnt(4)\n\t"
;         "v_mfma_f32_32x32x16_bf16 %0, %8, %10, %0\n\tv_mfma_f32_32x32x16_bf16 %1, %8, %11, %1\n\tv_mfma_f32_32x32x16_bf16 %2, %9, %10, %2\n\tv_mfma_f32_32x32x16_bf16 %3, %9, %11, %3\n\t"
;         "ds_read_b128 %8, %15\n\tds_read_b128 %9, %15 offset:4096\n\tds_read_b128 %10, %19\n\tds_read_b128 %11, %19 offset:4096\n\t"
;         "s_waitcnt lgkmcnt(4)\n\t"
;         "v_mfma_f32_32x32x16_bf16 %0, %4, %6, %0\n\tv_mfma_f32_32x32x16_bf16 %1, %4, %7, %1\n\tv_mfma_f32_32x32x16_bf16 %2, %5, %6, %2\n\tv_mfma_f32_32x32x16_bf16 %3, %5, %7, %3\n\t"
;         "s_waitcnt lgkmcnt(0)\n\t"
;         "v_mfma_f32_32x32x16_bf16 %0, %8, %10, %0\n\tv_mfma_f32_32x32x16_bf16 %1, %8, %11, %1\n\tv_mfma_f32_32x32x16_bf16 %2, %9, %10, %2\n\tv_mfma_f32_32x32x16_bf16 %3, %9, %11, %3"
;         : "+v"(acc[0][0]), "+v"(acc[0][1]), "+v"(acc[1][0]), "+v"(acc[1][1]),
;           "=&v"(p0), "=&v"(p1), "=&v"(q0), "=&v"(q1), "=&v"(u0), "=&v"(u1), "=&v"(w0), "=&v"(w1)
	ds_read_b128 v[84:87], v76
	ds_read_b128 v[88:91], v76 offset:4096
	ds_read_b128 v[92:95], v80
	ds_read_b128 v[96:99], v80 offset:4096
	v_mfma_f32_32x32x16_bf16 v[48:63], v[100:103], v[108:111], v[48:63]
	s_add_u32 s24, s58, 0x0
	s_addc_u32 s25, s59, 0
	s_add_u32 m0, s31, 0x18000
	v_lshl_add_u64 v[124:125], v[64:65], 0, s[24:25]
	global_load_lds_dwordx4 v[124:125], off
	v_mfma_f32_32x32x16_bf16 v[32:47], v[100:103], v[112:115], v[32:47]
	v_mfma_f32_32x32x16_bf16 v[16:31], v[104:107], v[108:111], v[16:31]
	s_add_u32 m0, s31, 0x1a000
	v_lshl_add_u64 v[126:127], v[66:67], 0, s[24:25]
	global_load_lds_dwordx4 v[126:127], off
	v_mfma_f32_32x32x16_bf16 v[0:15], v[104:107], v[112:115], v[0:15]
	ds_read_b128 v[100:103], v77
	ds_read_b128 v[104:107], v77 offset:4096
	ds_read_b128 v[108:111], v81
	ds_read_b128 v[112:115], v81 offset:4096
	s_waitcnt lgkmcnt(4)
	v_mfma_f32_32x32x16_bf16 v[48:63], v[84:87], v[92:95], v[48:63]
	s_add_u32 m0, s31, 0x1c000
	v_lshl_add_u64 v[124:125], v[68:69], 0, s[24:25]
	global_load_lds_dwordx4 v[124:125], off
	v_mfma_f32_32x32x16_bf16 v[32:47], v[84:87], v[96:99], v[32:47]
	v_mfma_f32_32x32x16_bf16 v[16:31], v[88:91], v[92:95], v[16:31]
	s_add_u32 m0, s31, 0x1e000
	v_lshl_add_u64 v[126:127], v[70:71], 0, s[24:25]
	global_load_lds_dwordx4 v[126:127], off
	v_mfma_f32_32x32x16_bf16 v[0:15], v[88:91], v[96:99], v[0:15]
	ds_read_b128 v[84:87], v78
	ds_read_b128 v[88:91], v78 offset:4096
	ds_read_b128 v[92:95], v82
	ds_read_b128 v[96:99], v82 offset:4096
	s_waitcnt lgkmcnt(4)
	v_mfma_f32_32x32x16_bf16 v[48:63], v[100:103], v[108:111], v[48:63]
	s_add_u32 s24, s60, 0x0
	s_addc_u32 s25, s61, 0
	s_add_u32 m0, s31, 0x20000
	v_lshl_add_u64 v[124:125], v[72:73], 0, s[24:25]
	global_load_lds_dwordx4 v[124:125], off
	v_mfma_f32_32x32x16_bf16 v[32:47], v[100:103], v[112:115], v[32:47]
	v_mfma_f32_32x32x16_bf16 v[16:31], v[104:107], v[108:111], v[16:31]
	s_add_u32 m0, s31, 0x22000
	v_lshl_add_u64 v[126:127], v[74:75], 0, s[24:25]
	global_load_lds_dwordx4 v[126:127], off
	v_mfma_f32_32x32x16_bf16 v[0:15], v[104:107], v[112:115], v[0:15]
	ds_read_b128 v[100:103], v79
	ds_read_b128 v[104:107], v79 offset:4096
	ds_read_b128 v[108:111], v83
	ds_read_b128 v[112:115], v83 offset:4096
	s_waitcnt lgkmcnt(4)
	v_mfma_f32_32x32x16_bf16 v[48:63], v[84:87], v[92:95], v[48:63]
	v_mfma_f32_32x32x16_bf16 v[32:47], v[84:87], v[96:99], v[32:47]
	v_mfma_f32_32x32x16_bf16 v[16:31], v[88:91], v[92:95], v[16:31]
	v_mfma_f32_32x32x16_bf16 v[0:15], v[88:91], v[96:99], v[0:15]
	s_waitcnt vmcnt(6) lgkmcnt(0)
	s_barrier
	ds_read_b128 v[84:87], v76 offset:49152
	ds_read_b128 v[88:91], v76 offset:53248
	ds_read_b128 v[92:95], v80 offset:49152
	ds_read_b128 v[96:99], v80 offset:53248
	v_mfma_f32_32x32x16_bf16 v[48:63], v[100:103], v[108:111], v[48:63]
	s_add_u32 s24, s58, 0x80
	s_addc_u32 s25, s59, 0
	s_mov_b32 m0, s31
	v_lshl_add_u64 v[124:125], v[64:65], 0, s[24:25]
	global_load_lds_dwordx4 v[124:125], off
	v_mfma_f32_32x32x16_bf16 v[32:47], v[100:103], v[112:115], v[32:47]
	v_mfma_f32_32x32x16_bf16 v[16:31], v[104:107], v[108:111], v[16:31]
	s_add_u32 m0, s31, 0x2000
	v_lshl_add_u64 v[126:127], v[66:67], 0, s[24:25]
	global_load_lds_dwordx4 v[126:127], off
	v_mfma_f32_32x32x16_bf16 v[0:15], v[104:107], v[112:115], v[0:15]
	ds_read_b128 v[100:103], v77 offset:49152
	ds_read_b128 v[104:107], v77 offset:53248
	ds_read_b128 v[108:111], v81 offset:49152
	ds_read_b128 v[112:115], v81 offset:53248
	s_waitcnt lgkmcnt(4)
	v_mfma_f32_32x32x16_bf16 v[48:63], v[84:87], v[92:95], v[48:63]
	s_add_u32 m0, s31, 0x4000
	v_lshl_add_u64 v[124:125], v[68:69], 0, s[24:25]
	global_load_lds_dwordx4 v[124:125], off
	v_mfma_f32_32x32x16_bf16 v[32:47], v[84:87], v[96:99], v[32:47]
	v_mfma_f32_32x32x16_bf16 v[16:31], v[88:91], v[92:95], v[16:31]
	s_add_u32 m0, s31, 0x6000
	v_lshl_add_u64 v[126:127], v[70:71], 0, s[24:25]
	global_load_lds_dwordx4 v[126:127], off
	v_mfma_f32_32x32x16_bf16 v[0:15], v[88:91], v[96:99], v[0:15]
	ds_read_b128 v[84:87], v78 offset:49152
	ds_read_b128 v[88:91], v78 offset:53248
	ds_read_b128 v[92:95], v82 offset:49152
	ds_read_b128 v[96:99], v82 offset:53248
	s_waitcnt lgkmcnt(4)
	v_mfma_f32_32x32x16_bf16 v[48:63], v[100:103], v[108:111], v[48:63]
	s_add_u32 s24, s60, 0x80
	s_addc_u32 s25, s61, 0
	s_add_u32 m0, s31, 0x8000
	v_lshl_add_u64 v[124:125], v[72:73], 0, s[24:25]
	global_load_lds_dwordx4 v[124:125], off
	v_mfma_f32_32x32x16_bf16 v[32:47], v[100:103], v[112:115], v[32:47]
	v_mfma_f32_32x32x16_bf16 v[16:31], v[104:107], v[108:111], v[16:31]
	s_add_u32 m0, s31, 0xa000
	v_lshl_add_u64 v[126:127], v[74:75], 0, s[24:25]
	global_load_lds_dwordx4 v[126:127], off
	v_mfma_f32_32x32x16_bf16 v[0:15], v[104:107], v[112:115], v[0:15]
	ds_read_b128 v[100:103], v79 offset:49152
	ds_read_b128 v[104:107], v79 offset:53248
	ds_read_b128 v[108:111], v83 offset:49152
	ds_read_b128 v[112:115], v83 offset:53248
	s_waitcnt lgkmcnt(4)
	v_mfma_f32_32x32x16_bf16 v[48:63], v[84:87], v[92:95], v[48:63]
	v_mfma_f32_32x32x16_bf16 v[32:47], v[84:87], v[96:99], v[32:47]
	v_mfma_f32_32x32x16_bf16 v[16:31], v[88:91], v[92:95], v[16:31]
	v_mfma_f32_32x32x16_bf16 v[0:15], v[88:91], v[96:99], v[0:15]
	s_waitcnt lgkmcnt(0)
	v_mfma_f32_32x32x16_bf16 v[48:63], v[100:103], v[108:111], v[48:63]
	v_mfma_f32_32x32x16_bf16 v[32:47], v[100:103], v[112:115], v[32:47]
	v_mfma_f32_32x32x16_bf16 v[16:31], v[104:107], v[108:111], v[16:31]
	v_mfma_f32_32x32x16_bf16 v[0:15], v[104:107], v[112:115], v[0:15]
	s_branch .Lx3_done
;     ...
;   for (int kt = 0; kt < nk; ++kt) {
;     if (kt + 1 < nk) asm volatile("s_waitcnt vmcnt(6)" ::: "memory");
;     else asm volatile("s_waitcnt vmcnt(0)" ::: "memory");
;     __builtin_amdgcn_s_barrier();
;     asm volatile("" ::: "memory");
;     if (kt + 2 < nk) { const int st2 = (st >= 1) ? st - 1 : 2; GEMM_ISSUE(kt + 2, st2); }
;     const char* la = lds + st * STAGE_B;
;     const char* lb = la + 32768;
;     const unsigned sa_u = (unsigned)(size_t)la + arow_u, sb_u = (unsigned)(size_t)lb + brow_u;
;     const unsigned a0 = sa_u + co0, a1 = sa_u + co1, a2 = sa_u + co2, a3 = sa_u + co3;
;     const unsigned b0 = sb_u + co0, b1 = sb_u + co1, b2 = sb_u + co2, b3 = sb_u + co3;
;     {
;       bf16x8 p0, p1, q0, q1, u0, u1, w0, w1;
;       asm volatile(
;         "ds_read_b128 %4, %12\n\tds_read_b128 %5, %12 offset:4096\n\tds_read_b128 %6, %16\n\tds_read_b128 %7, %16 offset:4096\n\t"
;         "ds_read_b128 %8, %13\n\tds_read_b128 %9, %13 offset:4096\n\tds_read_b128 %10, %17\n\tds_read_b128 %11, %17 offset:4096\n\t"
;         "s_waitcnt lgkmcnt(4)\n\t"
;         "v_mfma_f32_32x32x16_bf16 %0, %4, %6, %0\n\tv_mfma_f32_32x32x16_bf16 %1, %4, %7, %1\n\tv_mfma_f32_32x32x16_bf16 %2, %5, %6, %2\n\tv_mfma_f32_32x32x16_bf16 %3, %5, %7, %3\n\t"
;         "ds_read_b128 %4, %14\n\tds_read_b128 %5, %14 offset:4096\n\tds_read_b128 %6, %18\n\tds_read_b128 %7, %18 offset:4096\n\t"
;         "s_waitcnt lgkmcnt(4)\n\t"
;         "v_mfma_f32_32x32x16_bf16 %0, %8, %10, %0\n\tv_mfma_f32_32x32x16_bf16 %1, %8, %11, %1\n\tv_mfma_f32_32x32x16_bf16 %2, %9, %10, %2\n\tv_mfma_f32_32x32x16_bf16 %3, %9, %11, %3\n\t"
;         "ds_read_b128 %8, %15\n\tds_read_b128 %9, %15 offset:4096\n\tds_read_b128 %10, %19\n\tds_read_b128 %11, %19 offset:4096\n\t"
;         "s_waitcnt lgkmcnt(4)\n\t"
;         "v_mfma_f32_32x32x16_bf16 %0, %4, %6, %0\n\tv_mfma_f32_32x32x16_bf16 %1, %4, %7, %1\n\tv_mfma_f32_32x32x16_bf16 %2, %5, %6, %2\n\tv_mfma_f32_32x32x16_bf16 %3, %5, %7, %3\n\t"
;         "s_waitcnt lgkmcnt(0)\n\t"
;         "v_mfma_f32_32x32x16_bf16 %0, %8, %10, %0\n\tv_mfma_f32_32x32x16_bf16 %1, %8, %11, %1\n\tv_mfma_f32_32x32x16_bf16 %2, %9, %10, %2\n\tv_mfma_f32_32x32x16_bf16 %3, %9, %11, %3"
;         : "+v"(acc[0][0]), "+v"(acc[0][1]), "+v"(acc[1][0]), "+v"(acc[1][1]),
;           "=&v"(p0), "=&v"(p1), "=&v"(q0), "=&v"(q1), "=&v"(u0), "=&v"(u1), "=&v"(w0), "=&v"(w1)
.Lx3_v2:
	ds_read_b128 v[84:87], v116
	ds_read_b128 v[88:91], v116 offset:4096
	ds_read_b128 v[92:95], v120
	ds_read_b128 v[96:99], v120 offset:4096
	s_mov_b32 s24, 0x100
	s_mov_b32 s25, 0
	s_add_u32 m0, s31, 0xc000
	v_lshl_add_u64 v[124:125], v[64:65], 0, s[24:25]
	global_load_lds_dwordx4 v[124:125], off
	s_add_u32 m0, s31, 0xe000
	v_lshl_add_u64 v[126:127], v[66:67], 0, s[24:25]
	global_load_lds_dwordx4 v[126:127], off
	ds_read_b128 v[100:103], v117
	ds_read_b128 v[104:107], v117 offset:4096
	ds_read_b128 v[108:111], v121
	ds_read_b128 v[112:115], v121 offset:4096
	s_waitcnt lgkmcnt(4)
	v_mfma_f32_32x32x16_bf16 v[48:63], v[84:87], v[92:95], v[48:63]
	s_add_u32 m0, s31, 0x10000
	v_lshl_add_u64 v[124:125], v[68:69], 0, s[24:25]
	global_load_lds_dwordx4 v[124:125], off
	v_mfma_f32_32x32x16_bf16 v[32:47], v[84:87], v[96:99], v[32:47]
	v_mfma_f32_32x32x16_bf16 v[16:31], v[88:91], v[92:95], v[16:31]
	s_add_u32 m0, s31, 0x12000
	v_lshl_add_u64 v[126:127], v[70:71], 0, s[24:25]
	global_load_lds_dwordx4 v[126:127], off
	v_mfma_f32_32x32x16_bf16 v[0:15], v[88:91], v[96:99], v[0:15]
	ds_read_b128 v[84:87], v118
	ds_read_b128 v[88:91], v118 offset:4096
	ds_read_b128 v[92:95], v122
	ds_read_b128 v[96:99], v122 offset:4096
	s_waitcnt lgkmcnt(4)
	v_mfma_f32_32x32x16_bf16 v[48:63], v[100:103], v[108:111], v[48:63]
	s_add_u32 m0, s31, 0x14000
	v_lshl_add_u64 v[124:125], v[72:73], 0, s[24:25]
	global_load_lds_dwordx4 v[124:125], off
	v_mfma_f32_32x32x16_bf16 v[32:47], v[100:103], v[112:115], v[32:47]
	v_mfma_f32_32x32x16_bf16 v[16:31], v[104:107], v[108:111], v[16:31]
	s_add_u32 m0, s31, 0x16000
	v_lshl_add_u64 v[126:127], v[74:75], 0, s[24:25]
	global_load_lds_dwordx4 v[126:127], off
	v_mfma_f32_32x32x16_bf16 v[0:15], v[104:107], v[112:115], v[0:15]
	ds_read_b128 v[100:103], v119
	ds_read_b128 v[104:107], v119 offset:4096
	ds_read_b128 v[108:111], v123
	ds_read_b128 v[112:115], v123 offset:4096
	s_waitcnt lgkmcnt(4)
	v_mfma_f32_32x32x16_bf16 v[48:63], v[84:87], v[92:95], v[48:63]
	v_mfma_f32_32x32x16_bf16 v[32:47], v[84:87], v[96:99], v[32:47]
	v_mfma_f32_32x32x16_bf16 v[16:31], v[88:91], v[92:95], v[16:31]
	v_mfma_f32_32x32x16_bf16 v[0:15], v[88:91], v[96:99], v[0:15]
	s_waitcnt vmcnt(6) lgkmcnt(0)
	s_barrier
	ds_read_b128 v[84:87], v76
	ds_read_b128 v[88:91], v76 offset:4096
	ds_read_b128 v[92:95], v80
	ds_read_b128 v[96:99], v80 offset:4096
	v_mfma_f32_32x32x16_bf16 v[48:63], v[100:103], v[108:111], v[48:63]
	s_mov_b32 s24, 0x180
	s_mov_b32 s25, 0
	s_add_u32 m0, s31, 0x18000
	v_lshl_add_u64 v[124:125], v[64:65], 0, s[24:25]
	global_load_lds_dwordx4 v[124:125], off
	v_mfma_f32_32x32x16_bf16 v[32:47], v[100:103], v[112:115], v[32:47]
	v_mfma_f32_32x32x16_bf16 v[16:31], v[104:107], v[108:111], v[16:31]
	s_add_u32 m0, s31, 0x1a000
	v_lshl_add_u64 v[126:127], v[66:67], 0, s[24:25]
	global_load_lds_dwordx4 v[126:127], off
	v_mfma_f32_32x32x16_bf16 v[0:15], v[104:107], v[112:115], v[0:15]
	ds_read_b128 v[100:103], v77
	ds_read_b128 v[104:107], v77 offset:4096
	ds_read_b128 v[108:111], v81
	ds_read_b128 v[112:115], v81 offset:4096
	s_waitcnt lgkmcnt(4)
	v_mfma_f32_32x32x16_bf16 v[48:63], v[84:87], v[92:95], v[48:63]
	s_add_u32 m0, s31, 0x1c000
	v_lshl_add_u64 v[124:125], v[68:69], 0, s[24:25]
	global_load_lds_dwordx4 v[124:125], off
	v_mfma_f32_32x32x16_bf16 v[32:47], v[84:87], v[96:99], v[32:47]
	v_mfma_f32_32x32x16_bf16 v[16:31], v[88:91], v[92:95], v[16:31]
	s_add_u32 m0, s31, 0x1e000
	v_lshl_add_u64 v[126:127], v[70:71], 0, s[24:25]
	global_load_lds_dwordx4 v[126:127], off
	v_mfma_f32_32x32x16_bf16 v[0:15], v[88:91], v[96:99], v[0:15]
	ds_read_b128 v[84:87], v78
	ds_read_b128 v[88:91], v78 offset:4096
	ds_read_b128 v[92:95], v82
	ds_read_b128 v[96:99], v82 offset:4096
	s_waitcnt lgkmcnt(4)
	v_mfma_f32_32x32x16_bf16 v[48:63], v[100:103], v[108:111], v[48:63]
	s_add_u32 m0, s31, 0x20000
	v_lshl_add_u64 v[124:125], v[72:73], 0, s[24:25]
	global_load_lds_dwordx4 v[124:125], off
	v_mfma_f32_32x32x16_bf16 v[32:47], v[100:103], v[112:115], v[32:47]
	v_mfma_f32_32x32x16_bf16 v[16:31], v[104:107], v[108:111], v[16:31]
	s_add_u32 m0, s31, 0x22000
	v_lshl_add_u64 v[126:127], v[74:75], 0, s[24:25]
	global_load_lds_dwordx4 v[126:127], off
	v_mfma_f32_32x32x16_bf16 v[0:15], v[104:107], v[112:115], v[0:15]
	ds_read_b128 v[100:103], v79
	ds_read_b128 v[104:107], v79 offset:4096
	ds_read_b128 v[108:111], v83
	ds_read_b128 v[112:115], v83 offset:4096
	s_waitcnt lgkmcnt(4)
	v_mfma_f32_32x32x16_bf16 v[48:63], v[84:87], v[92:95], v[48:63]
	v_mfma_f32_32x32x16_bf16 v[32:47], v[84:87], v[96:99], v[32:47]
	v_mfma_f32_32x32x16_bf16 v[16:31], v[88:91], v[92:95], v[16:31]
	v_mfma_f32_32x32x16_bf16 v[0:15], v[88:91], v[96:99], v[0:15]
	s_waitcnt vmcnt(6) lgkmcnt(0)
	s_barrier
;     ...
;   for (int kt = 0; kt < nk; ++kt) {
;     if (kt + 1 < nk) asm volatile("s_waitcnt vmcnt(6)" ::: "memory");
;     else asm volatile("s_waitcnt vmcnt(0)" ::: "memory");
;     __builtin_amdgcn_s_barrier();
;     asm volatile("" ::: "memory");
;     if (kt + 2 < nk) { const int st2 = (st >= 1) ? st - 1 : 2; GEMM_ISSUE(kt + 2, st2); }
;     const char* la = lds + st * STAGE_B;
;     const char* lb = la + 32768;
;     const unsigned sa_u = (unsigned)(size_t)la + arow_u, sb_u = (unsigned)(size_t)lb + brow_u;
;     const unsigned a0 = sa_u + co0, a1 = sa_u + co1, a2 = sa_u + co2, a3 = sa_u + co3;
;     const unsigned b0 = sb_u + co0, b1 = sb_u + co1, b2 = sb_u + co2, b3 = sb_u + co3;
;     {
;       bf16x8 p0, p1, q0, q1, u0, u1, w0, w1;
;       asm volatile(
;         "ds_read_b128 %4, %12\n\tds_read_b128 %5, %12 offset:4096\n\tds_read_b128 %6, %16\n\tds_read_b128 %7, %16 offset:4096\n\t"
;         "ds_read_b128 %8, %13\n\tds_read_b128 %9, %13 offset:4096\n\tds_read_b128 %10, %17\n\tds_read_b128 %11, %17 offset:4096\n\t"
;         "s_waitcnt lgkmcnt(4)\n\t"
;         "v_mfma_f32_32x32x16_bf16 %0, %4, %6, %0\n\tv_mfma_f32_32x32x16_bf16 %1, %4, %7, %1\n\tv_mfma_f32_32x32x16_bf16 %2, %5, %6, %2\n\tv_mfma_f32_32x32x16_bf16 %3, %5, %7, %3\n\t"
;         "ds_read_b128 %4, %14\n\tds_read_b128 %5, %14 offset:4096\n\tds_read_b128 %6, %18\n\tds_read_b128 %7, %18 offset:4096\n\t"
;         "s_waitcnt lgkmcnt(4)\n\t"
;         "v_mfma_f32_32x32x16_bf16 %0, %8, %10, %0\n\tv_mfma_f32_32x32x16_bf16 %1, %8, %11, %1\n\tv_mfma_f32_32x32x16_bf16 %2, %9, %10, %2\n\tv_mfma_f32_32x32x16_bf16 %3, %9, %11, %3\n\t"
;         "ds_read_b128 %8, %15\n\tds_read_b128 %9, %15 offset:4096\n\tds_read_b128 %10, %19\n\tds_read_b128 %11, %19 offset:4096\n\t"
;         "s_waitcnt lgkmcnt(4)\n\t"
;         "v_mfma_f32_32x32x16_bf16 %0, %4, %6, %0\n\tv_mfma_f32_32x32x16_bf16 %1, %4, %7, %1\n\tv_mfma_f32_32x32x16_bf16 %2, %5, %6, %2\n\tv_mfma_f32_32x32x16_bf16 %3, %5, %7, %3\n\t"
;         "s_waitcnt lgkmcnt(0)\n\t"
;         "v_mfma_f32_32x32x16_bf16 %0, %8, %10, %0\n\tv_mfma_f32_32x32x16_bf16 %1, %8, %11, %1\n\tv_mfma_f32_32x32x16_bf16 %2, %9, %10, %2\n\tv_mfma_f32_32x32x16_bf16 %3, %9, %11, %3"
;         : "+v"(acc[0][0]), "+v"(acc[0][1]), "+v"(acc[1][0]), "+v"(acc[1][1]),
;           "=&v"(p0), "=&v"(p1), "=&v"(q0), "=&v"(q1), "=&v"(u0), "=&v"(u1), "=&v"(w0), "=&v"(w1)
	ds_read_b128 v[84:87], v76 offset:49152
	ds_read_b128 v[88:91], v76 offset:53248
	ds_read_b128 v[92:95], v80 offset:49152
	ds_read_b128 v[96:99], v80 offset:53248
	v_mfma_f32_32x32x16_bf16 v[48:63], v[100:103], v[108:111], v[48:63]
	s_mov_b32 s24, 0x200
	s_mov_b32 s25, 0
	s_mov_b32 m0, s31
	v_lshl_add_u64 v[124:125], v[64:65], 0, s[24:25]
	global_load_lds_dwordx4 v[124:125], off
	v_mfma_f32_32x32x16_bf16 v[32:47], v[100:103], v[112:115], v[32:47]
	v_mfma_f32_32x32x16_bf16 v[16:31], v[104:107], v[108:111], v[16:31]
	s_add_u32 m0, s31, 0x2000
	v_lshl_add_u64 v[126:127], v[66:67], 0, s[24:25]
	global_load_lds_dwordx4 v[126:127], off
	v_mfma_f32_32x32x16_bf16 v[0:15], v[104:107], v[112:115], v[0:15]
	ds_read_b128 v[100:103], v77 offset:49152
	ds_read_b128 v[104:107], v77 offset:53248
	ds_read_b128 v[108:111], v81 offset:49152
	ds_read_b128 v[112:115], v81 offset:53248
	s_waitcnt lgkmcnt(4)
	v_mfma_f32_32x32x16_bf16 v[48:63], v[84:87], v[92:95], v[48:63]
	s_add_u32 m0, s31, 0x4000
	v_lshl_add_u64 v[124:125], v[68:69], 0, s[24:25]
	global_load_lds_dwordx4 v[124:125], off
	v_mfma_f32_32x32x16_bf16 v[32:47], v[84:87], v[96:99], v[32:47]
	v_mfma_f32_32x32x16_bf16 v[16:31], v[88:91], v[92:95], v[16:31]
	s_add_u32 m0, s31, 0x6000
	v_lshl_add_u64 v[126:127], v[70:71], 0, s[24:25]
	global_load_lds_dwordx4 v[126:127], off
	v_mfma_f32_32x32x16_bf16 v[0:15], v[88:91], v[96:99], v[0:15]
	ds_read_b128 v[84:87], v78 offset:49152
	ds_read_b128 v[88:91], v78 offset:53248
	ds_read_b128 v[92:95], v82 offset:49152
	ds_read_b128 v[96:99], v82 offset:53248
	s_waitcnt lgkmcnt(4)
	v_mfma_f32_32x32x16_bf16 v[48:63], v[100:103], v[108:111], v[48:63]
	s_add_u32 m0, s31, 0x8000
	v_lshl_add_u64 v[124:125], v[72:73], 0, s[24:25]
	global_load_lds_dwordx4 v[124:125], off
	v_mfma_f32_32x32x16_bf16 v[32:47], v[100:103], v[112:115], v[32:47]
	v_mfma_f32_32x32x16_bf16 v[16:31], v[104:107], v[108:111], v[16:31]
	s_add_u32 m0, s31, 0xa000
	v_lshl_add_u64 v[126:127], v[74:75], 0, s[24:25]
	global_load_lds_dwordx4 v[126:127], off
	v_mfma_f32_32x32x16_bf16 v[0:15], v[104:107], v[112:115], v[0:15]
	ds_read_b128 v[100:103], v79 offset:49152
	ds_read_b128 v[104:107], v79 offset:53248
	ds_read_b128 v[108:111], v83 offset:49152
	ds_read_b128 v[112:115], v83 offset:53248
	s_waitcnt lgkmcnt(4)
	v_mfma_f32_32x32x16_bf16 v[48:63], v[84:87], v[92:95], v[48:63]
	v_mfma_f32_32x32x16_bf16 v[32:47], v[84:87], v[96:99], v[32:47]
	v_mfma_f32_32x32x16_bf16 v[16:31], v[88:91], v[92:95], v[16:31]
	v_mfma_f32_32x32x16_bf16 v[0:15], v[88:91], v[96:99], v[0:15]
	s_waitcnt vmcnt(6) lgkmcnt(0)
	s_barrier
	ds_read_b128 v[84:87], v116
	ds_read_b128 v[88:91], v116 offset:4096
	ds_read_b128 v[92:95], v120
	ds_read_b128 v[96:99], v120 offset:4096
	v_mfma_f32_32x32x16_bf16 v[48:63], v[100:103], v[108:111], v[48:63]
	s_mov_b32 s24, 0x280
	s_mov_b32 s25, 0
	s_add_u32 m0, s31, 0xc000
	v_lshl_add_u64 v[124:125], v[64:65], 0, s[24:25]
	global_load_lds_dwordx4 v[124:125], off
	v_mfma_f32_32x32x16_bf16 v[32:47], v[100:103], v[112:115], v[32:47]
	v_mfma_f32_32x32x16_bf16 v[16:31], v[104:107], v[108:111], v[16:31]
	s_add_u32 m0, s31, 0xe000
	v_lshl_add_u64 v[126:127], v[66:67], 0, s[24:25]
	global_load_lds_dwordx4 v[126:127], off
	v_mfma_f32_32x32x16_bf16 v[0:15], v[104:107], v[112:115], v[0:15]
	ds_read_b128 v[100:103], v117
	ds_read_b128 v[104:107], v117 offset:4096
	ds_read_b128 v[108:111], v121
	ds_read_b128 v[112:115], v121 offset:4096
	s_waitcnt lgkmcnt(4)
	v_mfma_f32_32x32x16_bf16 v[48:63], v[84:87], v[92:95], v[48:63]
	s_add_u32 m0, s31, 0x10000
	v_lshl_add_u64 v[124:125], v[68:69], 0, s[24:25]
	global_load_lds_dwordx4 v[124:125], off
	v_mfma_f32_32x32x16_bf16 v[32:47], v[84:87], v[96:99], v[32:47]
	v_mfma_f32_32x32x16_bf16 v[16:31], v[88:91], v[92:95], v[16:31]
	s_add_u32 m0, s31, 0x12000
	v_lshl_add_u64 v[126:127], v[70:71], 0, s[24:25]
	global_load_lds_dwordx4 v[126:127], off
	v_mfma_f32_32x32x16_bf16 v[0:15], v[88:91], v[96:99], v[0:15]
	ds_read_b128 v[84:87], v118
	ds_read_b128 v[88:91], v118 offset:4096
	ds_read_b128 v[92:95], v122
	ds_read_b128 v[96:99], v122 offset:4096
	s_waitcnt lgkmcnt(4)
	v_mfma_f32_32x32x16_bf16 v[48:63], v[100:103], v[108:111], v[48:63]
	s_add_u32 m0, s31, 0x14000
	v_lshl_add_u64 v[124:125], v[72:73], 0, s[24:25]
	global_load_lds_dwordx4 v[124:125], off
	v_mfma_f32_32x32x16_bf16 v[32:47], v[100:103], v[112:115], v[32:47]
	v_mfma_f32_32x32x16_bf16 v[16:31], v[104:107], v[108:111], v[16:31]
	s_add_u32 m0, s31, 0x16000
	v_lshl_add_u64 v[126:127], v[74:75], 0, s[24:25]
	global_load_lds_dwordx4 v[126:127], off
	v_mfma_f32_32x32x16_bf16 v[0:15], v[104:107], v[112:115], v[0:15]
	ds_read_b128 v[100:103], v119
	ds_read_b128 v[104:107], v119 offset:4096
	ds_read_b128 v[108:111], v123
	ds_read_b128 v[112:115], v123 offset:4096
	s_waitcnt lgkmcnt(4)
	v_mfma_f32_32x32x16_bf16 v[48:63], v[84:87], v[92:95], v[48:63]
	v_mfma_f32_32x32x16_bf16 v[32:47], v[84:87], v[96:99], v[32:47]
	v_mfma_f32_32x32x16_bf16 v[16:31], v[88:91], v[92:95], v[16:31]
	v_mfma_f32_32x32x16_bf16 v[0:15], v[88:91], v[96:99], v[0:15]
	s_waitcnt vmcnt(6) lgkmcnt(0)
	s_barrier
;     ...
;   for (int kt = 0; kt < nk; ++kt) {
;     if (kt + 1 < nk) asm volatile("s_waitcnt vmcnt(6)" ::: "memory");
;     else asm volatile("s_waitcnt vmcnt(0)" ::: "memory");
;     __builtin_amdgcn_s_barrier();
;     asm volatile("" ::: "memory");
;     if (kt + 2 < nk) { const int st2 = (st >= 1) ? st - 1 : 2; GEMM_ISSUE(kt + 2, st2); }
;     const char* la = lds + st * STAGE_B;
;     const char* lb = la + 32768;
;     const unsigned sa_u = (unsigned)(size_t)la + arow_u, sb_u = (unsigned)(size_t)lb + brow_u;
;     const unsigned a0 = sa_u + co0, a1 = sa_u + co1, a2 = sa_u + co2, a3 = sa_u + co3;
;     const unsigned b0 = sb_u + co0, b1 = sb_u + co1, b2 = sb_u + co2, b3 = sb_u + co3;
;     {
;       bf16x8 p0, p1, q0, q1, u0, u1, w0, w1;
;       asm volatile(
;         "ds_read_b128 %4, %12\n\tds_read_b128 %5, %12 offset:4096\n\tds_read_b128 %6, %16\n\tds_read_b128 %7, %16 offset:4096\n\t"
;         "ds_read_b128 %8, %13\n\tds_read_b128 %9, %13 offset:4096\n\tds_read_b128 %10, %17\n\tds_read_b128 %11, %17 offset:4096\n\t"
;         "s_waitcnt lgkmcnt(4)\n\t"
;         "v_mfma_f32_32x32x16_bf16 %0, %4, %6, %0\n\tv_mfma_f32_32x32x16_bf16 %1, %4, %7, %1\n\tv_mfma_f32_32x32x16_bf16 %2, %5, %6, %2\n\tv_mfma_f32_32x32x16_bf16 %3, %5, %7, %3\n\t"
;         "ds_read_b128 %4, %14\n\tds_read_b128 %5, %14 offset:4096\n\tds_read_b128 %6, %18\n\tds_read_b128 %7, %18 offset:4096\n\t"
;         "s_waitcnt lgkmcnt(4)\n\t"
;         "v_mfma_f32_32x32x16_bf16 %0, %8, %10, %0\n\tv_mfma_f32_32x32x16_bf16 %1, %8, %11, %1\n\tv_mfma_f32_32x32x16_bf16 %2, %9, %10, %2\n\tv_mfma_f32_32x32x16_bf16 %3, %9, %11, %3\n\t"
;         "ds_read_b128 %8, %15\n\tds_read_b128 %9, %15 offset:4096\n\tds_read_b128 %10, %19\n\tds_read_b128 %11, %19 offset:4096\n\t"
;         "s_waitcnt lgkmcnt(4)\n\t"
;         "v_mfma_f32_32x32x16_bf16 %0, %4, %6, %0\n\tv_mfma_f32_32x32x16_bf16 %1, %4, %7, %1\n\tv_mfma_f32_32x32x16_bf16 %2, %5, %6, %2\n\tv_mfma_f32_32x32x16_bf16 %3, %5, %7, %3\n\t"
;         "s_waitcnt lgkmcnt(0)\n\t"
;         "v_mfma_f32_32x32x16_bf16 %0, %8, %10, %0\n\tv_mfma_f32_32x32x16_bf16 %1, %8, %11, %1\n\tv_mfma_f32_32x32x16_bf16 %2, %9, %10, %2\n\tv_mfma_f32_32x32x16_bf16 %3, %9, %11, %3"
;         : "+v"(acc[0][0]), "+v"(acc[0][1]), "+v"(acc[1][0]), "+v"(acc[1][1]),
;           "=&v"(p0), "=&v"(p1), "=&v"(q0), "=&v"(q1), "=&v"(u0), "=&v"(u1), "=&v"(w0), "=&v"(w1)
	ds_read_b128 v[84:87], v76
	ds_read_b128 v[88:91], v76 offset:4096
	ds_read_b128 v[92:95], v80
	ds_read_b128 v[96:99], v80 offset:4096
	v_mfma_f32_32x32x16_bf16 v[48:63], v[100:103], v[108:111], v[48:63]
	s_mov_b32 s24, 0x300
	s_mov_b32 s25, 0
	s_add_u32 m0, s31, 0x18000
	v_lshl_add_u64 v[124:125], v[64:65], 0, s[24:25]
	global_load_lds_dwordx4 v[124:125], off
	v_mfma_f32_32x32x16_bf16 v[32:47], v[100:103], v[112:115], v[32:47]
	v_mfma_f32_32x32x16_bf16 v[16:31], v[104:107], v[108:111], v[16:31]
	s_add_u32 m0, s31, 0x1a000
	v_lshl_add_u64 v[126:127], v[66:67], 0, s[24:25]
	global_load_lds_dwordx4 v[126:127], off
	v_mfma_f32_32x32x16_bf16 v[0:15], v[104:107], v[112:115], v[0:15]
	ds_read_b128 v[100:103], v77
	ds_read_b128 v[104:107], v77 offset:4096
	ds_read_b128 v[108:111], v81
	ds_read_b128 v[112:115], v81 offset:4096
	s_waitcnt lgkmcnt(4)
	v_mfma_f32_32x32x16_bf16 v[48:63], v[84:87], v[92:95], v[48:63]
	s_add_u32 m0, s31, 0x1c000
	v_lshl_add_u64 v[124:125], v[68:69], 0, s[24:25]
	global_load_lds_dwordx4 v[124:125], off
	v_mfma_f32_32x32x16_bf16 v[32:47], v[84:87], v[96:99], v[32:47]
	v_mfma_f32_32x32x16_bf16 v[16:31], v[88:91], v[92:95], v[16:31]
	s_add_u32 m0, s31, 0x1e000
	v_lshl_add_u64 v[126:127], v[70:71], 0, s[24:25]
	global_load_lds_dwordx4 v[126:127], off
	v_mfma_f32_32x32x16_bf16 v[0:15], v[88:91], v[96:99], v[0:15]
	ds_read_b128 v[84:87], v78
	ds_read_b128 v[88:91], v78 offset:4096
	ds_read_b128 v[92:95], v82
	ds_read_b128 v[96:99], v82 offset:4096
	s_waitcnt lgkmcnt(4)
	v_mfma_f32_32x32x16_bf16 v[48:63], v[100:103], v[108:111], v[48:63]
	s_add_u32 m0, s31, 0x20000
	v_lshl_add_u64 v[124:125], v[72:73], 0, s[24:25]
	global_load_lds_dwordx4 v[124:125], off
	v_mfma_f32_32x32x16_bf16 v[32:47], v[100:103], v[112:115], v[32:47]
	v_mfma_f32_32x32x16_bf16 v[16:31], v[104:107], v[108:111], v[16:31]
	s_add_u32 m0, s31, 0x22000
	v_lshl_add_u64 v[126:127], v[74:75], 0, s[24:25]
	global_load_lds_dwordx4 v[126:127], off
	v_mfma_f32_32x32x16_bf16 v[0:15], v[104:107], v[112:115], v[0:15]
	ds_read_b128 v[100:103], v79
	ds_read_b128 v[104:107], v79 offset:4096
	ds_read_b128 v[108:111], v83
	ds_read_b128 v[112:115], v83 offset:4096
	s_waitcnt lgkmcnt(4)
	v_mfma_f32_32x32x16_bf16 v[48:63], v[84:87], v[92:95], v[48:63]
	v_mfma_f32_32x32x16_bf16 v[32:47], v[84:87], v[96:99], v[32:47]
	v_mfma_f32_32x32x16_bf16 v[16:31], v[88:91], v[92:95], v[16:31]
	v_mfma_f32_32x32x16_bf16 v[0:15], v[88:91], v[96:99], v[0:15]
	s_waitcnt vmcnt(6) lgkmcnt(0)
	s_barrier
	ds_read_b128 v[84:87], v76 offset:49152
	ds_read_b128 v[88:91], v76 offset:53248
	ds_read_b128 v[92:95], v80 offset:49152
	ds_read_b128 v[96:99], v80 offset:53248
	v_mfma_f32_32x32x16_bf16 v[48:63], v[100:103], v[108:111], v[48:63]
	s_mov_b32 s24, 0x380
	s_mov_b32 s25, 0
	s_mov_b32 m0, s31
	v_lshl_add_u64 v[124:125], v[64:65], 0, s[24:25]
	global_load_lds_dwordx4 v[124:125], off
	v_mfma_f32_32x32x16_bf16 v[32:47], v[100:103], v[112:115], v[32:47]
	v_mfma_f32_32x32x16_bf16 v[16:31], v[104:107], v[108:111], v[16:31]
	s_add_u32 m0, s31, 0x2000
	v_lshl_add_u64 v[126:127], v[66:67], 0, s[24:25]
	global_load_lds_dwordx4 v[126:127], off
	v_mfma_f32_32x32x16_bf16 v[0:15], v[104:107], v[112:115], v[0:15]
	ds_read_b128 v[100:103], v77 offset:49152
	ds_read_b128 v[104:107], v77 offset:53248
	ds_read_b128 v[108:111], v81 offset:49152
	ds_read_b128 v[112:115], v81 offset:53248
	s_waitcnt lgkmcnt(4)
	v_mfma_f32_32x32x16_bf16 v[48:63], v[84:87], v[92:95], v[48:63]
	s_add_u32 m0, s31, 0x4000
	v_lshl_add_u64 v[124:125], v[68:69], 0, s[24:25]
	global_load_lds_dwordx4 v[124:125], off
	v_mfma_f32_32x32x16_bf16 v[32:47], v[84:87], v[96:99], v[32:47]
	v_mfma_f32_32x32x16_bf16 v[16:31], v[88:91], v[92:95], v[16:31]
	s_add_u32 m0, s31, 0x6000
	v_lshl_add_u64 v[126:127], v[70:71], 0, s[24:25]
	global_load_lds_dwordx4 v[126:127], off
	v_mfma_f32_32x32x16_bf16 v[0:15], v[88:91], v[96:99], v[0:15]
	ds_read_b128 v[84:87], v78 offset:49152
	ds_read_b128 v[88:91], v78 offset:53248
	ds_read_b128 v[92:95], v82 offset:49152
	ds_read_b128 v[96:99], v82 offset:53248
	s_waitcnt lgkmcnt(4)
	v_mfma_f32_32x32x16_bf16 v[48:63], v[100:103], v[108:111], v[48:63]
	s_add_u32 m0, s31, 0x8000
	v_lshl_add_u64 v[124:125], v[72:73], 0, s[24:25]
	global_load_lds_dwordx4 v[124:125], off
	v_mfma_f32_32x32x16_bf16 v[32:47], v[100:103], v[112:115], v[32:47]
	v_mfma_f32_32x32x16_bf16 v[16:31], v[104:107], v[108:111], v[16:31]
	s_add_u32 m0, s31, 0xa000
	v_lshl_add_u64 v[126:127], v[74:75], 0, s[24:25]
	global_load_lds_dwordx4 v[126:127], off
	v_mfma_f32_32x32x16_bf16 v[0:15], v[104:107], v[112:115], v[0:15]
	ds_read_b128 v[100:103], v79 offset:49152
	ds_read_b128 v[104:107], v79 offset:53248
	ds_read_b128 v[108:111], v83 offset:49152
	ds_read_b128 v[112:115], v83 offset:53248
	s_waitcnt lgkmcnt(4)
	v_mfma_f32_32x32x16_bf16 v[48:63], v[84:87], v[92:95], v[48:63]
	v_mfma_f32_32x32x16_bf16 v[32:47], v[84:87], v[96:99], v[32:47]
	v_mfma_f32_32x32x16_bf16 v[16:31], v[88:91], v[92:95], v[16:31]
	v_mfma_f32_32x32x16_bf16 v[0:15], v[88:91], v[96:99], v[0:15]
	s_waitcnt vmcnt(6) lgkmcnt(0)
	s_barrier
;     ...
;   for (int kt = 0; kt < nk; ++kt) {
;     if (kt + 1 < nk) asm volatile("s_waitcnt vmcnt(6)" ::: "memory");
;     else asm volatile("s_waitcnt vmcnt(0)" ::: "memory");
;     __builtin_amdgcn_s_barrier();
;     asm volatile("" ::: "memory");
;     if (kt + 2 < nk) { const int st2 = (st >= 1) ? st - 1 : 2; GEMM_ISSUE(kt + 2, st2); }
;     const char* la = lds + st * STAGE_B;
;     const char* lb = la + 32768;
;     const unsigned sa_u = (unsigned)(size_t)la + arow_u, sb_u = (unsigned)(size_t)lb + brow_u;
;     const unsigned a0 = sa_u + co0, a1 = sa_u + co1, a2 = sa_u + co2, a3 = sa_u + co3;
;     const unsigned b0 = sb_u + co0, b1 = sb_u + co1, b2 = sb_u + co2, b3 = sb_u + co3;
;     {
;       bf16x8 p0, p1, q0, q1, u0, u1, w0, w1;
;       asm volatile(
;         "ds_read_b128 %4, %12\n\tds_read_b128 %5, %12 offset:4096\n\tds_read_b128 %6, %16\n\tds_read_b128 %7, %16 offset:4096\n\t"
;         "ds_read_b128 %8, %13\n\tds_read_b128 %9, %13 offset:4096\n\tds_read_b128 %10, %17\n\tds_read_b128 %11, %17 offset:4096\n\t"
;         "s_waitcnt lgkmcnt(4)\n\t"
;         "v_mfma_f32_32x32x16_bf16 %0, %4, %6, %0\n\tv_mfma_f32_32x32x16_bf16 %1, %4, %7, %1\n\tv_mfma_f32_32x32x16_bf16 %2, %5, %6, %2\n\tv_mfma_f32_32x32x16_bf16 %3, %5, %7, %3\n\t"
;         "ds_read_b128 %4, %14\n\tds_read_b128 %5, %14 offset:4096\n\tds_read_b128 %6, %18\n\tds_read_b128 %7, %18 offset:4096\n\t"
;         "s_waitcnt lgkmcnt(4)\n\t"
;         "v_mfma_f32_32x32x16_bf16 %0, %8, %10, %0\n\tv_mfma_f32_32x32x16_bf16 %1, %8, %11, %1\n\tv_mfma_f32_32x32x16_bf16 %2, %9, %10, %2\n\tv_mfma_f32_32x32x16_bf16 %3, %9, %11, %3\n\t"
;         "ds_read_b128 %8, %15\n\tds_read_b128 %9, %15 offset:4096\n\tds_read_b128 %10, %19\n\tds_read_b128 %11, %19 offset:4096\n\t"
;         "s_waitcnt lgkmcnt(4)\n\t"
;         "v_mfma_f32_32x32x16_bf16 %0, %4, %6, %0\n\tv_mfma_f32_32x32x16_bf16 %1, %4, %7, %1\n\tv_mfma_f32_32x32x16_bf16 %2, %5, %6, %2\n\tv_mfma_f32_32x32x16_bf16 %3, %5, %7, %3\n\t"
;         "s_waitcnt lgkmcnt(0)\n\t"
;         "v_mfma_f32_32x32x16_bf16 %0, %8, %10, %0\n\tv_mfma_f32_32x32x16_bf16 %1, %8, %11, %1\n\tv_mfma_f32_32x32x16_bf16 %2, %9, %10, %2\n\tv_mfma_f32_32x32x16_bf16 %3, %9, %11, %3"
;         : "+v"(acc[0][0]), "+v"(acc[0][1]), "+v"(acc[1][0]), "+v"(acc[1][1]),
;           "=&v"(p0), "=&v"(p1), "=&v"(q0), "=&v"(q1), "=&v"(u0), "=&v"(u1), "=&v"(w0), "=&v"(w1)
	ds_read_b128 v[84:87], v116
	ds_read_b128 v[88:91], v116 offset:4096
	ds_read_b128 v[92:95], v120
	ds_read_b128 v[96:99], v120 offset:4096
	v_mfma_f32_32x32x16_bf16 v[48:63], v[100:103], v[108:111], v[48:63]
	s_mov_b32 s24, 0x400
	s_mov_b32 s25, 0
	s_add_u32 m0, s31, 0xc000
	v_lshl_add_u64 v[124:125], v[64:65], 0, s[24:25]
	global_load_lds_dwordx4 v[124:125], off
	v_mfma_f32_32x32x16_bf16 v[32:47], v[100:103], v[112:115], v[32:47]
	v_mfma_f32_32x32x16_bf16 v[16:31], v[104:107], v[108:111], v[16:31]
	s_add_u32 m0, s31, 0xe000
	v_lshl_add_u64 v[126:127], v[66:67], 0, s[24:25]
	global_load_lds_dwordx4 v[126:127], off
	v_mfma_f32_32x32x16_bf16 v[0:15], v[104:107], v[112:115], v[0:15]
	ds_read_b128 v[100:103], v117
	ds_read_b128 v[104:107], v117 offset:4096
	ds_read_b128 v[108:111], v121
	ds_read_b128 v[112:115], v121 offset:4096
	s_waitcnt lgkmcnt(4)
	v_mfma_f32_32x32x16_bf16 v[48:63], v[84:87], v[92:95], v[48:63]
	s_add_u32 m0, s31, 0x10000
	v_lshl_add_u64 v[124:125], v[68:69], 0, s[24:25]
	global_load_lds_dwordx4 v[124:125], off
	v_mfma_f32_32x32x16_bf16 v[32:47], v[84:87], v[96:99], v[32:47]
	v_mfma_f32_32x32x16_bf16 v[16:31], v[88:91], v[92:95], v[16:31]
	s_add_u32 m0, s31, 0x12000
	v_lshl_add_u64 v[126:127], v[70:71], 0, s[24:25]
	global_load_lds_dwordx4 v[126:127], off
	v_mfma_f32_32x32x16_bf16 v[0:15], v[88:91], v[96:99], v[0:15]
	ds_read_b128 v[84:87], v118
	ds_read_b128 v[88:91], v118 offset:4096
	ds_read_b128 v[92:95], v122
	ds_read_b128 v[96:99], v122 offset:4096
	s_waitcnt lgkmcnt(4)
	v_mfma_f32_32x32x16_bf16 v[48:63], v[100:103], v[108:111], v[48:63]
	s_add_u32 m0, s31, 0x14000
	v_lshl_add_u64 v[124:125], v[72:73], 0, s[24:25]
	global_load_lds_dwordx4 v[124:125], off
	v_mfma_f32_32x32x16_bf16 v[32:47], v[100:103], v[112:115], v[32:47]
	v_mfma_f32_32x32x16_bf16 v[16:31], v[104:107], v[108:111], v[16:31]
	s_add_u32 m0, s31, 0x16000
	v_lshl_add_u64 v[126:127], v[74:75], 0, s[24:25]
	global_load_lds_dwordx4 v[126:127], off
	v_mfma_f32_32x32x16_bf16 v[0:15], v[104:107], v[112:115], v[0:15]
	ds_read_b128 v[100:103], v119
	ds_read_b128 v[104:107], v119 offset:4096
	ds_read_b128 v[108:111], v123
	ds_read_b128 v[112:115], v123 offset:4096
	s_waitcnt lgkmcnt(4)
	v_mfma_f32_32x32x16_bf16 v[48:63], v[84:87], v[92:95], v[48:63]
	v_mfma_f32_32x32x16_bf16 v[32:47], v[84:87], v[96:99], v[32:47]
	v_mfma_f32_32x32x16_bf16 v[16:31], v[88:91], v[92:95], v[16:31]
	v_mfma_f32_32x32x16_bf16 v[0:15], v[88:91], v[96:99], v[0:15]
	s_waitcnt vmcnt(6) lgkmcnt(0)
	s_barrier
	ds_read_b128 v[84:87], v76
	ds_read_b128 v[88:91], v76 offset:4096
	ds_read_b128 v[92:95], v80
	ds_read_b128 v[96:99], v80 offset:4096
	v_mfma_f32_32x32x16_bf16 v[48:63], v[100:103], v[108:111], v[48:63]
	s_mov_b32 s24, 0x480
	s_mov_b32 s25, 0
	s_add_u32 m0, s31, 0x18000
	v_lshl_add_u64 v[124:125], v[64:65], 0, s[24:25]
	global_load_lds_dwordx4 v[124:125], off
	v_mfma_f32_32x32x16_bf16 v[32:47], v[100:103], v[112:115], v[32:47]
	v_mfma_f32_32x32x16_bf16 v[16:31], v[104:107], v[108:111], v[16:31]
	s_add_u32 m0, s31, 0x1a000
	v_lshl_add_u64 v[126:127], v[66:67], 0, s[24:25]
	global_load_lds_dwordx4 v[126:127], off
	v_mfma_f32_32x32x16_bf16 v[0:15], v[104:107], v[112:115], v[0:15]
	ds_read_b128 v[100:103], v77
	ds_read_b128 v[104:107], v77 offset:4096
	ds_read_b128 v[108:111], v81
	ds_read_b128 v[112:115], v81 offset:4096
	s_waitcnt lgkmcnt(4)
	v_mfma_f32_32x32x16_bf16 v[48:63], v[84:87], v[92:95], v[48:63]
	s_add_u32 m0, s31, 0x1c000
	v_lshl_add_u64 v[124:125], v[68:69], 0, s[24:25]
	global_load_lds_dwordx4 v[124:125], off
	v_mfma_f32_32x32x16_bf16 v[32:47], v[84:87], v[96:99], v[32:47]
	v_mfma_f32_32x32x16_bf16 v[16:31], v[88:91], v[92:95], v[16:31]
	s_add_u32 m0, s31, 0x1e000
	v_lshl_add_u64 v[126:127], v[70:71], 0, s[24:25]
	global_load_lds_dwordx4 v[126:127], off
	v_mfma_f32_32x32x16_bf16 v[0:15], v[88:91], v[96:99], v[0:15]
	ds_read_b128 v[84:87], v78
	ds_read_b128 v[88:91], v78 offset:4096
	ds_read_b128 v[92:95], v82
	ds_read_b128 v[96:99], v82 offset:4096
	s_waitcnt lgkmcnt(4)
	v_mfma_f32_32x32x16_bf16 v[48:63], v[100:103], v[108:111], v[48:63]
	s_add_u32 m0, s31, 0x20000
	v_lshl_add_u64 v[124:125], v[72:73], 0, s[24:25]
	global_load_lds_dwordx4 v[124:125], off
	v_mfma_f32_32x32x16_bf16 v[32:47], v[100:103], v[112:115], v[32:47]
	v_mfma_f32_32x32x16_bf16 v[16:31], v[104:107], v[108:111], v[16:31]
	s_add_u32 m0, s31, 0x22000
	v_lshl_add_u64 v[126:127], v[74:75], 0, s[24:25]
	global_load_lds_dwordx4 v[126:127], off
	v_mfma_f32_32x32x16_bf16 v[0:15], v[104:107], v[112:115], v[0:15]
	ds_read_b128 v[100:103], v79
	ds_read_b128 v[104:107], v79 offset:4096
	ds_read_b128 v[108:111], v83
	ds_read_b128 v[112:115], v83 offset:4096
	s_waitcnt lgkmcnt(4)
	v_mfma_f32_32x32x16_bf16 v[48:63], v[84:87], v[92:95], v[48:63]
	v_mfma_f32_32x32x16_bf16 v[32:47], v[84:87], v[96:99], v[32:47]
	v_mfma_f32_32x32x16_bf16 v[16:31], v[88:91], v[92:95], v[16:31]
	v_mfma_f32_32x32x16_bf16 v[0:15], v[88:91], v[96:99], v[0:15]
	s_waitcnt vmcnt(6) lgkmcnt(0)
	s_barrier
;     ...
;   for (int kt = 0; kt < nk; ++kt) {
;     if (kt + 1 < nk) asm volatile("s_waitcnt vmcnt(6)" ::: "memory");
;     else asm volatile("s_waitcnt vmcnt(0)" ::: "memory");
;     __builtin_amdgcn_s_barrier();
;     asm volatile("" ::: "memory");
;     if (kt + 2 < nk) { const int st2 = (st >= 1) ? st - 1 : 2; GEMM_ISSUE(kt + 2, st2); }
;     const char* la = lds + st * STAGE_B;
;     const char* lb = la + 32768;
;     const unsigned sa_u = (unsigned)(size_t)la + arow_u, sb_u = (unsigned)(size_t)lb + brow_u;
;     const unsigned a0 = sa_u + co0, a1 = sa_u + co1, a2 = sa_u + co2, a3 = sa_u + co3;
;     const unsigned b0 = sb_u + co0, b1 = sb_u + co1, b2 = sb_u + co2, b3 = sb_u + co3;
;     {
;       bf16x8 p0, p1, q0, q1, u0, u1, w0, w1;
;       asm volatile(
;         "ds_read_b128 %4, %12\n\tds_read_b128 %5, %12 offset:4096\n\tds_read_b128 %6, %16\n\tds_read_b128 %7, %16 offset:4096\n\t"
;         "ds_read_b128 %8, %13\n\tds_read_b128 %9, %13 offset:4096\n\tds_read_b128 %10, %17\n\tds_read_b128 %11, %17 offset:4096\n\t"
;         "s_waitcnt lgkmcnt(4)\n\t"
;         "v_mfma_f32_32x32x16_bf16 %0, %4, %6, %0\n\tv_mfma_f32_32x32x16_bf16 %1, %4, %7, %1\n\tv_mfma_f32_32x32x16_bf16 %2, %5, %6, %2\n\tv_mfma_f32_32x32x16_bf16 %3, %5, %7, %3\n\t"
;         "ds_read_b128 %4, %14\n\tds_read_b128 %5, %14 offset:4096\n\tds_read_b128 %6, %18\n\tds_read_b128 %7, %18 offset:4096\n\t"
;         "s_waitcnt lgkmcnt(4)\n\t"
;         "v_mfma_f32_32x32x16_bf16 %0, %8, %10, %0\n\tv_mfma_f32_32x32x16_bf16 %1, %8, %11, %1\n\tv_mfma_f32_32x32x16_bf16 %2, %9, %10, %2\n\tv_mfma_f32_32x32x16_bf16 %3, %9, %11, %3\n\t"
;         "ds_read_b128 %8, %15\n\tds_read_b128 %9, %15 offset:4096\n\tds_read_b128 %10, %19\n\tds_read_b128 %11, %19 offset:4096\n\t"
;         "s_waitcnt lgkmcnt(4)\n\t"
;         "v_mfma_f32_32x32x16_bf16 %0, %4, %6, %0\n\tv_mfma_f32_32x32x16_bf16 %1, %4, %7, %1\n\tv_mfma_f32_32x32x16_bf16 %2, %5, %6, %2\n\tv_mfma_f32_32x32x16_bf16 %3, %5, %7, %3\n\t"
;         "s_waitcnt lgkmcnt(0)\n\t"
;         "v_mfma_f32_32x32x16_bf16 %0, %8, %10, %0\n\tv_mfma_f32_32x32x16_bf16 %1, %8, %11, %1\n\tv_mfma_f32_32x32x16_bf16 %2, %9, %10, %2\n\tv_mfma_f32_32x32x16_bf16 %3, %9, %11, %3"
;         : "+v"(acc[0][0]), "+v"(acc[0][1]), "+v"(acc[1][0]), "+v"(acc[1][1]),
;           "=&v"(p0), "=&v"(p1), "=&v"(q0), "=&v"(q1), "=&v"(u0), "=&v"(u1), "=&v"(w0), "=&v"(w1)
	ds_read_b128 v[84:87], v76 offset:49152
	ds_read_b128 v[88:91], v76 offset:53248
	ds_read_b128 v[92:95], v80 offset:49152
	ds_read_b128 v[96:99], v80 offset:53248
	v_mfma_f32_32x32x16_bf16 v[48:63], v[100:103], v[108:111], v[48:63]
	s_mov_b32 s24, 0x500
	s_mov_b32 s25, 0
	s_mov_b32 m0, s31
	v_lshl_add_u64 v[124:125], v[64:65], 0, s[24:25]
	global_load_lds_dwordx4 v[124:125], off
	v_mfma_f32_32x32x16_bf16 v[32:47], v[100:103], v[112:115], v[32:47]
	v_mfma_f32_32x32x16_bf16 v[16:31], v[104:107], v[108:111], v[16:31]
	s_add_u32 m0, s31, 0x2000
	v_lshl_add_u64 v[126:127], v[66:67], 0, s[24:25]
	global_load_lds_dwordx4 v[126:127], off
	v_mfma_f32_32x32x16_bf16 v[0:15], v[104:107], v[112:115], v[0:15]
	ds_read_b128 v[100:103], v77 offset:49152
	ds_read_b128 v[104:107], v77 offset:53248
	ds_read_b128 v[108:111], v81 offset:49152
	ds_read_b128 v[112:115], v81 offset:53248
	s_waitcnt lgkmcnt(4)
	v_mfma_f32_32x32x16_bf16 v[48:63], v[84:87], v[92:95], v[48:63]
	s_add_u32 m0, s31, 0x4000
	v_lshl_add_u64 v[124:125], v[68:69], 0, s[24:25]
	global_load_lds_dwordx4 v[124:125], off
	v_mfma_f32_32x32x16_bf16 v[32:47], v[84:87], v[96:99], v[32:47]
	v_mfma_f32_32x32x16_bf16 v[16:31], v[88:91], v[92:95], v[16:31]
	s_add_u32 m0, s31, 0x6000
	v_lshl_add_u64 v[126:127], v[70:71], 0, s[24:25]
	global_load_lds_dwordx4 v[126:127], off
	v_mfma_f32_32x32x16_bf16 v[0:15], v[88:91], v[96:99], v[0:15]
	ds_read_b128 v[84:87], v78 offset:49152
	ds_read_b128 v[88:91], v78 offset:53248
	ds_read_b128 v[92:95], v82 offset:49152
	ds_read_b128 v[96:99], v82 offset:53248
	s_waitcnt lgkmcnt(4)
	v_mfma_f32_32x32x16_bf16 v[48:63], v[100:103], v[108:111], v[48:63]
	s_add_u32 m0, s31, 0x8000
	v_lshl_add_u64 v[124:125], v[72:73], 0, s[24:25]
	global_load_lds_dwordx4 v[124:125], off
	v_mfma_f32_32x32x16_bf16 v[32:47], v[100:103], v[112:115], v[32:47]
	v_mfma_f32_32x32x16_bf16 v[16:31], v[104:107], v[108:111], v[16:31]
	s_add_u32 m0, s31, 0xa000
	v_lshl_add_u64 v[126:127], v[74:75], 0, s[24:25]
	global_load_lds_dwordx4 v[126:127], off
	v_mfma_f32_32x32x16_bf16 v[0:15], v[104:107], v[112:115], v[0:15]
	ds_read_b128 v[100:103], v79 offset:49152
	ds_read_b128 v[104:107], v79 offset:53248
	ds_read_b128 v[108:111], v83 offset:49152
	ds_read_b128 v[112:115], v83 offset:53248
	s_waitcnt lgkmcnt(4)
	v_mfma_f32_32x32x16_bf16 v[48:63], v[84:87], v[92:95], v[48:63]
	v_mfma_f32_32x32x16_bf16 v[32:47], v[84:87], v[96:99], v[32:47]
	v_mfma_f32_32x32x16_bf16 v[16:31], v[88:91], v[92:95], v[16:31]
	v_mfma_f32_32x32x16_bf16 v[0:15], v[88:91], v[96:99], v[0:15]
	s_waitcnt vmcnt(6) lgkmcnt(0)
	s_barrier
	ds_read_b128 v[84:87], v116
	ds_read_b128 v[88:91], v116 offset:4096
	ds_read_b128 v[92:95], v120
	ds_read_b128 v[96:99], v120 offset:4096
	v_mfma_f32_32x32x16_bf16 v[48:63], v[100:103], v[108:111], v[48:63]
	s_mov_b32 s24, 0x580
	s_mov_b32 s25, 0
	s_add_u32 m0, s31, 0xc000
	v_lshl_add_u64 v[124:125], v[64:65], 0, s[24:25]
	global_load_lds_dwordx4 v[124:125], off
	v_mfma_f32_32x32x16_bf16 v[32:47], v[100:103], v[112:115], v[32:47]
	v_mfma_f32_32x32x16_bf16 v[16:31], v[104:107], v[108:111], v[16:31]
	s_add_u32 m0, s31, 0xe000
	v_lshl_add_u64 v[126:127], v[66:67], 0, s[24:25]
	global_load_lds_dwordx4 v[126:127], off
	v_mfma_f32_32x32x16_bf16 v[0:15], v[104:107], v[112:115], v[0:15]
	ds_read_b128 v[100:103], v117
	ds_read_b128 v[104:107], v117 offset:4096
	ds_read_b128 v[108:111], v121
	ds_read_b128 v[112:115], v121 offset:4096
	s_waitcnt lgkmcnt(4)
	v_mfma_f32_32x32x16_bf16 v[48:63], v[84:87], v[92:95], v[48:63]
	s_add_u32 m0, s31, 0x10000
	v_lshl_add_u64 v[124:125], v[68:69], 0, s[24:25]
	global_load_lds_dwordx4 v[124:125], off
	v_mfma_f32_32x32x16_bf16 v[32:47], v[84:87], v[96:99], v[32:47]
	v_mfma_f32_32x32x16_bf16 v[16:31], v[88:91], v[92:95], v[16:31]
	s_add_u32 m0, s31, 0x12000
	v_lshl_add_u64 v[126:127], v[70:71], 0, s[24:25]
	global_load_lds_dwordx4 v[126:127], off
	v_mfma_f32_32x32x16_bf16 v[0:15], v[88:91], v[96:99], v[0:15]
	ds_read_b128 v[84:87], v118
	ds_read_b128 v[88:91], v118 offset:4096
	ds_read_b128 v[92:95], v122
	ds_read_b128 v[96:99], v122 offset:4096
	s_waitcnt lgkmcnt(4)
	v_mfma_f32_32x32x16_bf16 v[48:63], v[100:103], v[108:111], v[48:63]
	s_add_u32 m0, s31, 0x14000
	v_lshl_add_u64 v[124:125], v[72:73], 0, s[24:25]
	global_load_lds_dwordx4 v[124:125], off
	v_mfma_f32_32x32x16_bf16 v[32:47], v[100:103], v[112:115], v[32:47]
	v_mfma_f32_32x32x16_bf16 v[16:31], v[104:107], v[108:111], v[16:31]
	s_add_u32 m0, s31, 0x16000
	v_lshl_add_u64 v[126:127], v[74:75], 0, s[24:25]
	global_load_lds_dwordx4 v[126:127], off
	v_mfma_f32_32x32x16_bf16 v[0:15], v[104:107], v[112:115], v[0:15]
	ds_read_b128 v[100:103], v119
	ds_read_b128 v[104:107], v119 offset:4096
	ds_read_b128 v[108:111], v123
	ds_read_b128 v[112:115], v123 offset:4096
	s_waitcnt lgkmcnt(4)
	v_mfma_f32_32x32x16_bf16 v[48:63], v[84:87], v[92:95], v[48:63]
	v_mfma_f32_32x32x16_bf16 v[32:47], v[84:87], v[96:99], v[32:47]
	v_mfma_f32_32x32x16_bf16 v[16:31], v[88:91], v[92:95], v[16:31]
	v_mfma_f32_32x32x16_bf16 v[0:15], v[88:91], v[96:99], v[0:15]
	s_waitcnt vmcnt(6) lgkmcnt(0)
	s_barrier
;     ...
;   for (int kt = 0; kt < nk; ++kt) {
;     if (kt + 1 < nk) asm volatile("s_waitcnt vmcnt(6)" ::: "memory");
;     else asm volatile("s_waitcnt vmcnt(0)" ::: "memory");
;     __builtin_amdgcn_s_barrier();
;     asm volatile("" ::: "memory");
;     if (kt + 2 < nk) { const int st2 = (st >= 1) ? st - 1 : 2; GEMM_ISSUE(kt + 2, st2); }
;     const char* la = lds + st * STAGE_B;
;     const char* lb = la + 32768;
;     const unsigned sa_u = (unsigned)(size_t)la + arow_u, sb_u = (unsigned)(size_t)lb + brow_u;
;     const unsigned a0 = sa_u + co0, a1 = sa_u + co1, a2 = sa_u + co2, a3 = sa_u + co3;
;     const unsigned b0 = sb_u + co0, b1 = sb_u + co1, b2 = sb_u + co2, b3 = sb_u + co3;
;     {
;       bf16x8 p0, p1, q0, q1, u0, u1, w0, w1;
;       asm volatile(
;         "ds_read_b128 %4, %12\n\tds_read_b128 %5, %12 offset:4096\n\tds_read_b128 %6, %16\n\tds_read_b128 %7, %16 offset:4096\n\t"
;         "ds_read_b128 %8, %13\n\tds_read_b128 %9, %13 offset:4096\n\tds_read_b128 %10, %17\n\tds_read_b128 %11, %17 offset:4096\n\t"
;         "s_waitcnt lgkmcnt(4)\n\t"
;         "v_mfma_f32_32x32x16_bf16 %0, %4, %6, %0\n\tv_mfma_f32_32x32x16_bf16 %1, %4, %7, %1\n\tv_mfma_f32_32x32x16_bf16 %2, %5, %6, %2\n\tv_mfma_f32_32x32x16_bf16 %3, %5, %7, %3\n\t"
;         "ds_read_b128 %4, %14\n\tds_read_b128 %5, %14 offset:4096\n\tds_read_b128 %6, %18\n\tds_read_b128 %7, %18 offset:4096\n\t"
;         "s_waitcnt lgkmcnt(4)\n\t"
;         "v_mfma_f32_32x32x16_bf16 %0, %8, %10, %0\n\tv_mfma_f32_32x32x16_bf16 %1, %8, %11, %1\n\tv_mfma_f32_32x32x16_bf16 %2, %9, %10, %2\n\tv_mfma_f32_32x32x16_bf16 %3, %9, %11, %3\n\t"
;         "ds_read_b128 %8, %15\n\tds_read_b128 %9, %15 offset:4096\n\tds_read_b128 %10, %19\n\tds_read_b128 %11, %19 offset:4096\n\t"
;         "s_waitcnt lgkmcnt(4)\n\t"
;         "v_mfma_f32_32x32x16_bf16 %0, %4, %6, %0\n\tv_mfma_f32_32x32x16_bf16 %1, %4, %7, %1\n\tv_mfma_f32_32x32x16_bf16 %2, %5, %6, %2\n\tv_mfma_f32_32x32x16_bf16 %3, %5, %7, %3\n\t"
;         "s_waitcnt lgkmcnt(0)\n\t"
;         "v_mfma_f32_32x32x16_bf16 %0, %8, %10, %0\n\tv_mfma_f32_32x32x16_bf16 %1, %8, %11, %1\n\tv_mfma_f32_32x32x16_bf16 %2, %9, %10, %2\n\tv_mfma_f32_32x32x16_bf16 %3, %9, %11, %3"
;         : "+v"(acc[0][0]), "+v"(acc[0][1]), "+v"(acc[1][0]), "+v"(acc[1][1]),
;           "=&v"(p0), "=&v"(p1), "=&v"(q0), "=&v"(q1), "=&v"(u0), "=&v"(u1), "=&v"(w0), "=&v"(w1)
	ds_read_b128 v[84:87], v76
	ds_read_b128 v[88:91], v76 offset:4096
	ds_read_b128 v[92:95], v80
	ds_read_b128 v[96:99], v80 offset:4096
	v_mfma_f32_32x32x16_bf16 v[48:63], v[100:103], v[108:111], v[48:63]
	s_mov_b32 s24, 0x600
	s_mov_b32 s25, 0
	s_add_u32 m0, s31, 0x18000
	v_lshl_add_u64 v[124:125], v[64:65], 0, s[24:25]
	global_load_lds_dwordx4 v[124:125], off
	v_mfma_f32_32x32x16_bf16 v[32:47], v[100:103], v[112:115], v[32:47]
	v_mfma_f32_32x32x16_bf16 v[16:31], v[104:107], v[108:111], v[16:31]
	s_add_u32 m0, s31, 0x1a000
	v_lshl_add_u64 v[126:127], v[66:67], 0, s[24:25]
	global_load_lds_dwordx4 v[126:127], off
	v_mfma_f32_32x32x16_bf16 v[0:15], v[104:107], v[112:115], v[0:15]
	ds_read_b128 v[100:103], v77
	ds_read_b128 v[104:107], v77 offset:4096
	ds_read_b128 v[108:111], v81
	ds_read_b128 v[112:115], v81 offset:4096
	s_waitcnt lgkmcnt(4)
	v_mfma_f32_32x32x16_bf16 v[48:63], v[84:87], v[92:95], v[48:63]
	s_add_u32 m0, s31, 0x1c000
	v_lshl_add_u64 v[124:125], v[68:69], 0, s[24:25]
	global_load_lds_dwordx4 v[124:125], off
	v_mfma_f32_32x32x16_bf16 v[32:47], v[84:87], v[96:99], v[32:47]
	v_mfma_f32_32x32x16_bf16 v[16:31], v[88:91], v[92:95], v[16:31]
	s_add_u32 m0, s31, 0x1e000
	v_lshl_add_u64 v[126:127], v[70:71], 0, s[24:25]
	global_load_lds_dwordx4 v[126:127], off
	v_mfma_f32_32x32x16_bf16 v[0:15], v[88:91], v[96:99], v[0:15]
	ds_read_b128 v[84:87], v78
	ds_read_b128 v[88:91], v78 offset:4096
	ds_read_b128 v[92:95], v82
	ds_read_b128 v[96:99], v82 offset:4096
	s_waitcnt lgkmcnt(4)
	v_mfma_f32_32x32x16_bf16 v[48:63], v[100:103], v[108:111], v[48:63]
	s_add_u32 m0, s31, 0x20000
	v_lshl_add_u64 v[124:125], v[72:73], 0, s[24:25]
	global_load_lds_dwordx4 v[124:125], off
	v_mfma_f32_32x32x16_bf16 v[32:47], v[100:103], v[112:115], v[32:47]
	v_mfma_f32_32x32x16_bf16 v[16:31], v[104:107], v[108:111], v[16:31]
	s_add_u32 m0, s31, 0x22000
	v_lshl_add_u64 v[126:127], v[74:75], 0, s[24:25]
	global_load_lds_dwordx4 v[126:127], off
	v_mfma_f32_32x32x16_bf16 v[0:15], v[104:107], v[112:115], v[0:15]
	ds_read_b128 v[100:103], v79
	ds_read_b128 v[104:107], v79 offset:4096
	ds_read_b128 v[108:111], v83
	ds_read_b128 v[112:115], v83 offset:4096
	s_waitcnt lgkmcnt(4)
	v_mfma_f32_32x32x16_bf16 v[48:63], v[84:87], v[92:95], v[48:63]
	v_mfma_f32_32x32x16_bf16 v[32:47], v[84:87], v[96:99], v[32:47]
	v_mfma_f32_32x32x16_bf16 v[16:31], v[88:91], v[92:95], v[16:31]
	v_mfma_f32_32x32x16_bf16 v[0:15], v[88:91], v[96:99], v[0:15]
	s_waitcnt vmcnt(6) lgkmcnt(0)
	s_barrier
	ds_read_b128 v[84:87], v76 offset:49152
	ds_read_b128 v[88:91], v76 offset:53248
	ds_read_b128 v[92:95], v80 offset:49152
	ds_read_b128 v[96:99], v80 offset:53248
	v_mfma_f32_32x32x16_bf16 v[48:63], v[100:103], v[108:111], v[48:63]
	s_mov_b32 s24, 0x680
	s_mov_b32 s25, 0
	s_mov_b32 m0, s31
	v_lshl_add_u64 v[124:125], v[64:65], 0, s[24:25]
	global_load_lds_dwordx4 v[124:125], off
	v_mfma_f32_32x32x16_bf16 v[32:47], v[100:103], v[112:115], v[32:47]
	v_mfma_f32_32x32x16_bf16 v[16:31], v[104:107], v[108:111], v[16:31]
	s_add_u32 m0, s31, 0x2000
	v_lshl_add_u64 v[126:127], v[66:67], 0, s[24:25]
	global_load_lds_dwordx4 v[126:127], off
	v_mfma_f32_32x32x16_bf16 v[0:15], v[104:107], v[112:115], v[0:15]
	ds_read_b128 v[100:103], v77 offset:49152
	ds_read_b128 v[104:107], v77 offset:53248
	ds_read_b128 v[108:111], v81 offset:49152
	ds_read_b128 v[112:115], v81 offset:53248
	s_waitcnt lgkmcnt(4)
	v_mfma_f32_32x32x16_bf16 v[48:63], v[84:87], v[92:95], v[48:63]
	s_add_u32 m0, s31, 0x4000
	v_lshl_add_u64 v[124:125], v[68:69], 0, s[24:25]
	global_load_lds_dwordx4 v[124:125], off
	v_mfma_f32_32x32x16_bf16 v[32:47], v[84:87], v[96:99], v[32:47]
	v_mfma_f32_32x32x16_bf16 v[16:31], v[88:91], v[92:95], v[16:31]
	s_add_u32 m0, s31, 0x6000
	v_lshl_add_u64 v[126:127], v[70:71], 0, s[24:25]
	global_load_lds_dwordx4 v[126:127], off
	v_mfma_f32_32x32x16_bf16 v[0:15], v[88:91], v[96:99], v[0:15]
	ds_read_b128 v[84:87], v78 offset:49152
	ds_read_b128 v[88:91], v78 offset:53248
	ds_read_b128 v[92:95], v82 offset:49152
	ds_read_b128 v[96:99], v82 offset:53248
	s_waitcnt lgkmcnt(4)
	v_mfma_f32_32x32x16_bf16 v[48:63], v[100:103], v[108:111], v[48:63]
	s_add_u32 m0, s31, 0x8000
	v_lshl_add_u64 v[124:125], v[72:73], 0, s[24:25]
	global_load_lds_dwordx4 v[124:125], off
	v_mfma_f32_32x32x16_bf16 v[32:47], v[100:103], v[112:115], v[32:47]
	v_mfma_f32_32x32x16_bf16 v[16:31], v[104:107], v[108:111], v[16:31]
	s_add_u32 m0, s31, 0xa000
	v_lshl_add_u64 v[126:127], v[74:75], 0, s[24:25]
	global_load_lds_dwordx4 v[126:127], off
	v_mfma_f32_32x32x16_bf16 v[0:15], v[104:107], v[112:115], v[0:15]
	ds_read_b128 v[100:103], v79 offset:49152
	ds_read_b128 v[104:107], v79 offset:53248
	ds_read_b128 v[108:111], v83 offset:49152
	ds_read_b128 v[112:115], v83 offset:53248
	s_waitcnt lgkmcnt(4)
	v_mfma_f32_32x32x16_bf16 v[48:63], v[84:87], v[92:95], v[48:63]
	v_mfma_f32_32x32x16_bf16 v[32:47], v[84:87], v[96:99], v[32:47]
	v_mfma_f32_32x32x16_bf16 v[16:31], v[88:91], v[92:95], v[16:31]
	v_mfma_f32_32x32x16_bf16 v[0:15], v[88:91], v[96:99], v[0:15]
	s_waitcnt vmcnt(6) lgkmcnt(0)
	s_barrier
;     ...
;   for (int kt = 0; kt < nk; ++kt) {
;     if (kt + 1 < nk) asm volatile("s_waitcnt vmcnt(6)" ::: "memory");
;     else asm volatile("s_waitcnt vmcnt(0)" ::: "memory");
;     __builtin_amdgcn_s_barrier();
;     asm volatile("" ::: "memory");
;     if (kt + 2 < nk) { const int st2 = (st >= 1) ? st - 1 : 2; GEMM_ISSUE(kt + 2, st2); }
;     const char* la = lds + st * STAGE_B;
;     const char* lb = la + 32768;
;     const unsigned sa_u = (unsigned)(size_t)la + arow_u, sb_u = (unsigned)(size_t)lb + brow_u;
;     const unsigned a0 = sa_u + co0, a1 = sa_u + co1, a2 = sa_u + co2, a3 = sa_u + co3;
;     const unsigned b0 = sb_u + co0, b1 = sb_u + co1, b2 = sb_u + co2, b3 = sb_u + co3;
;     {
;       bf16x8 p0, p1, q0, q1, u0, u1, w0, w1;
;       asm volatile(
;         "ds_read_b128 %4, %12\n\tds_read_b128 %5, %12 offset:4096\n\tds_read_b128 %6, %16\n\tds_read_b128 %7, %16 offset:4096\n\t"
;         "ds_read_b128 %8, %13\n\tds_read_b128 %9, %13 offset:4096\n\tds_read_b128 %10, %17\n\tds_read_b128 %11, %17 offset:4096\n\t"
;         "s_waitcnt lgkmcnt(4)\n\t"
;         "v_mfma_f32_32x32x16_bf16 %0, %4, %6, %0\n\tv_mfma_f32_32x32x16_bf16 %1, %4, %7, %1\n\tv_mfma_f32_32x32x16_bf16 %2, %5, %6, %2\n\tv_mfma_f32_32x32x16_bf16 %3, %5, %7, %3\n\t"
;         "ds_read_b128 %4, %14\n\tds_read_b128 %5, %14 offset:4096\n\tds_read_b128 %6, %18\n\tds_read_b128 %7, %18 offset:4096\n\t"
;         "s_waitcnt lgkmcnt(4)\n\t"
;         "v_mfma_f32_32x32x16_bf16 %0, %8, %10, %0\n\tv_mfma_f32_32x32x16_bf16 %1, %8, %11, %1\n\tv_mfma_f32_32x32x16_bf16 %2, %9, %10, %2\n\tv_mfma_f32_32x32x16_bf16 %3, %9, %11, %3\n\t"
;         "ds_read_b128 %8, %15\n\tds_read_b128 %9, %15 offset:4096\n\tds_read_b128 %10, %19\n\tds_read_b128 %11, %19 offset:4096\n\t"
;         "s_waitcnt lgkmcnt(4)\n\t"
;         "v_mfma_f32_32x32x16_bf16 %0, %4, %6, %0\n\tv_mfma_f32_32x32x16_bf16 %1, %4, %7, %1\n\tv_mfma_f32_32x32x16_bf16 %2, %5, %6, %2\n\tv_mfma_f32_32x32x16_bf16 %3, %5, %7, %3\n\t"
;         "s_waitcnt lgkmcnt(0)\n\t"
;         "v_mfma_f32_32x32x16_bf16 %0, %8, %10, %0\n\tv_mfma_f32_32x32x16_bf16 %1, %8, %11, %1\n\tv_mfma_f32_32x32x16_bf16 %2, %9, %10, %2\n\tv_mfma_f32_32x32x16_bf16 %3, %9, %11, %3"
;         : "+v"(acc[0][0]), "+v"(acc[0][1]), "+v"(acc[1][0]), "+v"(acc[1][1]),
;           "=&v"(p0), "=&v"(p1), "=&v"(q0), "=&v"(q1), "=&v"(u0), "=&v"(u1), "=&v"(w0), "=&v"(w1)
	ds_read_b128 v[84:87], v116
	ds_read_b128 v[88:91], v116 offset:4096
	ds_read_b128 v[92:95], v120
	ds_read_b128 v[96:99], v120 offset:4096
	v_mfma_f32_32x32x16_bf16 v[48:63], v[100:103], v[108:111], v[48:63]
	s_mov_b32 s24, 0x700
	s_mov_b32 s25, 0
	s_add_u32 m0, s31, 0xc000
	v_lshl_add_u64 v[124:125], v[64:65], 0, s[24:25]
	global_load_lds_dwordx4 v[124:125], off
	v_mfma_f32_32x32x16_bf16 v[32:47], v[100:103], v[112:115], v[32:47]
	v_mfma_f32_32x32x16_bf16 v[16:31], v[104:107], v[108:111], v[16:31]
	s_add_u32 m0, s31, 0xe000
	v_lshl_add_u64 v[126:127], v[66:67], 0, s[24:25]
	global_load_lds_dwordx4 v[126:127], off
	v_mfma_f32_32x32x16_bf16 v[0:15], v[104:107], v[112:115], v[0:15]
	ds_read_b128 v[100:103], v117
	ds_read_b128 v[104:107], v117 offset:4096
	ds_read_b128 v[108:111], v121
	ds_read_b128 v[112:115], v121 offset:4096
	s_waitcnt lgkmcnt(4)
	v_mfma_f32_32x32x16_bf16 v[48:63], v[84:87], v[92:95], v[48:63]
	s_add_u32 m0, s31, 0x10000
	v_lshl_add_u64 v[124:125], v[68:69], 0, s[24:25]
	global_load_lds_dwordx4 v[124:125], off
	v_mfma_f32_32x32x16_bf16 v[32:47], v[84:87], v[96:99], v[32:47]
	v_mfma_f32_32x32x16_bf16 v[16:31], v[88:91], v[92:95], v[16:31]
	s_add_u32 m0, s31, 0x12000
	v_lshl_add_u64 v[126:127], v[70:71], 0, s[24:25]
	global_load_lds_dwordx4 v[126:127], off
	v_mfma_f32_32x32x16_bf16 v[0:15], v[88:91], v[96:99], v[0:15]
	ds_read_b128 v[84:87], v118
	ds_read_b128 v[88:91], v118 offset:4096
	ds_read_b128 v[92:95], v122
	ds_read_b128 v[96:99], v122 offset:4096
	s_waitcnt lgkmcnt(4)
	v_mfma_f32_32x32x16_bf16 v[48:63], v[100:103], v[108:111], v[48:63]
	s_add_u32 m0, s31, 0x14000
	v_lshl_add_u64 v[124:125], v[72:73], 0, s[24:25]
	global_load_lds_dwordx4 v[124:125], off
	v_mfma_f32_32x32x16_bf16 v[32:47], v[100:103], v[112:115], v[32:47]
	v_mfma_f32_32x32x16_bf16 v[16:31], v[104:107], v[108:111], v[16:31]
	s_add_u32 m0, s31, 0x16000
	v_lshl_add_u64 v[126:127], v[74:75], 0, s[24:25]
	global_load_lds_dwordx4 v[126:127], off
	v_mfma_f32_32x32x16_bf16 v[0:15], v[104:107], v[112:115], v[0:15]
	ds_read_b128 v[100:103], v119
	ds_read_b128 v[104:107], v119 offset:4096
	ds_read_b128 v[108:111], v123
	ds_read_b128 v[112:115], v123 offset:4096
	s_waitcnt lgkmcnt(4)
	v_mfma_f32_32x32x16_bf16 v[48:63], v[84:87], v[92:95], v[48:63]
	v_mfma_f32_32x32x16_bf16 v[32:47], v[84:87], v[96:99], v[32:47]
	v_mfma_f32_32x32x16_bf16 v[16:31], v[88:91], v[92:95], v[16:31]
	v_mfma_f32_32x32x16_bf16 v[0:15], v[88:91], v[96:99], v[0:15]
	s_waitcnt vmcnt(6) lgkmcnt(0)
	s_barrier
	ds_read_b128 v[84:87], v76
	ds_read_b128 v[88:91], v76 offset:4096
	ds_read_b128 v[92:95], v80
	ds_read_b128 v[96:99], v80 offset:4096
	v_mfma_f32_32x32x16_bf16 v[48:63], v[100:103], v[108:111], v[48:63]
	s_mov_b32 s24, 0x780
	s_mov_b32 s25, 0
	s_add_u32 m0, s31, 0x18000
	v_lshl_add_u64 v[124:125], v[64:65], 0, s[24:25]
	global_load_lds_dwordx4 v[124:125], off
	v_mfma_f32_32x32x16_bf16 v[32:47], v[100:103], v[112:115], v[32:47]
	v_mfma_f32_32x32x16_bf16 v[16:31], v[104:107], v[108:111], v[16:31]
	s_add_u32 m0, s31, 0x1a000
	v_lshl_add_u64 v[126:127], v[66:67], 0, s[24:25]
	global_load_lds_dwordx4 v[126:127], off
	v_mfma_f32_32x32x16_bf16 v[0:15], v[104:107], v[112:115], v[0:15]
	ds_read_b128 v[100:103], v77
	ds_read_b128 v[104:107], v77 offset:4096
	ds_read_b128 v[108:111], v81
	ds_read_b128 v[112:115], v81 offset:4096
	s_waitcnt lgkmcnt(4)
	v_mfma_f32_32x32x16_bf16 v[48:63], v[84:87], v[92:95], v[48:63]
	s_add_u32 m0, s31, 0x1c000
	v_lshl_add_u64 v[124:125], v[68:69], 0, s[24:25]
	global_load_lds_dwordx4 v[124:125], off
	v_mfma_f32_32x32x16_bf16 v[32:47], v[84:87], v[96:99], v[32:47]
	v_mfma_f32_32x32x16_bf16 v[16:31], v[88:91], v[92:95], v[16:31]
	s_add_u32 m0, s31, 0x1e000
	v_lshl_add_u64 v[126:127], v[70:71], 0, s[24:25]
	global_load_lds_dwordx4 v[126:127], off
	v_mfma_f32_32x32x16_bf16 v[0:15], v[88:91], v[96:99], v[0:15]
	ds_read_b128 v[84:87], v78
	ds_read_b128 v[88:91], v78 offset:4096
	ds_read_b128 v[92:95], v82
	ds_read_b128 v[96:99], v82 offset:4096
	s_waitcnt lgkmcnt(4)
	v_mfma_f32_32x32x16_bf16 v[48:63], v[100:103], v[108:111], v[48:63]
	s_add_u32 m0, s31, 0x20000
	v_lshl_add_u64 v[124:125], v[72:73], 0, s[24:25]
	global_load_lds_dwordx4 v[124:125], off
	v_mfma_f32_32x32x16_bf16 v[32:47], v[100:103], v[112:115], v[32:47]
	v_mfma_f32_32x32x16_bf16 v[16:31], v[104:107], v[108:111], v[16:31]
	s_add_u32 m0, s31, 0x22000
	v_lshl_add_u64 v[126:127], v[74:75], 0, s[24:25]
	global_load_lds_dwordx4 v[126:127], off
	v_mfma_f32_32x32x16_bf16 v[0:15], v[104:107], v[112:115], v[0:15]
	ds_read_b128 v[100:103], v79
	ds_read_b128 v[104:107], v79 offset:4096
	ds_read_b128 v[108:111], v83
	ds_read_b128 v[112:115], v83 offset:4096
	s_waitcnt lgkmcnt(4)
	v_mfma_f32_32x32x16_bf16 v[48:63], v[84:87], v[92:95], v[48:63]
	v_mfma_f32_32x32x16_bf16 v[32:47], v[84:87], v[96:99], v[32:47]
	v_mfma_f32_32x32x16_bf16 v[16:31], v[88:91], v[92:95], v[16:31]
	v_mfma_f32_32x32x16_bf16 v[0:15], v[88:91], v[96:99], v[0:15]
	s_waitcnt vmcnt(6) lgkmcnt(0)
	s_barrier
;     ...
;   for (int kt = 0; kt < nk; ++kt) {
;     if (kt + 1 < nk) asm volatile("s_waitcnt vmcnt(6)" ::: "memory");
;     else asm volatile("s_waitcnt vmcnt(0)" ::: "memory");
;     __builtin_amdgcn_s_barrier();
;     asm volatile("" ::: "memory");
;     if (kt + 2 < nk) { const int st2 = (st >= 1) ? st - 1 : 2; GEMM_ISSUE(kt + 2, st2); }
;     const char* la = lds + st * STAGE_B;
;     const char* lb = la + 32768;
;     const unsigned sa_u = (unsigned)(size_t)la + arow_u, sb_u = (unsigned)(size_t)lb + brow_u;
;     const unsigned a0 = sa_u + co0, a1 = sa_u + co1, a2 = sa_u + co2, a3 = sa_u + co3;
;     const unsigned b0 = sb_u + co0, b1 = sb_u + co1, b2 = sb_u + co2, b3 = sb_u + co3;
;     {
;       bf16x8 p0, p1, q0, q1, u0, u1, w0, w1;
;       asm volatile(
;         "ds_read_b128 %4, %12\n\tds_read_b128 %5, %12 offset:4096\n\tds_read_b128 %6, %16\n\tds_read_b128 %7, %16 offset:4096\n\t"
;         "ds_read_b128 %8, %13\n\tds_read_b128 %9, %13 offset:4096\n\tds_read_b128 %10, %17\n\tds_read_b128 %11, %17 offset:4096\n\t"
;         "s_waitcnt lgkmcnt(4)\n\t"
;         "v_mfma_f32_32x32x16_bf16 %0, %4, %6, %0\n\tv_mfma_f32_32x32x16_bf16 %1, %4, %7, %1\n\tv_mfma_f32_32x32x16_bf16 %2, %5, %6, %2\n\tv_mfma_f32_32x32x16_bf16 %3, %5, %7, %3\n\t"
;         "ds_read_b128 %4, %14\n\tds_read_b128 %5, %14 offset:4096\n\tds_read_b128 %6, %18\n\tds_read_b128 %7, %18 offset:4096\n\t"
;         "s_waitcnt lgkmcnt(4)\n\t"
;         "v_mfma_f32_32x32x16_bf16 %0, %8, %10, %0\n\tv_mfma_f32_32x32x16_bf16 %1, %8, %11, %1\n\tv_mfma_f32_32x32x16_bf16 %2, %9, %10, %2\n\tv_mfma_f32_32x32x16_bf16 %3, %9, %11, %3\n\t"
;         "ds_read_b128 %8, %15\n\tds_read_b128 %9, %15 offset:4096\n\tds_read_b128 %10, %19\n\tds_read_b128 %11, %19 offset:4096\n\t"
;         "s_waitcnt lgkmcnt(4)\n\t"
;         "v_mfma_f32_32x32x16_bf16 %0, %4, %6, %0\n\tv_mfma_f32_32x32x16_bf16 %1, %4, %7, %1\n\tv_mfma_f32_32x32x16_bf16 %2, %5, %6, %2\n\tv_mfma_f32_32x32x16_bf16 %3, %5, %7, %3\n\t"
;         "s_waitcnt lgkmcnt(0)\n\t"
;         "v_mfma_f32_32x32x16_bf16 %0, %8, %10, %0\n\tv_mfma_f32_32x32x16_bf16 %1, %8, %11, %1\n\tv_mfma_f32_32x32x16_bf16 %2, %9, %10, %2\n\tv_mfma_f32_32x32x16_bf16 %3, %9, %11, %3"
;         : "+v"(acc[0][0]), "+v"(acc[0][1]), "+v"(acc[1][0]), "+v"(acc[1][1]),
;           "=&v"(p0), "=&v"(p1), "=&v"(q0), "=&v"(q1), "=&v"(u0), "=&v"(u1), "=&v"(w0), "=&v"(w1)
	ds_read_b128 v[84:87], v76 offset:49152
	ds_read_b128 v[88:91], v76 offset:53248
	ds_read_b128 v[92:95], v80 offset:49152
	ds_read_b128 v[96:99], v80 offset:53248
	v_mfma_f32_32x32x16_bf16 v[48:63], v[100:103], v[108:111], v[48:63]
	s_add_u32 s24, s58, 0x0
	s_addc_u32 s25, s59, 0
	s_mov_b32 m0, s31
	v_lshl_add_u64 v[124:125], v[64:65], 0, s[24:25]
	global_load_lds_dwordx4 v[124:125], off
	v_mfma_f32_32x32x16_bf16 v[32:47], v[100:103], v[112:115], v[32:47]
	v_mfma_f32_32x32x16_bf16 v[16:31], v[104:107], v[108:111], v[16:31]
	s_add_u32 m0, s31, 0x2000
	v_lshl_add_u64 v[126:127], v[66:67], 0, s[24:25]
	global_load_lds_dwordx4 v[126:127], off
	v_mfma_f32_32x32x16_bf16 v[0:15], v[104:107], v[112:115], v[0:15]
	ds_read_b128 v[100:103], v77 offset:49152
	ds_read_b128 v[104:107], v77 offset:53248
	ds_read_b128 v[108:111], v81 offset:49152
	ds_read_b128 v[112:115], v81 offset:53248
	s_waitcnt lgkmcnt(4)
	v_mfma_f32_32x32x16_bf16 v[48:63], v[84:87], v[92:95], v[48:63]
	s_add_u32 m0, s31, 0x4000
	v_lshl_add_u64 v[124:125], v[68:69], 0, s[24:25]
	global_load_lds_dwordx4 v[124:125], off
	v_mfma_f32_32x32x16_bf16 v[32:47], v[84:87], v[96:99], v[32:47]
	v_mfma_f32_32x32x16_bf16 v[16:31], v[88:91], v[92:95], v[16:31]
	s_add_u32 m0, s31, 0x6000
	v_lshl_add_u64 v[126:127], v[70:71], 0, s[24:25]
	global_load_lds_dwordx4 v[126:127], off
	v_mfma_f32_32x32x16_bf16 v[0:15], v[88:91], v[96:99], v[0:15]
	ds_read_b128 v[84:87], v78 offset:49152
	ds_read_b128 v[88:91], v78 offset:53248
	ds_read_b128 v[92:95], v82 offset:49152
	ds_read_b128 v[96:99], v82 offset:53248
	s_waitcnt lgkmcnt(4)
	v_mfma_f32_32x32x16_bf16 v[48:63], v[100:103], v[108:111], v[48:63]
	s_add_u32 s24, s60, 0x0
	s_addc_u32 s25, s61, 0
	s_add_u32 m0, s31, 0x8000
	v_lshl_add_u64 v[124:125], v[72:73], 0, s[24:25]
	global_load_lds_dwordx4 v[124:125], off
	v_mfma_f32_32x32x16_bf16 v[32:47], v[100:103], v[112:115], v[32:47]
	v_mfma_f32_32x32x16_bf16 v[16:31], v[104:107], v[108:111], v[16:31]
	s_add_u32 m0, s31, 0xa000
	v_lshl_add_u64 v[126:127], v[74:75], 0, s[24:25]
	global_load_lds_dwordx4 v[126:127], off
	v_mfma_f32_32x32x16_bf16 v[0:15], v[104:107], v[112:115], v[0:15]
	ds_read_b128 v[100:103], v79 offset:49152
	ds_read_b128 v[104:107], v79 offset:53248
	ds_read_b128 v[108:111], v83 offset:49152
	ds_read_b128 v[112:115], v83 offset:53248
	s_waitcnt lgkmcnt(4)
	v_mfma_f32_32x32x16_bf16 v[48:63], v[84:87], v[92:95], v[48:63]
	v_mfma_f32_32x32x16_bf16 v[32:47], v[84:87], v[96:99], v[32:47]
	v_mfma_f32_32x32x16_bf16 v[16:31], v[88:91], v[92:95], v[16:31]
	v_mfma_f32_32x32x16_bf16 v[0:15], v[88:91], v[96:99], v[0:15]
	s_waitcnt vmcnt(6) lgkmcnt(0)
	s_barrier
	ds_read_b128 v[84:87], v116
	ds_read_b128 v[88:91], v116 offset:4096
	ds_read_b128 v[92:95], v120
	ds_read_b128 v[96:99], v120 offset:4096
	v_mfma_f32_32x32x16_bf16 v[48:63], v[100:103], v[108:111], v[48:63]
	s_add_u32 s24, s58, 0x80
	s_addc_u32 s25, s59, 0
	s_add_u32 m0, s31, 0xc000
	v_lshl_add_u64 v[124:125], v[64:65], 0, s[24:25]
	global_load_lds_dwordx4 v[124:125], off
	v_mfma_f32_32x32x16_bf16 v[32:47], v[100:103], v[112:115], v[32:47]
	v_mfma_f32_32x32x16_bf16 v[16:31], v[104:107], v[108:111], v[16:31]
	s_add_u32 m0, s31, 0xe000
	v_lshl_add_u64 v[126:127], v[66:67], 0, s[24:25]
	global_load_lds_dwordx4 v[126:127], off
	v_mfma_f32_32x32x16_bf16 v[0:15], v[104:107], v[112:115], v[0:15]
	ds_read_b128 v[100:103], v117
	ds_read_b128 v[104:107], v117 offset:4096
	ds_read_b128 v[108:111], v121
	ds_read_b128 v[112:115], v121 offset:4096
	s_waitcnt lgkmcnt(4)
	v_mfma_f32_32x32x16_bf16 v[48:63], v[84:87], v[92:95], v[48:63]
	s_add_u32 m0, s31, 0x10000
	v_lshl_add_u64 v[124:125], v[68:69], 0, s[24:25]
	global_load_lds_dwordx4 v[124:125], off
	v_mfma_f32_32x32x16_bf16 v[32:47], v[84:87], v[96:99], v[32:47]
	v_mfma_f32_32x32x16_bf16 v[16:31], v[88:91], v[92:95], v[16:31]
	s_add_u32 m0, s31, 0x12000
	v_lshl_add_u64 v[126:127], v[70:71], 0, s[24:25]
	global_load_lds_dwordx4 v[126:127], off
	v_mfma_f32_32x32x16_bf16 v[0:15], v[88:91], v[96:99], v[0:15]
	ds_read_b128 v[84:87], v118
	ds_read_b128 v[88:91], v118 offset:4096
	ds_read_b128 v[92:95], v122
	ds_read_b128 v[96:99], v122 offset:4096
	s_waitcnt lgkmcnt(4)
	v_mfma_f32_32x32x16_bf16 v[48:63], v[100:103], v[108:111], v[48:63]
	s_add_u32 s24, s60, 0x80
	s_addc_u32 s25, s61, 0
	s_add_u32 m0, s31, 0x14000
	v_lshl_add_u64 v[124:125], v[72:73], 0, s[24:25]
	global_load_lds_dwordx4 v[124:125], off
	v_mfma_f32_32x32x16_bf16 v[32:47], v[100:103], v[112:115], v[32:47]
	v_mfma_f32_32x32x16_bf16 v[16:31], v[104:107], v[108:111], v[16:31]
	s_add_u32 m0, s31, 0x16000
	v_lshl_add_u64 v[126:127], v[74:75], 0, s[24:25]
	global_load_lds_dwordx4 v[126:127], off
	v_mfma_f32_32x32x16_bf16 v[0:15], v[104:107], v[112:115], v[0:15]
	ds_read_b128 v[100:103], v119
	ds_read_b128 v[104:107], v119 offset:4096
	ds_read_b128 v[108:111], v123
	ds_read_b128 v[112:115], v123 offset:4096
	s_waitcnt lgkmcnt(4)
	v_mfma_f32_32x32x16_bf16 v[48:63], v[84:87], v[92:95], v[48:63]
	v_mfma_f32_32x32x16_bf16 v[32:47], v[84:87], v[96:99], v[32:47]
	v_mfma_f32_32x32x16_bf16 v[16:31], v[88:91], v[92:95], v[16:31]
	v_mfma_f32_32x32x16_bf16 v[0:15], v[88:91], v[96:99], v[0:15]
	s_waitcnt lgkmcnt(0)
	v_mfma_f32_32x32x16_bf16 v[48:63], v[100:103], v[108:111], v[48:63]
	v_mfma_f32_32x32x16_bf16 v[32:47], v[100:103], v[112:115], v[32:47]
	v_mfma_f32_32x32x16_bf16 v[16:31], v[104:107], v[108:111], v[16:31]
	v_mfma_f32_32x32x16_bf16 v[0:15], v[104:107], v[112:115], v[0:15]
.Lx3_done:
	s_add_u32 s100, s100, 1
	s_cmp_ge_u32 s100, 3
	s_cselect_b32 s101, 3, 0
	s_sub_u32 s100, s100, s101
	s_mov_b32 s101, 0
	s_waitcnt vmcnt(6)
	s_mov_b32 s53, 0x8000
	s_nop 15
	s_nop 15
	s_nop 7
	s_barrier
